# attention loops: next tile's first K fragment reads issued before the tile barrier (wrap-around LDS read pipeline), on top of v1 rescheduling
# speedup vs baseline: 1.0332x; 1.0056x over previous
; #define LAS __attribute__((address_space(3)))
; template <int DQK, bool DOUBLE> ...
;     constexpr int RB = DQK * 2, NCH = DQK / 8, NLD = NCH / 8;
;     const int wid = __builtin_amdgcn_readfirstlane(tid >> 6), lane = tid & 63, r32 = lane & 31, hi = lane >> 5;
;     LAS char* V_lds = lds; LAS char* K_lds = lds + K_OFF;
;     bf16x8 qr[DQK / 16];
;     { const bf16_t* Qw = Q + (size_t)(wid * 32 + r32) * ldq + hi * 8;
; #pragma unroll
;       for (int d0 = 0; d0 < DQK / 16; ++d0) qr[d0] = *(const bf16x8*)(Qw + d0 * 16); }
; #pragma unroll
;     for (int d = 0; d < 4; ++d) o[d] = f32x16{};
;     l_reg = 0.f;
;     int vrow[2], vcol[2], krow[NLD], kcol[NLD];
; #pragma unroll
;     for (int i = 0; i < 2; ++i) { const int q = tid + 512 * i, sub = q >> 5, within = q & 31, kk = (sub >> 2) * 8 + (within >> 2);
;         vrow[i] = kk; vcol[i] = (sub & 3) * 32 + (within & 3) * 8; }
; #pragma unroll
; __device__ __forceinline__ void attn_item(const AttnBufs& T, int type, int b, int h, int qrow0, int NT, LAS char* lds, int tid_) {
;     asm volatile("" : "+v"(tid_));
;     const int tid = tid_, wid = __builtin_amdgcn_readfirstlane(tid >> 6), lane = tid & 63, r32 = lane & 31, hi = lane >> 5;
;     const int rowc = MLAT + b * CTXL, rowl = b * SEQ;
;     LAS float* li = (LAS float*)(lds + att::LI_OFF) + wid * 64;
;     constexpr float LOG2E = 1.4426950408889634f;
;     const size_t orow0 = (size_t)qrow0 + wid * 32;
;     if (type == 0 && (MK_ATYPE & 1)) {
;         f32x16 o[4]; float l_reg; float rli[16];
;         att::attn_pass<128, ATT_DBL>(T.QA + (size_t)qrow0 * 1024 + h * 128, 1024, T.KA + (h >> 2) * 128, 256, T.VA + (h >> 2) * 128, 256, rowc, rowl, NT,
;                             T.lamv[1], o, l_reg, lds, tid);
;         att::row_recip(l_reg, rli, li, r32, hi);
; #pragma unroll
;         for (int d0 = 0; d0 < 4; ++d0)
; #pragma unroll
;             for (int r = 0; r < 16; ++r) o[d0][r] *= rli[r];
;         attn_out<false>(T, o, 0, h, orow0, lds, wid, lane, r32, hi);
;     } else if (type == 1 && (MK_ATYPE & 2)) {
;         f32x16 o[4]; float l_reg; float rli[16];
;         att::attn_pass<192, false>(T.QB + (size_t)qrow0 * 1536 + h * 192, 1536, T.KB + h * 192, 1536, T.VB + h * 128, 1024, rowc, rowl, NT,
;                             T.lamv[2], o, l_reg, lds, tid);
.LBB0_139:
	v_mov_b32_e32 v164, v186
	s_lshl_b32 s45, s70, 8
	v_readfirstlane_b32 s2, v164
	s_ashr_i32 s73, s2, 6
	s_and_b32 s2, s2, 0x3fffffc0
	s_lshl_b32 s2, s2, 2
	s_add_i32 s90, s2, 0
	s_lshl_b32 s2, s73, 5
	s_add_i32 s46, s45, 0x4000
	s_lshl_b32 s44, s70, 12
	s_add_i32 s90, s90, 0x1e000
	s_ashr_i32 s31, s30, 31
	s_ashr_i32 s3, s2, 31
	s_add_u32 s36, s2, s30
	s_addc_u32 s37, s3, s31
	v_and_b32_e32 v182, 63, v164
	v_and_b32_e32 v181, 31, v164
	v_bfe_u32 v176, v164, 5, 1
	s_mov_b64 s[56:57], -1
	s_mov_b64 s[48:49], 0
	s_cmp_lt_i32 s69, 1
	s_mulk_i32 s73, 0x4200
	s_mov_b64 s[50:51], 0
	s_cbranch_scc1 .LBB0_151
	s_cmp_eq_u32 s69, 1
	s_mov_b64 s[50:51], -1
	s_cbranch_scc0 .LBB0_150
	s_mul_i32 s3, s30, 0xc00
	v_readlane_b32 s4, v251, 32
	s_mul_hi_i32 s2, s30, 0xc00
	v_readlane_b32 s5, v251, 33
	s_add_u32 s4, s4, s3
	s_addc_u32 s5, s5, s2
	s_mul_i32 s2, s72, 0xc0
	s_ashr_i32 s3, s2, 31
	s_lshl_b64 s[2:3], s[2:3], 1
	s_add_u32 s4, s4, s2
	s_addc_u32 s5, s5, s3
	v_readlane_b32 s20, v251, 34
	v_readlane_b32 s21, v251, 35
	s_add_u32 s56, s20, s2
	s_addc_u32 s57, s21, s3
	s_lshl_b32 s50, s72, 7
	s_ashr_i32 s51, s50, 31
	s_lshl_b64 s[2:3], s[50:51], 1
	v_readlane_b32 s20, v251, 38
	v_readlane_b32 s21, v251, 39
	s_add_u32 s58, s20, s2
	v_readfirstlane_b32 s2, v164
	s_addc_u32 s59, s21, s3
	s_ashr_i32 s20, s2, 6
	v_lshl_or_b32 v1, s20, 5, v181
	v_mov_b64_e32 v[2:3], s[4:5]
	s_movk_i32 s41, 0xc00
	v_mad_i64_i32 v[2:3], s[2:3], v1, s41, v[2:3]
	v_lshlrev_b32_e32 v166, 4, v176
	v_mov_b32_e32 v167, v177
	v_lshl_add_u64 v[2:3], v[2:3], 0, v[166:167]
	global_load_dword v0, v177, s[14:15] offset:8
	global_load_dwordx4 v[112:115], v[2:3], off
	global_load_dwordx4 v[116:119], v[2:3], off offset:32
	global_load_dwordx4 v[120:123], v[2:3], off offset:64
	global_load_dwordx4 v[124:127], v[2:3], off offset:96
	s_waitcnt lgkmcnt(0)
	global_load_dwordx4 v[128:131], v[2:3], off offset:128
	global_load_dwordx4 v[132:135], v[2:3], off offset:160
	global_load_dwordx4 v[136:139], v[2:3], off offset:192
	global_load_dwordx4 v[140:143], v[2:3], off offset:224
	global_load_dwordx4 v[144:147], v[2:3], off offset:256
	global_load_dwordx4 v[148:151], v[2:3], off offset:288
	global_load_dwordx4 v[152:155], v[2:3], off offset:320
	global_load_dwordx4 v[156:159], v[2:3], off offset:352
	v_and_b32_e32 v2, 0x60, v164
	v_lshlrev_b32_e32 v3, 3, v164
	v_lshrrev_b32_e32 v1, 2, v164
	v_and_or_b32 v3, v3, 24, v2
	v_ashrrev_i32_e32 v2, 4, v164
	v_add_u32_e32 v4, 0x200, v164
	v_bfi_b32 v168, -8, v2, v1
	v_ashrrev_i32_e32 v2, 4, v4
	s_mov_b32 s2, 0x2aaaaaab
	v_bfi_b32 v170, -8, v2, v1
	v_mul_hi_i32 v1, v164, s2
	v_lshrrev_b32_e32 v2, 31, v1
	v_ashrrev_i32_e32 v1, 2, v1
	v_add_u32_e32 v172, v1, v2
	v_mul_lo_u32 v1, v172, 24
	v_sub_u32_e32 v1, v164, v1
	v_lshrrev_b32_e32 v2, 1, v172
	v_bitop3_b32 v1, v2, v1, 7 bitop3:0x6c
	v_lshlrev_b32_e32 v2, 3, v1
	v_mul_hi_i32 v1, v4, s2
	v_lshrrev_b32_e32 v5, 31, v1
	v_ashrrev_i32_e32 v1, 2, v1
	v_add_u32_e32 v174, v1, v5
	v_mul_lo_u32 v1, v174, 24
	v_sub_u32_e32 v1, v4, v1
	v_lshrrev_b32_e32 v4, 1, v174
	v_bitop3_b32 v1, v4, v1, 7 bitop3:0x6c
	s_ashr_i32 s47, s46, 31
	v_ashrrev_i32_e32 v169, 31, v168
	v_lshlrev_b32_e32 v4, 3, v1
	v_add_u32_e32 v1, 0x400, v164
	v_lshl_add_u64 v[8:9], v[168:169], 0, s[46:47]
	v_mul_hi_i32 v5, v1, s2
	s_lshl_b32 s2, s20, 10
	v_lshlrev_b64 v[8:9], 11, v[8:9]
	s_add_i32 s3, s2, 0
	v_lshl_add_u64 v[8:9], s[58:59], 0, v[8:9]
	v_lshlrev_b32_e32 v80, 1, v3
	v_mov_b32_e32 v81, v177
	v_lshl_add_u64 v[8:9], v[8:9], 0, v[80:81]
	s_mov_b32 m0, s3
	v_ashrrev_i32_e32 v171, 31, v170
	s_barrier
	global_load_lds_dwordx4 v[8:9], off
	v_lshl_add_u64 v[8:9], v[170:171], 0, s[46:47]
	v_lshlrev_b64 v[8:9], 11, v[8:9]
	v_lshl_add_u64 v[8:9], s[58:59], 0, v[8:9]
	s_add_i32 s21, s3, 0x2000
	v_lshl_add_u64 v[8:9], v[8:9], 0, v[80:81]
	s_mov_b32 m0, s21
	v_ashrrev_i32_e32 v173, 31, v172
	global_load_lds_dwordx4 v[8:9], off
	v_lshl_add_u64 v[8:9], v[172:173], 0, s[46:47]
	v_mov_b64_e32 v[84:85], s[56:57]
	v_lshrrev_b32_e32 v6, 31, v5
	v_ashrrev_i32_e32 v5, 2, v5
	v_mad_u64_u32 v[10:11], s[4:5], v8, s41, v[84:85]
	v_ashrrev_i32_e32 v3, 31, v2
	v_add_u32_e32 v192, v5, v6
	s_add_i32 s20, s3, 0xc000
	v_mad_i32_i24 v11, v9, s41, v11
	v_lshlrev_b64 v[82:83], 1, v[2:3]
	v_mul_lo_u32 v5, v192, 24
	v_lshl_add_u64 v[2:3], v[10:11], 0, v[82:83]
	s_mov_b32 m0, s20
	v_ashrrev_i32_e32 v175, 31, v174
	v_sub_u32_e32 v1, v1, v5
	v_lshrrev_b32_e32 v5, 1, v192
	global_load_lds_dwordx4 v[2:3], off
	v_lshl_add_u64 v[2:3], v[174:175], 0, s[46:47]
	v_bitop3_b32 v1, v5, v1, 7 bitop3:0x6c
	v_mad_u64_u32 v[8:9], s[4:5], v2, s41, v[84:85]
	v_ashrrev_i32_e32 v5, 31, v4
	v_mad_i32_i24 v9, v3, s41, v9
	v_lshlrev_b64 v[86:87], 1, v[4:5]
	s_add_i32 s33, s3, 0xe000
	v_lshl_add_u64 v[2:3], v[8:9], 0, v[86:87]
	s_mov_b32 m0, s33
	v_ashrrev_i32_e32 v193, 31, v192
	v_lshlrev_b32_e32 v6, 3, v1
	global_load_lds_dwordx4 v[2:3], off
	v_lshl_add_u64 v[2:3], v[192:193], 0, s[46:47]
	v_mad_u64_u32 v[4:5], s[4:5], v2, s41, v[84:85]
	v_ashrrev_i32_e32 v7, 31, v6
	v_mad_i32_i24 v5, v3, s41, v5
	v_lshlrev_b64 v[88:89], 1, v[6:7]
	s_add_i32 s35, s3, 0x10000
	s_add_i32 s4, s45, 0x4040
	v_lshl_add_u64 v[2:3], v[4:5], 0, v[88:89]
	s_mov_b32 m0, s35
	s_ashr_i32 s5, s4, 31
	global_load_lds_dwordx4 v[2:3], off
	v_lshl_add_u64 v[2:3], v[168:169], 0, s[4:5]
	v_lshlrev_b64 v[2:3], 11, v[2:3]
	v_lshl_add_u64 v[2:3], s[58:59], 0, v[2:3]
	s_add_i32 m0, s3, 0x4000
	v_lshl_add_u64 v[2:3], v[2:3], 0, v[80:81]
	global_load_lds_dwordx4 v[2:3], off
	v_lshl_add_u64 v[2:3], v[170:171], 0, s[4:5]
	v_lshlrev_b64 v[2:3], 11, v[2:3]
	v_lshl_add_u64 v[2:3], s[58:59], 0, v[2:3]
	v_lshl_add_u64 v[2:3], v[2:3], 0, v[80:81]
	s_add_i32 m0, s3, 0x6000
	v_mul_u32_u24_e32 v1, 0x180, v181
	global_load_lds_dwordx4 v[2:3], off
	v_lshl_add_u64 v[2:3], v[172:173], 0, s[4:5]
	v_mad_u64_u32 v[4:5], s[42:43], v2, s41, v[84:85]
	v_mad_i32_i24 v5, v3, s41, v5
	s_add_i32 m0, s3, 0x12000
	v_lshl_add_u64 v[2:3], v[4:5], 0, v[82:83]
	global_load_lds_dwordx4 v[2:3], off
	v_lshl_add_u64 v[2:3], v[174:175], 0, s[4:5]
	v_mad_u64_u32 v[4:5], s[42:43], v2, s41, v[84:85]
	v_mad_i32_i24 v5, v3, s41, v5
	v_lshl_add_u64 v[2:3], v[4:5], 0, v[86:87]
	s_add_i32 m0, s3, 0x14000
	s_waitcnt vmcnt(0)
	v_mov_b32_e32 v6, v0
	global_load_lds_dwordx4 v[2:3], off
	v_lshl_add_u64 v[2:3], v[192:193], 0, s[4:5]
	v_mad_u64_u32 v[4:5], s[4:5], v2, s41, v[84:85]
	v_mad_i32_i24 v5, v3, s41, v5
	s_add_i32 s4, s45, 0x4080
	v_lshl_add_u64 v[2:3], v[4:5], 0, v[88:89]
	s_add_i32 m0, s3, 0x16000
	s_ashr_i32 s5, s4, 31
	global_load_lds_dwordx4 v[2:3], off
	v_lshl_add_u64 v[2:3], v[168:169], 0, s[4:5]
	v_lshlrev_b64 v[2:3], 11, v[2:3]
	v_lshl_add_u64 v[2:3], s[58:59], 0, v[2:3]
	s_add_i32 m0, s3, 0x8000
	v_lshl_add_u64 v[2:3], v[2:3], 0, v[80:81]
	s_waitcnt vmcnt(0)
	s_waitcnt vmcnt(0) lgkmcnt(0)
	s_barrier
; #define LAS __attribute__((address_space(3)))
; #define VMW0() asm volatile("s_waitcnt vmcnt(0)" ::: "memory")
; template <int DQK>
; __device__ __forceinline__ void qkt(f32x16& p0, f32x16& p1, const LAS char* Ks, const bf16x8 (&qr)[DQK / 16], const int (&ka)[8], float nMB) {
;     constexpr int RB = DQK * 2, NA = (RB == 256) ? 8 : 4;
; #pragma unroll
;     for (int r = 0; r < 16; ++r) { p0[r] = nMB; p1[r] = nMB; }
; #pragma unroll
;     for (int d0 = 0; d0 < DQK / 16; ++d0) {
;         const LAS char* a = Ks + ka[d0 % NA] + (d0 / NA) * (NA * 32);
;         const bf16x8 b0 = *(const LAS bf16x8*)(a);
;         const bf16x8 b1 = *(const LAS bf16x8*)(a + 32 * RB);
;         p0 = __builtin_amdgcn_mfma_f32_32x32x16_bf16(b0, qr[d0], p0, 0, 0, 0);
;         p1 = __builtin_amdgcn_mfma_f32_32x32x16_bf16(b1, qr[d0], p1, 0, 0, 0); }
; }
; template <int DQK, bool DOUBLE> ...
;     ...
;     bf16x8 pa0, pa1, pa2, pa3;
;     __syncthreads();
;     DMA(0, 0); DMA(1, 1); VMW0(); __syncthreads();
	global_load_lds_dwordx4 v[2:3], off
	v_lshl_add_u64 v[2:3], v[170:171], 0, s[4:5]
	v_lshlrev_b64 v[2:3], 11, v[2:3]
	v_lshl_add_u64 v[2:3], s[58:59], 0, v[2:3]
	v_lshl_add_u64 v[2:3], v[2:3], 0, v[80:81]
	s_add_i32 m0, s3, 0xa000
	v_mov_b32_e32 v7, v0
	global_load_lds_dwordx4 v[2:3], off
	v_lshl_add_u64 v[2:3], v[172:173], 0, s[4:5]
	v_mad_u64_u32 v[4:5], s[42:43], v2, s41, v[84:85]
	v_mad_i32_i24 v5, v3, s41, v5
	s_add_i32 m0, s3, 0x18000
	v_lshl_add_u64 v[2:3], v[4:5], 0, v[82:83]
	global_load_lds_dwordx4 v[2:3], off
	v_lshl_add_u64 v[2:3], v[174:175], 0, s[4:5]
	v_mad_u64_u32 v[4:5], s[42:43], v2, s41, v[84:85]
	v_mad_i32_i24 v5, v3, s41, v5
	v_lshl_add_u64 v[2:3], v[4:5], 0, v[86:87]
	s_add_i32 m0, s3, 0x1a000
	s_movk_i32 s42, 0x118
	global_load_lds_dwordx4 v[2:3], off
	v_lshl_add_u64 v[2:3], v[192:193], 0, s[4:5]
	v_mad_u64_u32 v[4:5], s[4:5], v2, s41, v[84:85]
	v_mad_i32_i24 v5, v3, s41, v5
	v_lshl_add_u64 v[2:3], v[4:5], 0, v[88:89]
	s_add_i32 m0, s3, 0x1c000
	s_mov_b32 s5, 1
	global_load_lds_dwordx4 v[2:3], off
	v_lshlrev_b32_e32 v2, 3, v181
	v_and_b32_e32 v2, 0x70, v2
	v_or_b32_e32 v3, 32, v166
	v_bitop3_b32 v165, v3, v1, v2 bitop3:0xde
	v_or_b32_e32 v3, 64, v166
	v_bitop3_b32 v167, v3, v1, v2 bitop3:0xde
	v_or_b32_e32 v3, 0x60, v166
	v_bitop3_b32 v161, v166, v1, v2 bitop3:0xde
	v_bitop3_b32 v187, v3, v1, v2 bitop3:0xde
	v_lshlrev_b32_e32 v1, 1, v182
	v_and_b32_e32 v1, 32, v1
	v_lshlrev_b32_e32 v2, 3, v182
	v_lshlrev_b32_e32 v3, 4, v182
	v_and_b32_e32 v16, 0xc0, v3
	v_and_or_b32 v17, v2, s42, v1
	s_mov_b32 s4, 2
	v_mov_b32_e32 v1, v0
	v_mov_b32_e32 v2, v0
	v_mov_b32_e32 v3, v0
	v_mov_b32_e32 v4, v0
	v_mov_b32_e32 v5, v0
	v_mov_b32_e32 v8, v0
	v_mov_b32_e32 v9, v0
	v_mov_b32_e32 v10, v0
	v_mov_b32_e32 v11, v0
	v_mov_b32_e32 v12, v0
	v_mov_b32_e32 v13, v0
	v_mov_b32_e32 v14, v0
	v_mov_b32_e32 v15, v0
	v_add3_u32 v191, v16, 0, v17
	s_add_i32 s60, s45, 0x40c0
	v_add_u32_e32 v56, 0, v161
	ds_read_b128 v[16:19], v56 offset:49152
	ds_read_b128 v[48:51], v56 offset:61440
	v_add_u32_e32 v57, 0, v165
	v_add_u32_e32 v58, 0, v167
	v_add_u32_e32 v59, 0, v187
	s_waitcnt lgkmcnt(0)
	v_mfma_f32_32x32x16_bf16 v[32:47], v[16:19], v[112:115], v[0:15]
	v_mfma_f32_32x32x16_bf16 v[16:31], v[48:51], v[112:115], v[0:15]
	ds_read_b128 v[48:51], v57 offset:49152
	ds_read_b128 v[52:55], v57 offset:61440
	s_waitcnt lgkmcnt(0)
	v_mfma_f32_32x32x16_bf16 v[32:47], v[48:51], v[116:119], v[32:47]
	v_mfma_f32_32x32x16_bf16 v[16:31], v[52:55], v[116:119], v[16:31]
	ds_read_b128 v[48:51], v58 offset:49152
	ds_read_b128 v[52:55], v58 offset:61440
	s_waitcnt lgkmcnt(0)
	v_mfma_f32_32x32x16_bf16 v[32:47], v[48:51], v[120:123], v[32:47]
	v_mfma_f32_32x32x16_bf16 v[16:31], v[52:55], v[120:123], v[16:31]
	ds_read_b128 v[48:51], v59 offset:49152
	ds_read_b128 v[52:55], v59 offset:61440
	s_waitcnt lgkmcnt(0)
	v_mfma_f32_32x32x16_bf16 v[32:47], v[48:51], v[124:127], v[32:47]
	v_mfma_f32_32x32x16_bf16 v[16:31], v[52:55], v[124:127], v[16:31]
	ds_read_b128 v[48:51], v56 offset:49280
	ds_read_b128 v[52:55], v56 offset:61568
	s_waitcnt lgkmcnt(0)
	v_mfma_f32_32x32x16_bf16 v[32:47], v[48:51], v[128:131], v[32:47]
	v_mfma_f32_32x32x16_bf16 v[16:31], v[52:55], v[128:131], v[16:31]
	ds_read_b128 v[48:51], v57 offset:49280
	ds_read_b128 v[52:55], v57 offset:61568
	s_waitcnt lgkmcnt(0)
	v_mfma_f32_32x32x16_bf16 v[32:47], v[48:51], v[132:135], v[32:47]
	v_mfma_f32_32x32x16_bf16 v[16:31], v[52:55], v[132:135], v[16:31]
	ds_read_b128 v[48:51], v58 offset:49280
	ds_read_b128 v[52:55], v58 offset:61568
	s_waitcnt lgkmcnt(0)
	v_mfma_f32_32x32x16_bf16 v[32:47], v[48:51], v[136:139], v[32:47]
	v_mfma_f32_32x32x16_bf16 v[16:31], v[52:55], v[136:139], v[16:31]
	ds_read_b128 v[48:51], v59 offset:49280
	ds_read_b128 v[52:55], v59 offset:61568
	s_waitcnt lgkmcnt(0)
	v_mfma_f32_32x32x16_bf16 v[32:47], v[48:51], v[140:143], v[32:47]
	v_mfma_f32_32x32x16_bf16 v[16:31], v[52:55], v[140:143], v[16:31]
	ds_read_b128 v[48:51], v56 offset:49408
	ds_read_b128 v[52:55], v56 offset:61696
	s_waitcnt lgkmcnt(0)
	v_mfma_f32_32x32x16_bf16 v[32:47], v[48:51], v[144:147], v[32:47]
	v_mfma_f32_32x32x16_bf16 v[16:31], v[52:55], v[144:147], v[16:31]
	ds_read_b128 v[48:51], v57 offset:49408
	ds_read_b128 v[52:55], v57 offset:61696
	s_waitcnt lgkmcnt(0)
	v_mfma_f32_32x32x16_bf16 v[32:47], v[48:51], v[148:151], v[32:47]
	v_mfma_f32_32x32x16_bf16 v[16:31], v[52:55], v[148:151], v[16:31]
	ds_read_b128 v[48:51], v58 offset:49408
	ds_read_b128 v[52:55], v58 offset:61696
	s_waitcnt lgkmcnt(0)
	v_mfma_f32_32x32x16_bf16 v[32:47], v[48:51], v[152:155], v[32:47]
	v_mfma_f32_32x32x16_bf16 v[16:31], v[52:55], v[152:155], v[16:31]
	ds_read_b128 v[48:51], v59 offset:49408
	ds_read_b128 v[52:55], v59 offset:61696
	s_waitcnt lgkmcnt(0)
; #define SBAR() __builtin_amdgcn_sched_barrier(0)
; #define VMW0() asm volatile("s_waitcnt vmcnt(0)" ::: "memory")
; template <int D0> __device__ __forceinline__ void pv_one(f32x16& od, unsigned vb, bf16x8 pa0, bf16x8 pa1, bf16x8 pa2, bf16x8 pa3) {
;     const s16x4 l0 = tr_read<v_rd_off(D0, 0, 0)>(vb), h0 = tr_read<v_rd_off(D0, 0, 1)>(vb), l1 = tr_read<v_rd_off(D0, 1, 0)>(vb), h1 = tr_read<v_rd_off(D0, 1, 1)>(vb);
;     const s16x4 l2 = tr_read<v_rd_off(D0, 2, 0)>(vb), h2 = tr_read<v_rd_off(D0, 2, 1)>(vb), l3 = tr_read<v_rd_off(D0, 3, 0)>(vb), h3 = tr_read<v_rd_off(D0, 3, 1)>(vb);
;     asm volatile("s_waitcnt lgkmcnt(0)" ::: "memory"); SBAR();
;     ...
;     od = __builtin_amdgcn_mfma_f32_32x32x16_bf16(pa0, PK(l0, h0), od, 0, 0, 0);
;     od = __builtin_amdgcn_mfma_f32_32x32x16_bf16(pa1, PK(l1, h1), od, 0, 0, 0);
;     od = __builtin_amdgcn_mfma_f32_32x32x16_bf16(pa2, PK(l2, h2), od, 0, 0, 0);
;     od = __builtin_amdgcn_mfma_f32_32x32x16_bf16(pa3, PK(l3, h3), od, 0, 0, 0);
;     ...
; }
; __device__ __forceinline__ void pv_d0(f32x16 (&o)[4], unsigned vb, bf16x8 pa0, bf16x8 pa1, bf16x8 pa2, bf16x8 pa3) {
;     pv_one<0>(o[0], vb, pa0, pa1, pa2, pa3); pv_one<1>(o[1], vb, pa0, pa1, pa2, pa3); pv_one<2>(o[2], vb, pa0, pa1, pa2, pa3); pv_one<3>(o[3], vb, pa0, pa1, pa2, pa3);
; }
; __device__ __forceinline__ void partialSM(f32x16& p0, f32x16& p1) {
; #pragma unroll
;     for (int r = 0; r < 16; ++r) p0[r] = __builtin_amdgcn_exp2f(p0[r]);
; }
; __device__ __forceinline__ void finishSM(f32x16& p0, f32x16& p1, float& l_reg, bf16x8& pa0, bf16x8& pa1, bf16x8& pa2, bf16x8& pa3) {
; #pragma unroll
;     for (int r = 0; r < 16; ++r) p1[r] = __builtin_amdgcn_exp2f(p1[r]);
;     float ps = 0;
; #pragma unroll
;     for (int r = 0; r < 16; ++r) ps += p0[r];
; #pragma unroll
;     for (int r = 0; r < 16; ++r) ps += p1[r];
;     l_reg += ps;
;     ...
;     PK8(p0, 0, pa0); PK8(p0, 8, pa1); PK8(p1, 0, pa2); PK8(p1, 8, pa3);
;     ...
; }
; template <int DQK, bool DOUBLE> ...
;     ...
;         for (int j = 0; j < NT; ++j) {
;             SBAR(); qkt<DQK>(p0, p1, K_lds + bc * K_STRIDE, qr, ka, nMB);
;             partialSM(p0, p1); finishSM(p0, p1, l_reg, pa0, pa1, pa2, pa3); SBAR();
;             pv_d0(o, vb0 + bc * V_BYTES, pa0, pa1, pa2, pa3);
;             if (j + 1 < NT) { VMW0(); __syncthreads(); if (j + 3 < NT) DMA(j + 3, bc); }
;             { const int _t = bc; bc = bn; bn = bf; bf = _t; }
;         }
	v_mfma_f32_32x32x16_bf16 v[32:47], v[48:51], v[156:159], v[32:47]
	v_mfma_f32_32x32x16_bf16 v[16:31], v[52:55], v[156:159], v[16:31]
	s_nop 10
	v_exp_f32_e32 v32, v32
	v_exp_f32_e32 v33, v33
	v_exp_f32_e32 v34, v34
	v_exp_f32_e32 v35, v35
	v_exp_f32_e32 v36, v36
	v_add_f32_e32 v48, 0, v32
	v_exp_f32_e32 v37, v37
	v_add_f32_e32 v48, v33, v48
	v_exp_f32_e32 v38, v38
	v_add_f32_e32 v48, v34, v48
	v_exp_f32_e32 v39, v39
	v_add_f32_e32 v48, v35, v48
	v_exp_f32_e32 v40, v40
	v_add_f32_e32 v48, v36, v48
	v_exp_f32_e32 v41, v41
	v_add_f32_e32 v48, v37, v48
	v_exp_f32_e32 v42, v42
	v_add_f32_e32 v48, v38, v48
	v_exp_f32_e32 v43, v43
	v_add_f32_e32 v48, v39, v48
	v_exp_f32_e32 v44, v44
	v_add_f32_e32 v48, v40, v48
	v_exp_f32_e32 v45, v45
	v_add_f32_e32 v48, v41, v48
	v_exp_f32_e32 v46, v46
	v_add_f32_e32 v48, v42, v48
	v_exp_f32_e32 v47, v47
	v_add_f32_e32 v48, v43, v48
	v_exp_f32_e32 v16, v16
	v_add_f32_e32 v48, v44, v48
	v_exp_f32_e32 v17, v17
	v_add_f32_e32 v48, v45, v48
	v_exp_f32_e32 v18, v18
	v_add_f32_e32 v48, v46, v48
	v_exp_f32_e32 v19, v19
	v_add_f32_e32 v48, v47, v48
	v_exp_f32_e32 v20, v20
	v_add_f32_e32 v48, v16, v48
	v_exp_f32_e32 v21, v21
	v_add_f32_e32 v48, v17, v48
	v_exp_f32_e32 v22, v22
	v_add_f32_e32 v48, v18, v48
	v_exp_f32_e32 v23, v23
	v_add_f32_e32 v48, v19, v48
	v_exp_f32_e32 v24, v24
	v_add_f32_e32 v48, v20, v48
	v_exp_f32_e32 v25, v25
	v_add_f32_e32 v48, v21, v48
	v_exp_f32_e32 v26, v26
	v_add_f32_e32 v48, v22, v48
	v_exp_f32_e32 v27, v27
	v_add_f32_e32 v48, v23, v48
	v_exp_f32_e32 v28, v28
	v_add_f32_e32 v48, v24, v48
	v_exp_f32_e32 v29, v29
	v_add_f32_e32 v48, v25, v48
	v_exp_f32_e32 v30, v30
	v_add_f32_e32 v48, v26, v48
	v_exp_f32_e32 v31, v31
	v_add_f32_e32 v48, v27, v48
	v_add_f32_e32 v48, v28, v48
	v_add_f32_e32 v48, v29, v48
	v_add_f32_e32 v48, v30, v48
	v_add_f32_e32 v48, v31, v48
	v_add_f32_e32 v202, 0, v48
	v_cvt_pk_bf16_f32 v64, v32, v33
	v_cvt_pk_bf16_f32 v65, v34, v35
	v_cvt_pk_bf16_f32 v66, v36, v37
	v_cvt_pk_bf16_f32 v67, v38, v39
	v_cvt_pk_bf16_f32 v90, v40, v41
	v_cvt_pk_bf16_f32 v91, v42, v43
	v_cvt_pk_bf16_f32 v92, v44, v45
	v_cvt_pk_bf16_f32 v93, v46, v47
	v_cvt_pk_bf16_f32 v94, v16, v17
	v_cvt_pk_bf16_f32 v95, v18, v19
	v_cvt_pk_bf16_f32 v96, v20, v21
	v_cvt_pk_bf16_f32 v97, v22, v23
	v_cvt_pk_bf16_f32 v98, v24, v25
	v_cvt_pk_bf16_f32 v99, v26, v27
	v_cvt_pk_bf16_f32 v100, v28, v29
	v_cvt_pk_bf16_f32 v101, v30, v31
	ds_read_b64_tr_b16 v[16:17], v191 offset:0
	ds_read_b64_tr_b16 v[18:19], v191 offset:0x800
	ds_read_b64_tr_b16 v[32:33], v191 offset:0x1000
	ds_read_b64_tr_b16 v[34:35], v191 offset:0x1800
	ds_read_b64_tr_b16 v[36:37], v191 offset:0x2000
	ds_read_b64_tr_b16 v[38:39], v191 offset:0x2800
	ds_read_b64_tr_b16 v[40:41], v191 offset:0x3000
	ds_read_b64_tr_b16 v[42:43], v191 offset:0x3800
	s_waitcnt lgkmcnt(0)
	s_nop 0
	v_mfma_f32_32x32x16_bf16 v[16:31], v[64:67], v[16:19], 0
	v_mfma_f32_32x32x16_bf16 v[16:31], v[90:93], v[32:35], v[16:31]
	ds_read_b64_tr_b16 v[32:33], v191 offset:0x200
	ds_read_b64_tr_b16 v[34:35], v191 offset:0xa00
	ds_read_b64_tr_b16 v[48:49], v191 offset:0x1200
	ds_read_b64_tr_b16 v[50:51], v191 offset:0x1a00
	ds_read_b64_tr_b16 v[52:53], v191 offset:0x2200
	ds_read_b64_tr_b16 v[54:55], v191 offset:0x2a00
	ds_read_b64_tr_b16 v[56:57], v191 offset:0x3200
	v_mfma_f32_32x32x16_bf16 v[16:31], v[94:97], v[36:39], v[16:31]
	ds_read_b64_tr_b16 v[58:59], v191 offset:0x3a00
	s_waitcnt lgkmcnt(0)
	v_mfma_f32_32x32x16_bf16 v[16:31], v[98:101], v[40:43], v[16:31]
	v_mfma_f32_32x32x16_bf16 v[32:47], v[64:67], v[32:35], 0
	v_mfma_f32_32x32x16_bf16 v[32:47], v[90:93], v[48:51], v[32:47]
	ds_read_b64_tr_b16 v[48:49], v191 offset:0x400
	ds_read_b64_tr_b16 v[50:51], v191 offset:0xc00
	ds_read_b64_tr_b16 v[68:69], v191 offset:0x1400
	ds_read_b64_tr_b16 v[70:71], v191 offset:0x1c00
	ds_read_b64_tr_b16 v[72:73], v191 offset:0x2400
	ds_read_b64_tr_b16 v[74:75], v191 offset:0x2c00
	ds_read_b64_tr_b16 v[76:77], v191 offset:0x3400
	v_mfma_f32_32x32x16_bf16 v[32:47], v[94:97], v[52:55], v[32:47]
	ds_read_b64_tr_b16 v[78:79], v191 offset:0x3c00
	s_waitcnt lgkmcnt(0)
	v_mfma_f32_32x32x16_bf16 v[32:47], v[98:101], v[56:59], v[32:47]
	v_mfma_f32_32x32x16_bf16 v[48:63], v[64:67], v[48:51], 0
	v_mfma_f32_32x32x16_bf16 v[48:63], v[90:93], v[68:71], v[48:63]
	ds_read_b64_tr_b16 v[68:69], v191 offset:0x600
	ds_read_b64_tr_b16 v[70:71], v191 offset:0xe00
	ds_read_b64_tr_b16 v[102:103], v191 offset:0x1600
	ds_read_b64_tr_b16 v[104:105], v191 offset:0x1e00
	ds_read_b64_tr_b16 v[106:107], v191 offset:0x2600
	ds_read_b64_tr_b16 v[108:109], v191 offset:0x2e00
	ds_read_b64_tr_b16 v[194:195], v191 offset:0x3600
	v_mfma_f32_32x32x16_bf16 v[48:63], v[94:97], v[72:75], v[48:63]
	ds_read_b64_tr_b16 v[196:197], v191 offset:0x3e00
	s_waitcnt lgkmcnt(0)
	v_mfma_f32_32x32x16_bf16 v[48:63], v[98:101], v[76:79], v[48:63]
	v_mfma_f32_32x32x16_bf16 v[64:79], v[64:67], v[68:71], 0
	s_ashr_i32 s61, s60, 31
	v_lshl_add_u64 v[110:111], v[168:169], 0, s[60:61]
	v_lshlrev_b64 v[110:111], 11, v[110:111]
	v_lshl_add_u64 v[110:111], s[58:59], 0, v[110:111]
	s_mov_b32 m0, s3
	v_lshl_add_u64 v[110:111], v[110:111], 0, v[80:81]
	s_waitcnt vmcnt(0)
	s_waitcnt vmcnt(0)
	s_barrier
	global_load_lds_dwordx4 v[110:111], off
	v_lshl_add_u64 v[110:111], v[170:171], 0, s[60:61]
	v_mfma_f32_32x32x16_bf16 v[64:79], v[90:93], v[102:105], v[64:79]
	v_lshlrev_b64 v[90:91], 11, v[110:111]
	v_lshl_add_u64 v[90:91], s[58:59], 0, v[90:91]
	v_lshl_add_u64 v[90:91], v[90:91], 0, v[80:81]
	s_mov_b32 m0, s21
	v_lshl_add_u64 v[198:199], s[56:57], 0, v[86:87]
	global_load_lds_dwordx4 v[90:91], off
	v_lshl_add_u64 v[90:91], v[172:173], 0, s[60:61]
	v_mad_u64_u32 v[92:93], s[42:43], v90, s41, v[84:85]
	v_mad_i32_i24 v93, v91, s41, v93
	v_lshl_add_u64 v[90:91], v[92:93], 0, v[82:83]
	s_mov_b32 m0, s20
	v_mfma_f32_32x32x16_bf16 v[64:79], v[94:97], v[106:109], v[64:79]
	global_load_lds_dwordx4 v[90:91], off
	v_lshl_add_u64 v[90:91], v[174:175], 0, s[60:61]
	v_mad_u64_u32 v[92:93], s[20:21], v90, s41, v[84:85]
	v_mad_i32_i24 v93, v91, s41, v93
	v_lshl_add_u64 v[90:91], v[92:93], 0, v[86:87]
	s_mov_b32 m0, s33
	v_mfma_f32_32x32x16_bf16 v[64:79], v[98:101], v[194:197], v[64:79]
	global_load_lds_dwordx4 v[90:91], off
	v_lshl_add_u64 v[90:91], v[192:193], 0, s[60:61]
	v_mad_u64_u32 v[84:85], s[20:21], v90, s41, v[84:85]
	v_mad_i32_i24 v85, v91, s41, v85
	v_lshl_add_u64 v[84:85], v[84:85], 0, v[88:89]
	s_mov_b32 m0, s35
	v_lshl_add_u64 v[194:195], s[58:59], 0, v[80:81]
	global_load_lds_dwordx4 v[84:85], off
	v_lshl_add_u64 v[196:197], s[56:57], 0, v[82:83]
	v_lshl_add_u64 v[200:201], s[56:57], 0, v[88:89]
	s_add_i32 s20, s71, -1
	s_mov_b32 s21, 0
	s_mov_b32 s56, s44
	s_mov_b32 s35, 0
	s_waitcnt lgkmcnt(0)
	s_mul_i32 s42, s5, 0x6000
	v_add_u32_e32 v206, s42, v161
	v_add_u32_e32 v207, s42, v165
	v_add_u32_e32 v208, s42, v167
	v_add_u32_e32 v209, s42, v187
	ds_read_b128 v[220:223], v206 offset:49152
	ds_read_b128 v[238:241], v207 offset:49152
	ds_read_b128 v[242:245], v208 offset:49152
; #define LAS __attribute__((address_space(3)))
; #define SBAR() __builtin_amdgcn_sched_barrier(0)
; #define PK8(P, BASE, OUT) do { u32x4 w = {cvt_pk_bf16(P[BASE + 0], P[BASE + 1]), cvt_pk_bf16(P[BASE + 2], P[BASE + 3]), cvt_pk_bf16(P[BASE + 4], P[BASE + 5]), cvt_pk_bf16(P[BASE + 6], P[BASE + 7])}; \
;     OUT = *reinterpret_cast<bf16x8*>(&w); } while (0)
; #define VMW0() asm volatile("s_waitcnt vmcnt(0)" ::: "memory")
; __device__ __forceinline__ void partialSM(f32x16& p0, f32x16& p1) {
; #pragma unroll
;     for (int r = 0; r < 16; ++r) p0[r] = __builtin_amdgcn_exp2f(p0[r]);
; }
; __device__ __forceinline__ void finishSM(f32x16& p0, f32x16& p1, float& l_reg, bf16x8& pa0, bf16x8& pa1, bf16x8& pa2, bf16x8& pa3) {
; #pragma unroll
;     for (int r = 0; r < 16; ++r) p1[r] = __builtin_amdgcn_exp2f(p1[r]);
;     float ps = 0;
; #pragma unroll
;     for (int r = 0; r < 16; ++r) ps += p0[r];
; #pragma unroll
;     for (int r = 0; r < 16; ++r) ps += p1[r];
;     l_reg += ps;
;     ...
;     PK8(p0, 0, pa0); PK8(p0, 8, pa1); PK8(p1, 0, pa2); PK8(p1, 8, pa3);
;     ...
; }
; template <int DQK>
; __device__ __forceinline__ void qkt(f32x16& p0, f32x16& p1, const LAS char* Ks, const bf16x8 (&qr)[DQK / 16], const int (&ka)[8], float nMB) {
;     constexpr int RB = DQK * 2, NA = (RB == 256) ? 8 : 4;
; #pragma unroll
;     for (int r = 0; r < 16; ++r) { p0[r] = nMB; p1[r] = nMB; }
; #pragma unroll
;     for (int d0 = 0; d0 < DQK / 16; ++d0) {
;         const LAS char* a = Ks + ka[d0 % NA] + (d0 / NA) * (NA * 32);
;         const bf16x8 b0 = *(const LAS bf16x8*)(a);
;         const bf16x8 b1 = *(const LAS bf16x8*)(a + 32 * RB);
;         p0 = __builtin_amdgcn_mfma_f32_32x32x16_bf16(b0, qr[d0], p0, 0, 0, 0);
;         p1 = __builtin_amdgcn_mfma_f32_32x32x16_bf16(b1, qr[d0], p1, 0, 0, 0); }
; }
; template <int DQK, bool DOUBLE> ...
;     ...
;         for (int j = 0; j < NT; ++j) {
;             SBAR(); qkt<DQK>(p0, p1, K_lds + bc * K_STRIDE, qr, ka, nMB);
;             partialSM(p0, p1); finishSM(p0, p1, l_reg, pa0, pa1, pa2, pa3); SBAR();
;             pv_d0(o, vb0 + bc * V_BYTES, pa0, pa1, pa2, pa3);
;             if (j + 1 < NT) { VMW0(); __syncthreads(); if (j + 3 < NT) DMA(j + 3, bc); }
;             { const int _t = bc; bc = bn; bn = bf; bf = _t; }
;         }
.LBB0_142:
	s_mov_b32 s33, s4
	s_mov_b32 s4, s35
	s_mul_i32 s35, s5, 0x6000
	s_add_i32 s35, s35, 0
	s_lshl_b32 s41, s5, 14
	v_add_u32_e32 v184, s41, v191
	s_waitcnt lgkmcnt(2)
	v_mfma_f32_32x32x16_bf16 v[96:111], v[220:223], v[112:115], v[0:15]
	ds_read_b128 v[246:249], v209 offset:49152
	s_waitcnt lgkmcnt(2)
	v_mfma_f32_32x32x16_bf16 v[96:111], v[238:241], v[116:119], v[96:111]
	ds_read_b128 v[220:223], v206 offset:49280
	s_waitcnt lgkmcnt(2)
	v_mfma_f32_32x32x16_bf16 v[96:111], v[242:245], v[120:123], v[96:111]
	ds_read_b128 v[238:241], v207 offset:49280
	s_waitcnt lgkmcnt(2)
	v_mfma_f32_32x32x16_bf16 v[96:111], v[246:249], v[124:127], v[96:111]
	ds_read_b128 v[242:245], v208 offset:49280
	s_waitcnt lgkmcnt(2)
	v_mfma_f32_32x32x16_bf16 v[96:111], v[220:223], v[128:131], v[96:111]
	ds_read_b128 v[246:249], v209 offset:49280
	s_waitcnt lgkmcnt(2)
	v_mfma_f32_32x32x16_bf16 v[96:111], v[238:241], v[132:135], v[96:111]
	ds_read_b128 v[220:223], v206 offset:49408
	s_waitcnt lgkmcnt(2)
	v_mfma_f32_32x32x16_bf16 v[96:111], v[242:245], v[136:139], v[96:111]
	ds_read_b128 v[238:241], v207 offset:49408
	s_waitcnt lgkmcnt(2)
	v_mfma_f32_32x32x16_bf16 v[96:111], v[246:249], v[140:143], v[96:111]
	ds_read_b128 v[242:245], v208 offset:49408
	s_waitcnt lgkmcnt(2)
	v_mfma_f32_32x32x16_bf16 v[96:111], v[220:223], v[144:147], v[96:111]
	ds_read_b128 v[246:249], v209 offset:49408
	s_waitcnt lgkmcnt(2)
	v_mfma_f32_32x32x16_bf16 v[96:111], v[238:241], v[148:151], v[96:111]
	ds_read_b128 v[220:223], v206 offset:61440
	s_waitcnt lgkmcnt(2)
	v_mfma_f32_32x32x16_bf16 v[96:111], v[242:245], v[152:155], v[96:111]
	ds_read_b128 v[238:241], v207 offset:61440
	s_waitcnt lgkmcnt(2)
	v_mfma_f32_32x32x16_bf16 v[96:111], v[246:249], v[156:159], v[96:111]
	ds_read_b128 v[242:245], v208 offset:61440
	s_waitcnt lgkmcnt(2)
	v_mfma_f32_32x32x16_bf16 v[80:95], v[220:223], v[112:115], v[0:15]
	ds_read_b128 v[246:249], v209 offset:61440
	s_waitcnt lgkmcnt(2)
	v_mfma_f32_32x32x16_bf16 v[80:95], v[238:241], v[116:119], v[80:95]
	ds_read_b128 v[220:223], v206 offset:61568
	s_nop 4
	v_exp_f32_e32 v96, v96
	v_exp_f32_e32 v97, v97
	v_exp_f32_e32 v104, v104
	s_waitcnt lgkmcnt(2)
	v_mfma_f32_32x32x16_bf16 v[80:95], v[242:245], v[120:123], v[80:95]
	ds_read_b128 v[238:241], v207 offset:61568
	v_exp_f32_e32 v98, v98
	v_exp_f32_e32 v105, v105
	s_waitcnt lgkmcnt(2)
	v_mfma_f32_32x32x16_bf16 v[80:95], v[246:249], v[124:127], v[80:95]
	ds_read_b128 v[242:245], v208 offset:61568
	v_exp_f32_e32 v99, v99
	v_exp_f32_e32 v106, v106
	s_waitcnt lgkmcnt(2)
	v_mfma_f32_32x32x16_bf16 v[80:95], v[220:223], v[128:131], v[80:95]
	ds_read_b128 v[246:249], v209 offset:61568
	v_exp_f32_e32 v100, v100
	v_exp_f32_e32 v107, v107
	s_waitcnt lgkmcnt(2)
	v_mfma_f32_32x32x16_bf16 v[80:95], v[238:241], v[132:135], v[80:95]
	ds_read_b128 v[220:223], v206 offset:61696
	v_exp_f32_e32 v101, v101
	v_exp_f32_e32 v108, v108
	s_waitcnt lgkmcnt(2)
	v_mfma_f32_32x32x16_bf16 v[80:95], v[242:245], v[136:139], v[80:95]
	ds_read_b128 v[238:241], v207 offset:61696
	v_exp_f32_e32 v102, v102
	v_exp_f32_e32 v109, v109
	s_waitcnt lgkmcnt(2)
	v_mfma_f32_32x32x16_bf16 v[80:95], v[246:249], v[140:143], v[80:95]
	ds_read_b128 v[242:245], v208 offset:61696
	v_exp_f32_e32 v103, v103
	v_exp_f32_e32 v110, v110
	s_waitcnt lgkmcnt(2)
	v_mfma_f32_32x32x16_bf16 v[80:95], v[220:223], v[144:147], v[80:95]
	ds_read_b128 v[246:249], v209 offset:61696
	v_exp_f32_e32 v111, v111
	s_waitcnt lgkmcnt(2)
	v_mfma_f32_32x32x16_bf16 v[80:95], v[238:241], v[148:151], v[80:95]
	ds_read_b64_tr_b16 v[220:221], v184 offset:0
	ds_read_b64_tr_b16 v[222:223], v184 offset:2048
	v_cvt_pk_bf16_f32 v204, v96, v97
	v_cvt_pk_bf16_f32 v205, v98, v99
	v_cvt_pk_bf16_f32 v208, v104, v105
	s_waitcnt lgkmcnt(3)
	v_mfma_f32_32x32x16_bf16 v[80:95], v[242:245], v[152:155], v[80:95]
	ds_read_b64_tr_b16 v[238:239], v184 offset:512
	ds_read_b64_tr_b16 v[240:241], v184 offset:2560
	v_cvt_pk_bf16_f32 v206, v100, v101
	v_cvt_pk_bf16_f32 v209, v106, v107
	s_waitcnt lgkmcnt(4)
	v_mfma_f32_32x32x16_bf16 v[80:95], v[246:249], v[156:159], v[80:95]
	ds_read_b64_tr_b16 v[242:243], v184 offset:1024
	ds_read_b64_tr_b16 v[244:245], v184 offset:3072
	v_cvt_pk_bf16_f32 v207, v102, v103
	v_cvt_pk_bf16_f32 v210, v108, v109
	v_add_f32_e32 v96, 0, v96
	v_add_f32_e32 v96, v97, v96
	s_waitcnt lgkmcnt(4)
	v_mfma_f32_32x32x16_bf16 v[16:31], v[204:207], v[220:223], v[16:31]
	ds_read_b64_tr_b16 v[246:247], v184 offset:1536
	ds_read_b64_tr_b16 v[248:249], v184 offset:3584
	v_cvt_pk_bf16_f32 v211, v110, v111
	v_add_f32_e32 v96, v98, v96
	v_add_f32_e32 v96, v99, v96
	v_add_f32_e32 v96, v100, v96
	s_waitcnt lgkmcnt(4)
	v_mfma_f32_32x32x16_bf16 v[32:47], v[204:207], v[238:241], v[32:47]
	ds_read_b64_tr_b16 v[220:221], v184 offset:4096
	ds_read_b64_tr_b16 v[222:223], v184 offset:6144
	v_exp_f32_e32 v80, v80
	v_exp_f32_e32 v81, v81
	v_exp_f32_e32 v88, v88
	v_exp_f32_e32 v89, v89
	v_add_f32_e32 v96, v101, v96
	v_add_f32_e32 v96, v102, v96
	s_waitcnt lgkmcnt(4)
; #define SBAR() __builtin_amdgcn_sched_barrier(0)
; #define VMW0() asm volatile("s_waitcnt vmcnt(0)" ::: "memory")
; template <int D0> __device__ __forceinline__ void pv_one(f32x16& od, unsigned vb, bf16x8 pa0, bf16x8 pa1, bf16x8 pa2, bf16x8 pa3) {
;     const s16x4 l0 = tr_read<v_rd_off(D0, 0, 0)>(vb), h0 = tr_read<v_rd_off(D0, 0, 1)>(vb), l1 = tr_read<v_rd_off(D0, 1, 0)>(vb), h1 = tr_read<v_rd_off(D0, 1, 1)>(vb);
;     const s16x4 l2 = tr_read<v_rd_off(D0, 2, 0)>(vb), h2 = tr_read<v_rd_off(D0, 2, 1)>(vb), l3 = tr_read<v_rd_off(D0, 3, 0)>(vb), h3 = tr_read<v_rd_off(D0, 3, 1)>(vb);
;     asm volatile("s_waitcnt lgkmcnt(0)" ::: "memory"); SBAR();
;     ...
;     od = __builtin_amdgcn_mfma_f32_32x32x16_bf16(pa0, PK(l0, h0), od, 0, 0, 0);
;     od = __builtin_amdgcn_mfma_f32_32x32x16_bf16(pa1, PK(l1, h1), od, 0, 0, 0);
;     od = __builtin_amdgcn_mfma_f32_32x32x16_bf16(pa2, PK(l2, h2), od, 0, 0, 0);
;     od = __builtin_amdgcn_mfma_f32_32x32x16_bf16(pa3, PK(l3, h3), od, 0, 0, 0);
;     ...
; }
; __device__ __forceinline__ void pv_d0(f32x16 (&o)[4], unsigned vb, bf16x8 pa0, bf16x8 pa1, bf16x8 pa2, bf16x8 pa3) {
;     pv_one<0>(o[0], vb, pa0, pa1, pa2, pa3); pv_one<1>(o[1], vb, pa0, pa1, pa2, pa3); pv_one<2>(o[2], vb, pa0, pa1, pa2, pa3); pv_one<3>(o[3], vb, pa0, pa1, pa2, pa3);
; }
; template <int DQK, bool DOUBLE> ...
;     ...
;         for (int j = 0; j < NT; ++j) {
;             SBAR(); qkt<DQK>(p0, p1, K_lds + bc * K_STRIDE, qr, ka, nMB);
;             partialSM(p0, p1); finishSM(p0, p1, l_reg, pa0, pa1, pa2, pa3); SBAR();
;             pv_d0(o, vb0 + bc * V_BYTES, pa0, pa1, pa2, pa3);
;             if (j + 1 < NT) { VMW0(); __syncthreads(); if (j + 3 < NT) DMA(j + 3, bc); }
;             { const int _t = bc; bc = bn; bn = bf; bf = _t; }
;         }
	v_mfma_f32_32x32x16_bf16 v[48:63], v[204:207], v[242:245], v[48:63]
	ds_read_b64_tr_b16 v[238:239], v184 offset:4608
	ds_read_b64_tr_b16 v[240:241], v184 offset:6656
	v_exp_f32_e32 v82, v82
	v_exp_f32_e32 v83, v83
	v_exp_f32_e32 v90, v90
	v_add_f32_e32 v96, v103, v96
	v_add_f32_e32 v96, v104, v96
	s_waitcnt lgkmcnt(4)
	v_mfma_f32_32x32x16_bf16 v[64:79], v[204:207], v[246:249], v[64:79]
	ds_read_b64_tr_b16 v[242:243], v184 offset:5120
	ds_read_b64_tr_b16 v[244:245], v184 offset:7168
	v_exp_f32_e32 v84, v84
	v_exp_f32_e32 v85, v85
	v_exp_f32_e32 v91, v91
	v_add_f32_e32 v96, v105, v96
	v_add_f32_e32 v96, v106, v96
	s_waitcnt lgkmcnt(4)
	v_mfma_f32_32x32x16_bf16 v[16:31], v[208:211], v[220:223], v[16:31]
	ds_read_b64_tr_b16 v[246:247], v184 offset:5632
	ds_read_b64_tr_b16 v[248:249], v184 offset:7680
	v_exp_f32_e32 v86, v86
	v_exp_f32_e32 v87, v87
	v_exp_f32_e32 v92, v92
	v_add_f32_e32 v96, v107, v96
	v_add_f32_e32 v96, v108, v96
	s_waitcnt lgkmcnt(4)
	v_mfma_f32_32x32x16_bf16 v[32:47], v[208:211], v[238:241], v[32:47]
	ds_read_b64_tr_b16 v[220:221], v184 offset:8192
	ds_read_b64_tr_b16 v[222:223], v184 offset:10240
	v_cvt_pk_bf16_f32 v212, v80, v81
	v_cvt_pk_bf16_f32 v213, v82, v83
	v_exp_f32_e32 v93, v93
	v_add_f32_e32 v96, v109, v96
	v_add_f32_e32 v96, v110, v96
	s_waitcnt lgkmcnt(4)
	v_mfma_f32_32x32x16_bf16 v[48:63], v[208:211], v[242:245], v[48:63]
	ds_read_b64_tr_b16 v[238:239], v184 offset:8704
	ds_read_b64_tr_b16 v[240:241], v184 offset:10752
	v_cvt_pk_bf16_f32 v214, v84, v85
	v_exp_f32_e32 v94, v94
	v_add_f32_e32 v96, v111, v96
	s_waitcnt lgkmcnt(4)
	v_mfma_f32_32x32x16_bf16 v[64:79], v[208:211], v[246:249], v[64:79]
	ds_read_b64_tr_b16 v[242:243], v184 offset:9216
	ds_read_b64_tr_b16 v[244:245], v184 offset:11264
	v_cvt_pk_bf16_f32 v215, v86, v87
	v_exp_f32_e32 v95, v95
	v_add_f32_e32 v80, v80, v96
	v_add_f32_e32 v80, v81, v80
	s_waitcnt lgkmcnt(4)
	v_mfma_f32_32x32x16_bf16 v[16:31], v[212:215], v[220:223], v[16:31]
	ds_read_b64_tr_b16 v[246:247], v184 offset:9728
	ds_read_b64_tr_b16 v[248:249], v184 offset:11776
	v_cvt_pk_bf16_f32 v216, v88, v89
	v_add_f32_e32 v80, v82, v80
	v_add_f32_e32 v80, v83, v80
	v_add_f32_e32 v80, v84, v80
	s_waitcnt lgkmcnt(4)
	v_mfma_f32_32x32x16_bf16 v[32:47], v[212:215], v[238:241], v[32:47]
	ds_read_b64_tr_b16 v[220:221], v184 offset:12288
	ds_read_b64_tr_b16 v[222:223], v184 offset:14336
	v_cvt_pk_bf16_f32 v217, v90, v91
	v_add_f32_e32 v80, v85, v80
	v_add_f32_e32 v80, v86, v80
	v_add_f32_e32 v80, v87, v80
	s_waitcnt lgkmcnt(4)
	v_mfma_f32_32x32x16_bf16 v[48:63], v[212:215], v[242:245], v[48:63]
	ds_read_b64_tr_b16 v[238:239], v184 offset:12800
	ds_read_b64_tr_b16 v[240:241], v184 offset:14848
	v_cvt_pk_bf16_f32 v218, v92, v93
	s_waitcnt lgkmcnt(4)
	v_mfma_f32_32x32x16_bf16 v[64:79], v[212:215], v[246:249], v[64:79]
	ds_read_b64_tr_b16 v[242:243], v184 offset:13312
	ds_read_b64_tr_b16 v[244:245], v184 offset:15360
	v_cvt_pk_bf16_f32 v219, v94, v95
	v_add_f32_e32 v80, v88, v80
	v_add_f32_e32 v80, v89, v80
	v_add_f32_e32 v80, v90, v80
	s_waitcnt lgkmcnt(4)
	v_mfma_f32_32x32x16_bf16 v[16:31], v[216:219], v[220:223], v[16:31]
	ds_read_b64_tr_b16 v[246:247], v184 offset:13824
	ds_read_b64_tr_b16 v[248:249], v184 offset:15872
	s_mul_i32 s42, s33, 0x6000
	v_add_u32_e32 v206, s42, v161
	v_add_u32_e32 v207, s42, v165
	v_add_u32_e32 v208, s42, v167
	v_add_u32_e32 v209, s42, v187
	v_add_f32_e32 v80, v91, v80
	v_add_f32_e32 v80, v92, v80
	v_add_f32_e32 v80, v93, v80
	v_add_f32_e32 v80, v94, v80
	s_waitcnt lgkmcnt(4)
	v_mfma_f32_32x32x16_bf16 v[32:47], v[216:219], v[238:241], v[32:47]
	ds_read_b128 v[220:223], v206 offset:49152
	v_add_f32_e32 v80, v95, v80
	s_waitcnt lgkmcnt(3)
	v_mfma_f32_32x32x16_bf16 v[48:63], v[216:219], v[242:245], v[48:63]
	ds_read_b128 v[238:241], v207 offset:49152
	s_waitcnt lgkmcnt(2)
	v_mfma_f32_32x32x16_bf16 v[64:79], v[216:219], v[246:249], v[64:79]
	ds_read_b128 v[242:245], v208 offset:49152
	s_add_i32 s42, s21, 2
	s_cmp_ge_i32 s42, s71
	s_cbranch_scc1 .LBB0_145
	s_waitcnt vmcnt(0)
	s_add_i32 s42, s21, 4
	s_cmp_ge_i32 s42, s71
	s_waitcnt vmcnt(0)
	s_barrier
	s_cbranch_scc1 .LBB0_145
	s_ashr_i32 s57, s56, 31
	v_lshl_add_u64 v[184:185], s[56:57], 0, v[168:169]
	s_add_i32 s41, s3, s41
	v_lshlrev_b64 v[184:185], 11, v[184:185]
	v_lshl_add_u64 v[184:185], v[194:195], 0, v[184:185]
	s_mov_b32 m0, s41
	s_add_i32 s35, s35, s2
	global_load_lds_dwordx4 v[184:185], off
	v_lshl_add_u64 v[184:185], s[56:57], 0, v[170:171]
	v_lshlrev_b64 v[184:185], 11, v[184:185]
	v_lshl_add_u64 v[184:185], v[194:195], 0, v[184:185]
	s_add_i32 m0, s41, 0x2000
	s_movk_i32 s41, 0xc00
	global_load_lds_dwordx4 v[184:185], off
	v_lshl_add_u64 v[184:185], s[56:57], 0, v[172:173]
	v_mad_u64_u32 v[204:205], s[42:43], v184, s41, v[196:197]
	s_add_i32 m0, s35, 0xc000
	v_mad_i32_i24 v205, v185, s41, v205
	v_lshl_add_u64 v[184:185], s[56:57], 0, v[174:175]
	global_load_lds_dwordx4 v[204:205], off
	v_mad_u64_u32 v[204:205], s[42:43], v184, s41, v[198:199]
	v_mad_i32_i24 v205, v185, s41, v205
	s_add_i32 m0, s35, 0xe000
	v_lshl_add_u64 v[184:185], s[56:57], 0, v[192:193]
	global_load_lds_dwordx4 v[204:205], off
	v_mad_u64_u32 v[204:205], s[42:43], v184, s41, v[200:201]
	v_mad_i32_i24 v205, v185, s41, v205
	s_add_i32 m0, s35, 0x10000
	s_nop 0
	global_load_lds_dwordx4 v[204:205], off

; #define LAS __attribute__((address_space(3)))
; __device__ __forceinline__ int crow(int r, int hi) { return (r & 3) + 8 * (r >> 2) + 4 * hi; }
; __device__ __forceinline__ void row_recip(float l_reg, float (&rli)[16], LAS float* li, int r32, int hi) {
;     { auto rr = __builtin_amdgcn_permlane32_swap(__float_as_uint(l_reg), __float_as_uint(l_reg), false, false);
;       l_reg = __uint_as_float(rr[0]) + __uint_as_float(rr[1]); }
;     if (hi == 0) li[r32] = l_reg;
;     asm volatile("s_waitcnt lgkmcnt(0)" ::: "memory");
; #pragma unroll
;     for (int r = 0; r < 16; ++r) rli[r] = __builtin_amdgcn_rcpf(li[crow(r, hi)]);
;     asm volatile("s_waitcnt lgkmcnt(0)" ::: "memory");
; }
; template <bool SUBLN>
; __device__ __forceinline__ void attn_out(const AttnBufs& T, f32x16 (&o)[4], int type, int h, size_t orow0, LAS char* lds, int wid, int lane, int r32, int hi) {
;     const int rr = lane >> 5, c4 = (lane & 31) * 4;
;     const int col = type * 1024 + h * 128 + c4;
;     const bf16_t* gp = T.GATE + (orow0 + rr) * 3072 + col; bf16_t* op = T.BR + (orow0 + rr) * 3072 + col;
;     u32x2 gg[16];
; #pragma unroll
;     for (int i = 0; i < 16; ++i) gg[i] = *(const u32x2*)(gp + (size_t)i * 2 * 3072);
;     __syncthreads();
; __device__ __forceinline__ void attn_item(const AttnBufs& T, int type, int b, int h, int qrow0, int NT, LAS char* lds, int tid_) {
;     ...
;         att::row_recip(l_reg, rli, li, r32, hi);
; #pragma unroll
;         for (int d0 = 0; d0 < 4; ++d0)
; #pragma unroll
;             for (int r = 0; r < 16; ++r) o[d0][r] *= rli[r];
;         attn_out<false>(T, o, 1, h, orow0, lds, wid, lane, r32, hi);
.LBB0_147:
	s_waitcnt lgkmcnt(0)
	s_nop 11
	v_mov_b32_e32 v0, v202
	s_nop 1
	v_permlane32_swap_b32_e32 v202, v0
	v_cmp_gt_u32_e32 vcc, 32, v182
	s_and_saveexec_b64 s[56:57], vcc
	v_lshl_add_u32 v1, v181, 2, s90
	v_add_f32_e32 v0, v202, v0
	ds_write_b32 v1, v0
	s_or_b64 exec, exec, s[56:57]
	s_waitcnt lgkmcnt(0)
	v_add_u32_e32 v8, s90, v166
	ds_read_b128 v[0:3], v8
	ds_read_b128 v[4:7], v8 offset:32
	v_readlane_b32 s2, v251, 46
	v_readlane_b32 s3, v251, 47
	s_movk_i32 s4, 0x1800
	s_waitcnt lgkmcnt(0)
	v_rcp_f32_e32 v9, v0
	v_rcp_f32_e32 v10, v1
	v_rcp_f32_e32 v11, v2
	v_rcp_f32_e32 v12, v3
	ds_read_b128 v[0:3], v8 offset:64
	v_rcp_f32_e32 v4, v4
	v_rcp_f32_e32 v5, v5
	v_mul_f32_e32 v99, v34, v11
	v_mul_f32_e32 v100, v35, v12
	s_waitcnt lgkmcnt(0)
	v_rcp_f32_e32 v13, v0
	v_rcp_f32_e32 v14, v1
	v_rcp_f32_e32 v15, v2
	v_rcp_f32_e32 v80, v3
	ds_read_b128 v[0:3], v8 offset:96
	v_mov_b32_e32 v35, v177
	v_mul_f32_e32 v85, v20, v4
	v_mul_f32_e32 v86, v21, v5
	v_mul_f32_e32 v101, v36, v4
	s_waitcnt lgkmcnt(0)
	v_rcp_f32_e32 v0, v0
	v_rcp_f32_e32 v1, v1
	v_rcp_f32_e32 v2, v2
	v_rcp_f32_e32 v3, v3
	v_mul_f32_e32 v93, v28, v0
	v_mul_f32_e32 v44, v44, v0
	v_mul_f32_e32 v60, v60, v0
	v_mul_f32_e32 v76, v76, v0
	v_lshlrev_b32_e32 v0, 2, v182
	v_mul_f32_e32 v94, v29, v1
	v_mul_f32_e32 v95, v30, v2
	v_mul_f32_e32 v96, v31, v3
	v_mul_f32_e32 v45, v45, v1
	v_mul_f32_e32 v46, v46, v2
	v_mul_f32_e32 v47, v47, v3
	v_mul_f32_e32 v61, v61, v1
	v_mul_f32_e32 v62, v62, v2
	v_mul_f32_e32 v63, v63, v3
	v_mul_f32_e32 v77, v77, v1
	v_mul_f32_e32 v78, v78, v2
	v_mul_f32_e32 v79, v79, v3
	v_and_b32_e32 v34, 0x7c, v0
	v_lshl_add_u64 v[0:1], s[36:37], 0, v[176:177]
	v_mov_b64_e32 v[2:3], s[2:3]
	v_mul_f32_e32 v102, v37, v5
	v_mul_f32_e32 v52, v52, v4
	v_mul_f32_e32 v53, v53, v5
	v_mul_f32_e32 v68, v68, v4
	v_mul_f32_e32 v69, v69, v5
	v_mad_u64_u32 v[2:3], s[2:3], v0, s4, v[2:3]
	v_lshl_add_u64 v[4:5], v[34:35], 0, s[50:51]
	v_mul_f32_e32 v82, v17, v10
	v_mul_f32_e32 v83, v18, v11
	v_mul_f32_e32 v98, v33, v10
	v_mul_f32_e32 v49, v49, v10
	v_mul_f32_e32 v50, v50, v11
	v_mul_f32_e32 v65, v65, v10
	v_mul_f32_e32 v66, v66, v11
	v_mad_i32_i24 v3, v1, s4, v3
	v_lshlrev_b64 v[10:11], 1, v[4:5]
	s_waitcnt lgkmcnt(0)
	v_lshl_add_u64 v[2:3], v[2:3], 0, v[10:11]
	v_mul_f32_e32 v103, v40, v13
	v_mul_f32_e32 v104, v41, v14
	global_load_dwordx2 v[40:41], v[2:3], off offset:2048
	v_readlane_b32 s2, v251, 48
	v_readlane_b32 s3, v251, 49
	v_mul_f32_e32 v97, v32, v9
	v_mul_f32_e32 v91, v26, v15
	v_mov_b64_e32 v[4:5], s[2:3]
	v_mad_u64_u32 v[36:37], s[2:3], v0, s4, v[4:5]
	v_add_co_u32_e32 v0, vcc, s40, v2
	v_mad_i32_i24 v37, v1, s4, v37
	s_nop 0
	v_addc_co_u32_e32 v1, vcc, 0, v3, vcc
	global_load_dwordx2 v[32:33], v[0:1], off offset:2048
	v_add_co_u32_e32 v0, vcc, s82, v2
	s_mov_b32 s4, 0x9000
	s_nop 0
	v_addc_co_u32_e32 v1, vcc, 0, v3, vcc
	global_load_dwordx2 v[30:31], v[0:1], off offset:2048
	v_add_co_u32_e32 v0, vcc, s4, v2
	v_mul_f32_e32 v92, v27, v80
	s_nop 0
	v_addc_co_u32_e32 v1, vcc, 0, v3, vcc
	global_load_dwordx2 v[28:29], v[0:1], off offset:2048
	v_add_co_u32_e32 v0, vcc, s77, v2
	s_mov_b32 s5, 0xf000
	s_nop 0
	v_addc_co_u32_e32 v1, vcc, 0, v3, vcc
	global_load_dwordx2 v[26:27], v[0:1], off offset:2048
	v_rcp_f32_e32 v6, v6
	v_rcp_f32_e32 v7, v7
	v_add_co_u32_e32 v0, vcc, s5, v2
	v_mul_f32_e32 v89, v24, v13
	s_nop 0
	v_addc_co_u32_e32 v1, vcc, 0, v3, vcc
	v_mul_f32_e32 v90, v25, v14
	global_load_dwordx2 v[24:25], v[0:1], off offset:2048
	v_add_co_u32_e32 v0, vcc, s85, v2
	s_mov_b32 s20, 0x15000
	s_nop 0
	v_addc_co_u32_e32 v1, vcc, 0, v3, vcc
	v_mul_f32_e32 v87, v22, v6
	v_mul_f32_e32 v88, v23, v7
	global_load_dwordx2 v[22:23], v[0:1], off offset:2048
	v_add_co_u32_e32 v0, vcc, s20, v2
	s_mov_b32 s21, 0x1b000
	s_nop 0
	v_addc_co_u32_e32 v1, vcc, 0, v3, vcc
	global_load_dwordx2 v[20:21], v[0:1], off offset:2048
	v_add_co_u32_e32 v0, vcc, s76, v2
	v_mul_f32_e32 v84, v19, v12
	s_nop 0
	v_addc_co_u32_e32 v1, vcc, 0, v3, vcc
	global_load_dwordx2 v[18:19], v[0:1], off offset:2048
	v_add_co_u32_e32 v0, vcc, s21, v2
	v_mul_f32_e32 v81, v16, v9
	s_nop 0
	v_addc_co_u32_e32 v1, vcc, 0, v3, vcc
	global_load_dwordx2 v[16:17], v[0:1], off offset:2048
	v_add_co_u32_e32 v0, vcc, s92, v2
	s_mov_b32 s3, 0x21000
	s_nop 0
	v_addc_co_u32_e32 v1, vcc, 0, v3, vcc
	v_mul_f32_e32 v42, v42, v15
	v_mul_f32_e32 v57, v57, v14
	v_mul_f32_e32 v58, v58, v15
	v_mul_f32_e32 v73, v73, v14
	v_mul_f32_e32 v74, v74, v15
	global_load_dwordx2 v[14:15], v[0:1], off offset:2048
	v_add_co_u32_e32 v0, vcc, s3, v2
	v_mul_f32_e32 v51, v51, v12
	s_nop 0
	v_addc_co_u32_e32 v1, vcc, 0, v3, vcc
	v_mul_f32_e32 v56, v56, v13
	v_mul_f32_e32 v67, v67, v12
	v_mul_f32_e32 v72, v72, v13
	global_load_dwordx2 v[12:13], v[0:1], off offset:2048
	v_add_co_u32_e32 v0, vcc, s91, v2
	s_mov_b32 s33, 0x27000
	s_nop 0
	v_addc_co_u32_e32 v1, vcc, 0, v3, vcc
	v_mul_f32_e32 v48, v48, v9
	v_mul_f32_e32 v64, v64, v9
	global_load_dwordx2 v[8:9], v[0:1], off offset:2048
	v_add_co_u32_e32 v0, vcc, s33, v2
	v_mul_f32_e32 v38, v38, v6
	s_nop 0
	v_addc_co_u32_e32 v1, vcc, 0, v3, vcc
	v_mul_f32_e32 v39, v39, v7
	v_mul_f32_e32 v54, v54, v6
	v_mul_f32_e32 v55, v55, v7
	v_mul_f32_e32 v70, v70, v6
	v_mul_f32_e32 v71, v71, v7
	global_load_dwordx2 v[6:7], v[0:1], off offset:2048
	v_add_co_u32_e32 v0, vcc, s94, v2
	s_mov_b32 s2, 0x2d000
	s_nop 0
	v_addc_co_u32_e32 v1, vcc, 0, v3, vcc
	global_load_dwordx2 v[4:5], v[0:1], off offset:2048
	v_add_co_u32_e32 v0, vcc, s2, v2
	s_add_i32 s2, s73, 0
	s_nop 0
	v_addc_co_u32_e32 v1, vcc, 0, v3, vcc
	global_load_dwordx2 v[2:3], v[0:1], off offset:2048
	v_lshlrev_b32_e32 v0, 2, v181
	v_mul_u32_u24_e32 v1, 0x840, v176
	v_add3_u32 v0, s2, v0, v1
	v_mul_f32_e32 v43, v43, v80
	v_mul_f32_e32 v59, v59, v80
	v_mul_f32_e32 v75, v75, v80
	v_add_u32_e32 v1, 0x400, v0
	v_add_u32_e32 v35, 0x1000, v0
	v_add_u32_e32 v80, 0x1400, v0
	s_waitcnt vmcnt(0)
	s_barrier
; #define LAS __attribute__((address_space(3)))
; __device__ __forceinline__ float bf2f(unsigned h) { return __uint_as_float(h << 16); }
; __device__ __forceinline__ unsigned cvt_pk_bf16(float lo, float hi) { unsigned r; asm volatile("v_cvt_pk_bf16_f32 %0, %1, %2" : "=v"(r) : "v"(lo), "v"(hi)); return r; }
; __device__ __forceinline__ int crow(int r, int hi) { return (r & 3) + 8 * (r >> 2) + 4 * hi; }
; template <bool SUBLN>
; __device__ __forceinline__ void attn_out(const AttnBufs& T, f32x16 (&o)[4], int type, int h, size_t orow0, LAS char* lds, int wid, int lane, int r32, int hi) {
;     ...
; #pragma unroll
;     for (int d0 = 0; d0 < 4; ++d0)
; #pragma unroll
;         for (int r = 0; r < 16; ++r) stg[att::crow(r, hi) * 132 + d0 * 32 + r32] = o[d0][r];
;     asm volatile("s_waitcnt lgkmcnt(0)" ::: "memory");
;     f32x4 wsub = {1.f, 1.f, 1.f, 1.f};
;     if (SUBLN) { wsub = *(const f32x4*)(T.subln + c4) * (1.f - T.lam_init); }
; #pragma unroll
;     for (int i = 0; i < 16; ++i) {
;         f32x4 v = *(const LAS f32x4*)(stg + (2 * i + rr) * 132 + c4);
;         if (SUBLN) {
;             float s = (v[0] * v[0] + v[1] * v[1]) + (v[2] * v[2] + v[3] * v[3]);
;             s += __shfl_xor(s, 1); s += __shfl_xor(s, 2); s += __shfl_xor(s, 4); s += __shfl_xor(s, 8); s += __shfl_xor(s, 16);
;             v = v * (rsqrtf(s * (1.f / 128.f) + EPS)) * wsub;
;         }
;         u32x2 w; w.x = cvt_pk_bf16(v[0] * bf2f(gg[i].x & 0xffffu), v[1] * bf2f(gg[i].x >> 16)); w.y = cvt_pk_bf16(v[2] * bf2f(gg[i].y & 0xffffu), v[3] * bf2f(gg[i].y >> 16));
;         *(u32x2*)(op + (size_t)i * 2 * 3072) = w;
;     }
	ds_write2_b32 v0, v81, v97 offset1:32
	ds_write2_b32 v0, v82, v98 offset0:132 offset1:164
	ds_write2_b32 v1, v83, v99 offset0:8 offset1:40
	ds_write2_b32 v1, v84, v100 offset0:140 offset1:172
	ds_write2_b32 v35, v85, v101 offset0:32 offset1:64
	ds_write2_b32 v35, v86, v102 offset0:164 offset1:196
	ds_write2_b32 v80, v87, v38 offset0:40 offset1:72
	ds_write2_b32 v80, v88, v39 offset0:172 offset1:204
	v_add_u32_e32 v38, 0x2000, v0
	v_add_u32_e32 v39, 0x2400, v0
	ds_write2_b32 v38, v89, v103 offset0:64 offset1:96
	ds_write2_b32 v38, v90, v104 offset0:196 offset1:228
	ds_write2_b32 v39, v91, v42 offset0:72 offset1:104
	ds_write2_b32 v39, v92, v43 offset0:204 offset1:236
	v_add_u32_e32 v42, 0x3000, v0
	v_add_u32_e32 v43, 0x3200, v0
	ds_write2_b32 v42, v93, v44 offset0:96 offset1:128
	ds_write2_b32 v43, v94, v45 offset0:100 offset1:132
	v_add_u32_e32 v43, 0x3400, v0
	v_add_u32_e32 v44, 0x3600, v0
	ds_write2_b32 v43, v95, v46 offset0:104 offset1:136
	ds_write2_b32 v44, v96, v47 offset0:108 offset1:140
	ds_write2_b32 v0, v48, v64 offset0:64 offset1:96
	ds_write2_b32 v0, v49, v65 offset0:196 offset1:228
	ds_write2_b32 v1, v50, v66 offset0:72 offset1:104
	ds_write2_b32 v1, v51, v67 offset0:204 offset1:236
	ds_write2_b32 v35, v52, v68 offset0:96 offset1:128
	v_add_u32_e32 v1, 0x1200, v0
	ds_write2_b32 v1, v53, v69 offset0:100 offset1:132
	ds_write2_b32 v80, v54, v70 offset0:104 offset1:136
	v_add_u32_e32 v1, 0x1600, v0
	ds_write2_b32 v1, v55, v71 offset0:108 offset1:140
	ds_write2_b32 v38, v56, v72 offset0:128 offset1:160
	ds_write2_b32 v39, v57, v73 offset0:4 offset1:36
	ds_write2_b32 v39, v58, v74 offset0:136 offset1:168
	v_add_u32_e32 v1, 0x2800, v0
	v_add_u32_e32 v0, 0x3800, v0
	ds_write2_b32 v1, v59, v75 offset0:12 offset1:44
	ds_write2_b32 v42, v60, v76 offset0:160 offset1:192
	ds_write2_b32 v43, v61, v77 offset0:36 offset1:68
	ds_write2_b32 v43, v62, v78 offset0:168 offset1:200
	ds_write2_b32 v0, v63, v79 offset0:44 offset1:76
	v_lshlrev_b32_e32 v34, 2, v34
	v_mul_u32_u24_e32 v35, 0x210, v176
	s_waitcnt lgkmcnt(0)
	v_add3_u32 v34, s2, v34, v35
	v_lshl_add_u64 v[10:11], v[36:37], 0, v[10:11]
	ds_read_b128 v[36:39], v34
	v_lshlrev_b32_e32 v35, 16, v40
	v_lshl_add_u64 v[0:1], v[10:11], 0, s[28:29]
	s_mov_b64 s[50:51], 0
	s_waitcnt lgkmcnt(0)
	v_mul_f32_e32 v35, v36, v35
	v_and_b32_e32 v36, 0xffff0000, v40
	v_mul_f32_e32 v36, v37, v36
	v_and_b32_e32 v37, 0xffff0000, v41
	v_cvt_pk_bf16_f32 v36, v35, v36
	v_lshlrev_b32_e32 v35, 16, v41
	v_mul_f32_e32 v37, v39, v37
	v_mul_f32_e32 v35, v38, v35
	v_cvt_pk_bf16_f32 v37, v35, v37
	global_store_dwordx2 v[10:11], v[36:37], off offset:2048
	ds_read_b128 v[36:39], v34 offset:1056
	v_lshlrev_b32_e32 v35, 16, v32
	v_and_b32_e32 v32, 0xffff0000, v32
	s_waitcnt lgkmcnt(0)
	v_mul_f32_e32 v35, v36, v35
	v_mul_f32_e32 v32, v37, v32
	v_cvt_pk_bf16_f32 v32, v35, v32
	v_lshlrev_b32_e32 v35, 16, v33
	v_and_b32_e32 v33, 0xffff0000, v33
	v_add_co_u32_e32 v36, vcc, s40, v10
	v_mul_f32_e32 v33, v39, v33
	s_nop 0
	v_addc_co_u32_e32 v37, vcc, 0, v11, vcc
	v_mul_f32_e32 v35, v38, v35
	v_cvt_pk_bf16_f32 v33, v35, v33
	global_store_dwordx2 v[36:37], v[32:33], off offset:2048
	ds_read_b128 v[36:39], v34 offset:2112
	v_lshlrev_b32_e32 v32, 16, v30
	v_and_b32_e32 v30, 0xffff0000, v30
	v_lshlrev_b32_e32 v35, 16, v28
	v_and_b32_e32 v28, 0xffff0000, v28
	s_waitcnt lgkmcnt(0)
	v_mul_f32_e32 v32, v36, v32
	v_mul_f32_e32 v30, v37, v30
	v_cvt_pk_bf16_f32 v30, v32, v30
	v_lshlrev_b32_e32 v32, 16, v31
	v_and_b32_e32 v31, 0xffff0000, v31
	v_mul_f32_e32 v32, v38, v32
	v_mul_f32_e32 v31, v39, v31
	v_cvt_pk_bf16_f32 v31, v32, v31
	v_add_co_u32_e32 v32, vcc, s82, v10
	s_nop 1
	v_addc_co_u32_e32 v33, vcc, 0, v11, vcc
	global_store_dwordx2 v[32:33], v[30:31], off offset:2048
	ds_read_b128 v[30:33], v34 offset:3168
	s_waitcnt lgkmcnt(0)
	v_mul_f32_e32 v30, v30, v35
	v_mul_f32_e32 v28, v31, v28
	v_cvt_pk_bf16_f32 v28, v30, v28
	v_lshlrev_b32_e32 v30, 16, v29
	v_and_b32_e32 v29, 0xffff0000, v29
	v_mul_f32_e32 v30, v32, v30
	v_mul_f32_e32 v29, v33, v29
	v_cvt_pk_bf16_f32 v29, v30, v29
	v_add_co_u32_e32 v30, vcc, s4, v10
	v_lshlrev_b32_e32 v32, 16, v26
	s_nop 0
	v_addc_co_u32_e32 v31, vcc, 0, v11, vcc
	global_store_dwordx2 v[30:31], v[28:29], off offset:2048
	ds_read_b128 v[28:31], v34 offset:4224
	v_and_b32_e32 v26, 0xffff0000, v26
	s_waitcnt lgkmcnt(0)
	v_mul_f32_e32 v28, v28, v32
	v_mul_f32_e32 v26, v29, v26
	v_cvt_pk_bf16_f32 v26, v28, v26
	v_lshlrev_b32_e32 v28, 16, v27
	v_and_b32_e32 v27, 0xffff0000, v27
	v_mul_f32_e32 v28, v30, v28
	v_mul_f32_e32 v27, v31, v27
	v_cvt_pk_bf16_f32 v27, v28, v27
	v_add_co_u32_e32 v28, vcc, s77, v10
	v_lshlrev_b32_e32 v30, 16, v24
	s_nop 0
	v_addc_co_u32_e32 v29, vcc, 0, v11, vcc
	global_store_dwordx2 v[28:29], v[26:27], off offset:2048
	ds_read_b128 v[26:29], v34 offset:5280
	v_and_b32_e32 v24, 0xffff0000, v24
	s_waitcnt lgkmcnt(0)
	v_mul_f32_e32 v26, v26, v30
	v_mul_f32_e32 v24, v27, v24
	v_cvt_pk_bf16_f32 v24, v26, v24
	v_lshlrev_b32_e32 v26, 16, v25
	v_and_b32_e32 v25, 0xffff0000, v25
	v_mul_f32_e32 v26, v28, v26
	v_mul_f32_e32 v25, v29, v25
	v_cvt_pk_bf16_f32 v25, v26, v25
	v_add_co_u32_e32 v26, vcc, s5, v10
	v_lshlrev_b32_e32 v28, 16, v22
	s_nop 0
	v_addc_co_u32_e32 v27, vcc, 0, v11, vcc
	global_store_dwordx2 v[26:27], v[24:25], off offset:2048
	ds_read_b128 v[24:27], v34 offset:6336
	v_and_b32_e32 v22, 0xffff0000, v22
	s_waitcnt lgkmcnt(0)
; #define LAS __attribute__((address_space(3)))
; __device__ __forceinline__ float bf2f(unsigned h) { return __uint_as_float(h << 16); }
; __device__ __forceinline__ unsigned cvt_pk_bf16(float lo, float hi) { unsigned r; asm volatile("v_cvt_pk_bf16_f32 %0, %1, %2" : "=v"(r) : "v"(lo), "v"(hi)); return r; }
; template <bool SUBLN>
; __device__ __forceinline__ void attn_out(const AttnBufs& T, f32x16 (&o)[4], int type, int h, size_t orow0, LAS char* lds, int wid, int lane, int r32, int hi) {
;     ...
;     for (int i = 0; i < 16; ++i) {
;         f32x4 v = *(const LAS f32x4*)(stg + (2 * i + rr) * 132 + c4);
;         if (SUBLN) {
;             float s = (v[0] * v[0] + v[1] * v[1]) + (v[2] * v[2] + v[3] * v[3]);
;             s += __shfl_xor(s, 1); s += __shfl_xor(s, 2); s += __shfl_xor(s, 4); s += __shfl_xor(s, 8); s += __shfl_xor(s, 16);
;             v = v * (rsqrtf(s * (1.f / 128.f) + EPS)) * wsub;
;         }
;         u32x2 w; w.x = cvt_pk_bf16(v[0] * bf2f(gg[i].x & 0xffffu), v[1] * bf2f(gg[i].x >> 16)); w.y = cvt_pk_bf16(v[2] * bf2f(gg[i].y & 0xffffu), v[3] * bf2f(gg[i].y >> 16));
;         *(u32x2*)(op + (size_t)i * 2 * 3072) = w;
;     }
	v_mul_f32_e32 v24, v24, v28
	v_mul_f32_e32 v22, v25, v22
	v_cvt_pk_bf16_f32 v22, v24, v22
	v_lshlrev_b32_e32 v24, 16, v23
	v_and_b32_e32 v23, 0xffff0000, v23
	v_mul_f32_e32 v24, v26, v24
	v_mul_f32_e32 v23, v27, v23
	v_cvt_pk_bf16_f32 v23, v24, v23
	v_add_co_u32_e32 v24, vcc, s85, v10
	v_lshlrev_b32_e32 v26, 16, v20
	s_nop 0
	v_addc_co_u32_e32 v25, vcc, 0, v11, vcc
	global_store_dwordx2 v[24:25], v[22:23], off offset:2048
	ds_read_b128 v[22:25], v34 offset:7392
	v_and_b32_e32 v20, 0xffff0000, v20
	s_waitcnt lgkmcnt(0)
	v_mul_f32_e32 v22, v22, v26
	v_mul_f32_e32 v20, v23, v20
	v_cvt_pk_bf16_f32 v20, v22, v20
	v_lshlrev_b32_e32 v22, 16, v21
	v_and_b32_e32 v21, 0xffff0000, v21
	v_mul_f32_e32 v22, v24, v22
	v_mul_f32_e32 v21, v25, v21
	v_cvt_pk_bf16_f32 v21, v22, v21
	v_add_co_u32_e32 v22, vcc, s20, v10
	v_lshlrev_b32_e32 v24, 16, v18
	s_nop 0
	v_addc_co_u32_e32 v23, vcc, 0, v11, vcc
	global_store_dwordx2 v[22:23], v[20:21], off offset:2048
	ds_read_b128 v[20:23], v34 offset:8448
	v_and_b32_e32 v18, 0xffff0000, v18
	s_waitcnt lgkmcnt(0)
	v_mul_f32_e32 v20, v20, v24
	v_mul_f32_e32 v18, v21, v18
	v_cvt_pk_bf16_f32 v18, v20, v18
	v_lshlrev_b32_e32 v20, 16, v19
	v_and_b32_e32 v19, 0xffff0000, v19
	v_mul_f32_e32 v20, v22, v20
	v_mul_f32_e32 v19, v23, v19
	v_cvt_pk_bf16_f32 v19, v20, v19
	v_add_co_u32_e32 v20, vcc, s76, v10
	v_lshlrev_b32_e32 v22, 16, v16
	s_nop 0
	v_addc_co_u32_e32 v21, vcc, 0, v11, vcc
	global_store_dwordx2 v[20:21], v[18:19], off offset:2048
	ds_read_b128 v[18:21], v34 offset:9504
	v_and_b32_e32 v16, 0xffff0000, v16
	s_waitcnt lgkmcnt(0)
	v_mul_f32_e32 v18, v18, v22
	v_mul_f32_e32 v16, v19, v16
	v_cvt_pk_bf16_f32 v16, v18, v16
	v_lshlrev_b32_e32 v18, 16, v17
	v_and_b32_e32 v17, 0xffff0000, v17
	v_mul_f32_e32 v18, v20, v18
	v_mul_f32_e32 v17, v21, v17
	v_cvt_pk_bf16_f32 v17, v18, v17
	v_add_co_u32_e32 v18, vcc, s21, v10
	v_lshlrev_b32_e32 v20, 16, v14
	s_nop 0
	v_addc_co_u32_e32 v19, vcc, 0, v11, vcc
	global_store_dwordx2 v[18:19], v[16:17], off offset:2048
	ds_read_b128 v[16:19], v34 offset:10560
	v_and_b32_e32 v14, 0xffff0000, v14
	s_waitcnt lgkmcnt(0)
	v_mul_f32_e32 v16, v16, v20
	v_mul_f32_e32 v14, v17, v14
	v_cvt_pk_bf16_f32 v14, v16, v14
	v_lshlrev_b32_e32 v16, 16, v15
	v_and_b32_e32 v15, 0xffff0000, v15
	v_mul_f32_e32 v16, v18, v16
	v_mul_f32_e32 v15, v19, v15
	v_cvt_pk_bf16_f32 v15, v16, v15
	v_add_co_u32_e32 v16, vcc, s92, v10
	v_lshlrev_b32_e32 v18, 16, v12
	s_nop 0
	v_addc_co_u32_e32 v17, vcc, 0, v11, vcc
	global_store_dwordx2 v[16:17], v[14:15], off offset:2048
	ds_read_b128 v[14:17], v34 offset:11616
	v_and_b32_e32 v12, 0xffff0000, v12
	s_waitcnt lgkmcnt(0)
	v_mul_f32_e32 v14, v14, v18
	v_mul_f32_e32 v12, v15, v12
	v_cvt_pk_bf16_f32 v12, v14, v12
	v_lshlrev_b32_e32 v14, 16, v13
	v_and_b32_e32 v13, 0xffff0000, v13
	v_mul_f32_e32 v14, v16, v14
	v_mul_f32_e32 v13, v17, v13
	v_cvt_pk_bf16_f32 v13, v14, v13
	v_add_co_u32_e32 v14, vcc, s3, v10
	v_lshlrev_b32_e32 v16, 16, v8
	s_nop 0
	v_addc_co_u32_e32 v15, vcc, 0, v11, vcc
	global_store_dwordx2 v[14:15], v[12:13], off offset:2048
	ds_read_b128 v[12:15], v34 offset:12672
	v_and_b32_e32 v8, 0xffff0000, v8
	s_waitcnt lgkmcnt(0)
	v_mul_f32_e32 v12, v12, v16
	v_mul_f32_e32 v8, v13, v8
	v_cvt_pk_bf16_f32 v8, v12, v8
	v_lshlrev_b32_e32 v12, 16, v9
	v_and_b32_e32 v9, 0xffff0000, v9
	v_mul_f32_e32 v12, v14, v12
	v_mul_f32_e32 v9, v15, v9
	v_cvt_pk_bf16_f32 v9, v12, v9
	v_add_co_u32_e32 v12, vcc, s91, v10
	s_nop 1
	v_addc_co_u32_e32 v13, vcc, 0, v11, vcc
	global_store_dwordx2 v[12:13], v[8:9], off offset:2048
	ds_read_b128 v[12:15], v34 offset:13728
	v_lshlrev_b32_e32 v8, 16, v6
	v_and_b32_e32 v6, 0xffff0000, v6
	s_waitcnt lgkmcnt(0)
	v_mul_f32_e32 v8, v12, v8
	v_mul_f32_e32 v6, v13, v6
	v_cvt_pk_bf16_f32 v6, v8, v6
	v_lshlrev_b32_e32 v8, 16, v7
	v_and_b32_e32 v7, 0xffff0000, v7
	v_mul_f32_e32 v8, v14, v8
	v_mul_f32_e32 v7, v15, v7
	v_cvt_pk_bf16_f32 v7, v8, v7
	v_add_co_u32_e32 v8, vcc, s33, v10
	v_lshlrev_b32_e32 v12, 16, v4
	s_nop 0
	v_addc_co_u32_e32 v9, vcc, 0, v11, vcc
	global_store_dwordx2 v[8:9], v[6:7], off offset:2048
	ds_read_b128 v[6:9], v34 offset:14784
	v_and_b32_e32 v4, 0xffff0000, v4
	s_waitcnt lgkmcnt(0)
	v_mul_f32_e32 v6, v6, v12
	v_mul_f32_e32 v4, v7, v4
	v_cvt_pk_bf16_f32 v4, v6, v4
	v_lshlrev_b32_e32 v6, 16, v5
	v_and_b32_e32 v5, 0xffff0000, v5
	v_mul_f32_e32 v6, v8, v6
	v_mul_f32_e32 v5, v9, v5
	v_cvt_pk_bf16_f32 v5, v6, v5
	v_add_co_u32_e32 v6, vcc, s94, v10
	v_lshlrev_b32_e32 v8, 16, v2
	s_nop 0
	v_addc_co_u32_e32 v7, vcc, 0, v11, vcc
	global_store_dwordx2 v[6:7], v[4:5], off offset:2048
	ds_read_b128 v[4:7], v34 offset:15840
	v_and_b32_e32 v2, 0xffff0000, v2
	s_waitcnt lgkmcnt(0)
	v_mul_f32_e32 v4, v4, v8
	v_mul_f32_e32 v2, v5, v2
	v_cvt_pk_bf16_f32 v2, v4, v2
	v_lshlrev_b32_e32 v4, 16, v3
	v_and_b32_e32 v3, 0xffff0000, v3
	v_mul_f32_e32 v3, v7, v3
	v_mul_f32_e32 v4, v6, v4
	v_cvt_pk_bf16_f32 v3, v4, v3

; __device__ __forceinline__ int v_rd_base(int lane) { return ((lane & 3) << 3) | (((lane >> 2) & 3) << 6) | (((lane >> 4) & 1) << 5) | (((lane >> 5) & 1) << 8); }
; #define VMW0() asm volatile("s_waitcnt vmcnt(0)" ::: "memory")
; template <int DQK, bool DOUBLE> ...
;     ...
;     { const bf16_t* Qw = Q + (size_t)(wid * 32 + r32) * ldq + hi * 8;
; #pragma unroll
;       for (int d0 = 0; d0 < DQK / 16; ++d0) qr[d0] = *(const bf16x8*)(Qw + d0 * 16); }
; #pragma unroll
;     for (int d = 0; d < 4; ++d) o[d] = f32x16{};
;     l_reg = 0.f;
;     int vrow[2], vcol[2], krow[NLD], kcol[NLD];
; #pragma unroll
;     for (int i = 0; i < 2; ++i) { const int q = tid + 512 * i, sub = q >> 5, within = q & 31, kk = (sub >> 2) * 8 + (within >> 2);
;         vrow[i] = kk; vcol[i] = (sub & 3) * 32 + (within & 3) * 8; }
; #pragma unroll
;     for (int i = 0; i < NLD; ++i) { const int q = tid + 512 * i, row = q / NCH, chp = q % NCH; const int x = (RB == 256) ? (row & 15) : ((row >> 1) & 7);
;         krow[i] = row; kcol[i] = (chp ^ x) * 8; }
;     const unsigned vb0 = (unsigned)(uintptr_t)V_lds + v_rd_base(lane);
;     int ka[8];
; #pragma unroll
;     for (int q = 0; q < 8; ++q) ka[q] = kswz<RB>(r32, q * 32 + hi * 16);
;     ...
;     bf16x8 pa0, pa1, pa2, pa3;
;     __syncthreads();
;     DMA(0, 0); DMA(1, 1); VMW0(); __syncthreads();
; __device__ __forceinline__ void attn_item(const AttnBufs& T, int type, int b, int h, int qrow0, int NT, LAS char* lds, int tid_) {
;     ...
;     } else if (MK_ATYPE & 4) {
;         f32x16 o[4]; float l_reg; float rli[16];
;         att::attn_pass<64, ATT_DBL>(T.QC + (size_t)qrow0 * 1024 + h * 128, 1024, T.KC + h * 128, 1024, T.VC + h * 128, 1024, rowc, rowl, NT,
;                            T.lamv[3], o, l_reg, lds, tid);
.LBB0_153:
	v_lshlrev_b32_e32 v144, 4, v176
	v_and_b32_e32 v4, 0x60, v164
	v_lshlrev_b32_e32 v5, 3, v164
	v_add_u32_e32 v194, 0x200, v164
	v_lshlrev_b32_e32 v6, 4, v182
	s_andn2_b64 vcc, exec, s[50:51]
	v_ashrrev_i32_e32 v195, 4, v164
	v_ashrrev_i32_e32 v165, 31, v164
	v_lshlrev_b32_e32 v174, 3, v182
	v_lshrrev_b32_e32 v196, 2, v164
	v_and_or_b32 v193, v5, 24, v4
	v_ashrrev_i32_e32 v197, 4, v194
	v_or_b32_e32 v187, 32, v144
	v_or_b32_e32 v191, 64, v144
	v_or_b32_e32 v192, 0x60, v144
	v_lshlrev_b32_e32 v175, 1, v182
	v_and_b32_e32 v173, 0xc0, v6
	s_cbranch_vccnz .LBB0_171
	s_lshl_b64 s[2:3], s[30:31], 11
	v_readlane_b32 s4, v251, 40
	v_readlane_b32 s5, v251, 41
	s_add_u32 s4, s4, s2
	s_addc_u32 s5, s5, s3
	s_lshl_b32 s48, s72, 7
	s_ashr_i32 s49, s48, 31
	s_lshl_b64 s[2:3], s[48:49], 1
	s_add_u32 s50, s4, s2
	s_addc_u32 s51, s5, s3
	v_readlane_b32 s4, v251, 42
	v_readlane_b32 s5, v251, 43
	s_add_u32 s60, s4, s2
	s_addc_u32 s61, s5, s3
	v_readlane_b32 s4, v251, 44
	v_readlane_b32 s5, v251, 45
	s_add_u32 s56, s4, s2
	v_readfirstlane_b32 s2, v164
	s_addc_u32 s57, s5, s3
	s_ashr_i32 s2, s2, 6
	v_lshl_or_b32 v2, s2, 5, v181
	v_ashrrev_i32_e32 v3, 31, v2
	v_lshlrev_b64 v[2:3], 11, v[2:3]
	v_lshrrev_b32_e32 v1, 29, v165
	v_lshl_add_u64 v[2:3], s[50:51], 0, v[2:3]
	v_mov_b32_e32 v145, v177
	v_add_u32_e32 v1, v164, v1
	v_lshl_add_u64 v[2:3], v[2:3], 0, v[144:145]
	v_ashrrev_i32_e32 v132, 3, v1
	v_and_b32_e32 v1, 0x1ffffff8, v1
	global_load_dword v0, v177, s[14:15] offset:12
	global_load_dwordx4 v[112:115], v[2:3], off
	global_load_dwordx4 v[116:119], v[2:3], off offset:32
	global_load_dwordx4 v[120:123], v[2:3], off offset:64
	global_load_dwordx4 v[124:127], v[2:3], off offset:96
	v_sub_u32_e32 v1, v164, v1
	v_lshrrev_b32_e32 v2, 1, v132
	v_bitop3_b32 v1, v2, v1, 7 bitop3:0x6c
	v_bfi_b32 v128, -8, v195, v196
	v_lshlrev_b32_e32 v2, 3, v1
	s_add_i32 s42, s45, 0x4040
	v_ashrrev_i32_e32 v129, 31, v128
	v_ashrrev_i32_e32 v3, 31, v2
	s_ashr_i32 s43, s42, 31
	v_lshlrev_b64 v[16:17], 1, v[2:3]
	v_lshl_add_u64 v[2:3], v[128:129], 0, s[42:43]
	v_bfi_b32 v130, -8, v197, v196
	v_lshlrev_b64 v[2:3], 11, v[2:3]
	s_ashr_i32 s47, s46, 31
	v_lshlrev_b32_e32 v80, 1, v193
	v_mov_b32_e32 v81, v177
	s_waitcnt lgkmcnt(0)
	v_ashrrev_i32_e32 v131, 31, v130
	v_lshl_add_u64 v[2:3], s[56:57], 0, v[2:3]
	v_lshl_add_u64 v[4:5], v[128:129], 0, s[46:47]
	v_lshl_add_u64 v[148:149], v[2:3], 0, v[80:81]
	v_lshl_add_u64 v[2:3], v[130:131], 0, s[42:43]
	v_lshlrev_b64 v[4:5], 11, v[4:5]
	v_lshlrev_b64 v[2:3], 11, v[2:3]
	v_lshl_add_u64 v[4:5], s[56:57], 0, v[4:5]
	v_ashrrev_i32_e32 v133, 31, v132
	v_lshl_add_u64 v[2:3], s[56:57], 0, v[2:3]
	v_lshl_add_u64 v[140:141], v[4:5], 0, v[80:81]
	v_lshl_add_u64 v[4:5], v[130:131], 0, s[46:47]
	v_lshl_add_u64 v[150:151], v[2:3], 0, v[80:81]
	v_lshl_add_u64 v[2:3], v[132:133], 0, s[42:43]
	v_lshlrev_b64 v[4:5], 11, v[4:5]
	v_lshlrev_b64 v[2:3], 11, v[2:3]
	s_add_i32 s42, s45, 0x4080
	s_lshl_b32 s3, s2, 10
	v_lshl_add_u64 v[4:5], s[56:57], 0, v[4:5]
	v_lshl_add_u64 v[2:3], s[60:61], 0, v[2:3]
	s_ashr_i32 s43, s42, 31
	s_add_i32 s4, s3, 0
	v_lshl_add_u64 v[142:143], v[4:5], 0, v[80:81]
	v_lshl_add_u64 v[4:5], v[132:133], 0, s[46:47]
	v_lshl_add_u64 v[152:153], v[2:3], 0, v[16:17]
	v_lshl_add_u64 v[2:3], v[128:129], 0, s[42:43]
	s_mov_b32 m0, s4
	s_add_i32 s2, s4, 0x2000
	v_lshlrev_b64 v[4:5], 11, v[4:5]
	v_lshlrev_b64 v[2:3], 11, v[2:3]
	s_barrier
	global_load_lds_dwordx4 v[140:141], off
	s_mov_b32 m0, s2
	v_lshl_add_u64 v[4:5], s[60:61], 0, v[4:5]
	s_add_i32 s21, s4, 0xc000
	v_lshl_add_u64 v[2:3], s[56:57], 0, v[2:3]
	global_load_lds_dwordx4 v[142:143], off
	v_lshl_add_u64 v[146:147], v[4:5], 0, v[16:17]
	s_mov_b32 m0, s21
	v_lshl_add_u64 v[154:155], v[2:3], 0, v[80:81]
	v_lshl_add_u64 v[2:3], v[130:131], 0, s[42:43]
	global_load_lds_dwordx4 v[146:147], off
	s_add_i32 m0, s4, 0x4000
	v_lshlrev_b64 v[2:3], 11, v[2:3]
	global_load_lds_dwordx4 v[148:149], off
	s_add_i32 m0, s4, 0x6000
	v_lshl_add_u64 v[2:3], s[56:57], 0, v[2:3]
	global_load_lds_dwordx4 v[150:151], off
	s_add_i32 m0, s4, 0x12000
	v_lshl_add_u64 v[156:157], v[2:3], 0, v[80:81]
	v_lshl_add_u64 v[2:3], v[132:133], 0, s[42:43]
	global_load_lds_dwordx4 v[152:153], off
	s_add_i32 m0, s4, 0x8000
	v_lshlrev_b64 v[2:3], 11, v[2:3]
	s_waitcnt vmcnt(0)
	s_waitcnt vmcnt(0) lgkmcnt(0)
	s_barrier
; #define LAS __attribute__((address_space(3)))
; #define PK8(P, BASE, OUT) do { u32x4 w = {cvt_pk_bf16(P[BASE + 0], P[BASE + 1]), cvt_pk_bf16(P[BASE + 2], P[BASE + 3]), cvt_pk_bf16(P[BASE + 4], P[BASE + 5]), cvt_pk_bf16(P[BASE + 6], P[BASE + 7])}; \
;     OUT = *reinterpret_cast<bf16x8*>(&w); } while (0)
; #define VMW0() asm volatile("s_waitcnt vmcnt(0)" ::: "memory")
; __device__ __forceinline__ void partialSM(f32x16& p0, f32x16& p1) {
; #pragma unroll
;     for (int r = 0; r < 16; ++r) p0[r] = __builtin_amdgcn_exp2f(p0[r]);
; }
; __device__ __forceinline__ void finishSM(f32x16& p0, f32x16& p1, float& l_reg, bf16x8& pa0, bf16x8& pa1, bf16x8& pa2, bf16x8& pa3) {
; #pragma unroll
;     for (int r = 0; r < 16; ++r) p1[r] = __builtin_amdgcn_exp2f(p1[r]);
;     float ps = 0;
; #pragma unroll
;     for (int r = 0; r < 16; ++r) ps += p0[r];
; #pragma unroll
;     for (int r = 0; r < 16; ++r) ps += p1[r];
;     l_reg += ps;
;     ...
;     PK8(p0, 0, pa0); PK8(p0, 8, pa1); PK8(p1, 0, pa2); PK8(p1, 8, pa3);
;     ...
; }
; template <int DQK>
; __device__ __forceinline__ void qkt(f32x16& p0, f32x16& p1, const LAS char* Ks, const bf16x8 (&qr)[DQK / 16], const int (&ka)[8], float nMB) {
;     constexpr int RB = DQK * 2, NA = (RB == 256) ? 8 : 4;
; #pragma unroll
;     for (int r = 0; r < 16; ++r) { p0[r] = nMB; p1[r] = nMB; }
; #pragma unroll
;     for (int d0 = 0; d0 < DQK / 16; ++d0) {
;         const LAS char* a = Ks + ka[d0 % NA] + (d0 / NA) * (NA * 32);
;         const bf16x8 b0 = *(const LAS bf16x8*)(a);
;         const bf16x8 b1 = *(const LAS bf16x8*)(a + 32 * RB);
;         p0 = __builtin_amdgcn_mfma_f32_32x32x16_bf16(b0, qr[d0], p0, 0, 0, 0);
;         p1 = __builtin_amdgcn_mfma_f32_32x32x16_bf16(b1, qr[d0], p1, 0, 0, 0); }
; }
; template <int DQK, bool DOUBLE> ...
;     ...
;     bf16x8 pa0, pa1, pa2, pa3;
;     __syncthreads();
;     DMA(0, 0); DMA(1, 1); VMW0(); __syncthreads();
	global_load_lds_dwordx4 v[154:155], off
	s_add_i32 m0, s4, 0xa000
	v_lshl_add_u64 v[2:3], s[60:61], 0, v[2:3]
	global_load_lds_dwordx4 v[156:157], off
	v_lshl_add_u64 v[158:159], v[2:3], 0, v[16:17]
	s_add_i32 m0, s4, 0x18000
	v_lshlrev_b32_e32 v2, 3, v181
	global_load_lds_dwordx4 v[158:159], off
	v_lshlrev_b32_e32 v1, 7, v181
	v_and_b32_e32 v2, 0x70, v2
	v_bitop3_b32 v145, v144, v1, v2 bitop3:0xde
	v_bitop3_b32 v161, v187, v1, v2 bitop3:0xde
	v_bitop3_b32 v198, v191, v1, v2 bitop3:0xde
	v_bitop3_b32 v199, v192, v1, v2 bitop3:0xde
	v_and_b32_e32 v1, 32, v175
	s_movk_i32 s33, 0x118
	v_and_or_b32 v18, v174, s33, v1
	s_mov_b32 s5, 1
	v_lshlrev_b32_e32 v172, 3, v176
	s_mov_b32 s20, 2
	v_mov_b32_e32 v1, v0
	v_mov_b32_e32 v2, v0
	v_mov_b32_e32 v3, v0
	v_mov_b32_e32 v4, v0
	v_mov_b32_e32 v5, v0
	v_mov_b32_e32 v6, v0
	v_mov_b32_e32 v7, v0
	v_mov_b32_e32 v8, v0
	v_mov_b32_e32 v9, v0
	v_mov_b32_e32 v10, v0
	v_mov_b32_e32 v11, v0
	v_mov_b32_e32 v12, v0
	v_mov_b32_e32 v13, v0
	v_mov_b32_e32 v14, v0
	v_mov_b32_e32 v15, v0
	v_add3_u32 v200, v173, 0, v18
	v_lshl_add_u64 v[134:135], s[60:61], 0, v[16:17]
	s_add_i32 s58, s45, 0x40c0
	v_add_u32_e32 v202, 0, v145
	ds_read_b128 v[16:19], v202 offset:49152
	ds_read_b128 v[48:51], v202 offset:53248
	v_add_u32_e32 v203, 0, v161
	v_add_u32_e32 v204, 0, v198
	v_add_u32_e32 v205, 0, v199
	s_waitcnt lgkmcnt(0)
	v_mfma_f32_32x32x16_bf16 v[32:47], v[16:19], v[112:115], v[0:15]
	v_mfma_f32_32x32x16_bf16 v[16:31], v[48:51], v[112:115], v[0:15]
	ds_read_b128 v[48:51], v203 offset:49152
	ds_read_b128 v[52:55], v203 offset:53248
	s_waitcnt lgkmcnt(0)
	v_mfma_f32_32x32x16_bf16 v[32:47], v[48:51], v[116:119], v[32:47]
	v_mfma_f32_32x32x16_bf16 v[16:31], v[52:55], v[116:119], v[16:31]
	ds_read_b128 v[48:51], v204 offset:49152
	ds_read_b128 v[52:55], v204 offset:53248
	s_waitcnt lgkmcnt(0)
	v_mfma_f32_32x32x16_bf16 v[32:47], v[48:51], v[120:123], v[32:47]
	v_mfma_f32_32x32x16_bf16 v[16:31], v[52:55], v[120:123], v[16:31]
	ds_read_b128 v[48:51], v205 offset:49152
	ds_read_b128 v[52:55], v205 offset:53248
	s_waitcnt lgkmcnt(0)
	v_mfma_f32_32x32x16_bf16 v[32:47], v[48:51], v[124:127], v[32:47]
	v_mfma_f32_32x32x16_bf16 v[16:31], v[52:55], v[124:127], v[16:31]
	s_nop 10
	v_exp_f32_e32 v32, v32
	v_exp_f32_e32 v33, v33
	v_exp_f32_e32 v34, v34
	v_exp_f32_e32 v35, v35
	v_exp_f32_e32 v36, v36
	v_add_f32_e32 v48, 0, v32
	v_exp_f32_e32 v37, v37
	v_add_f32_e32 v48, v33, v48
	v_exp_f32_e32 v38, v38
	v_add_f32_e32 v48, v34, v48
	v_exp_f32_e32 v39, v39
	v_add_f32_e32 v48, v35, v48
	v_exp_f32_e32 v40, v40
	v_add_f32_e32 v48, v36, v48
	v_exp_f32_e32 v41, v41
	v_add_f32_e32 v48, v37, v48
	v_exp_f32_e32 v42, v42
	v_add_f32_e32 v48, v38, v48
	v_exp_f32_e32 v43, v43
	v_add_f32_e32 v48, v39, v48
	v_exp_f32_e32 v44, v44
	v_add_f32_e32 v48, v40, v48
	v_exp_f32_e32 v45, v45
	v_add_f32_e32 v48, v41, v48
	v_exp_f32_e32 v46, v46
	v_add_f32_e32 v48, v42, v48
	v_exp_f32_e32 v47, v47
	v_add_f32_e32 v48, v43, v48
	v_exp_f32_e32 v16, v16
	v_add_f32_e32 v48, v44, v48
	v_exp_f32_e32 v17, v17
	v_add_f32_e32 v48, v45, v48
	v_exp_f32_e32 v18, v18
	v_add_f32_e32 v48, v46, v48
	v_exp_f32_e32 v19, v19
	v_add_f32_e32 v48, v47, v48
	v_exp_f32_e32 v20, v20
	v_add_f32_e32 v48, v16, v48
	v_exp_f32_e32 v21, v21
	v_add_f32_e32 v48, v17, v48
	v_exp_f32_e32 v22, v22
	v_add_f32_e32 v48, v18, v48
	v_exp_f32_e32 v23, v23
	v_add_f32_e32 v48, v19, v48
	v_exp_f32_e32 v24, v24
	v_add_f32_e32 v48, v20, v48
	v_exp_f32_e32 v25, v25
	v_add_f32_e32 v48, v21, v48
	v_exp_f32_e32 v26, v26
	v_add_f32_e32 v48, v22, v48
	v_exp_f32_e32 v27, v27
	v_add_f32_e32 v48, v23, v48
	v_exp_f32_e32 v28, v28
	v_add_f32_e32 v48, v24, v48
	v_exp_f32_e32 v29, v29
	v_add_f32_e32 v48, v25, v48
	v_exp_f32_e32 v30, v30
	v_add_f32_e32 v48, v26, v48
	v_exp_f32_e32 v31, v31
	v_add_f32_e32 v48, v27, v48
	v_add_f32_e32 v48, v28, v48
	v_add_f32_e32 v48, v29, v48
	v_add_f32_e32 v48, v30, v48
	v_add_f32_e32 v48, v31, v48
	v_add_f32_e32 v136, 0, v48
	v_cvt_pk_bf16_f32 v64, v32, v33
	v_cvt_pk_bf16_f32 v65, v34, v35
	v_cvt_pk_bf16_f32 v66, v36, v37
	v_cvt_pk_bf16_f32 v67, v38, v39
	v_cvt_pk_bf16_f32 v82, v40, v41
	v_cvt_pk_bf16_f32 v83, v42, v43
	v_cvt_pk_bf16_f32 v84, v44, v45
	v_cvt_pk_bf16_f32 v85, v46, v47
	v_cvt_pk_bf16_f32 v86, v16, v17
	v_cvt_pk_bf16_f32 v87, v18, v19
	v_cvt_pk_bf16_f32 v88, v20, v21
	v_cvt_pk_bf16_f32 v89, v22, v23
	v_cvt_pk_bf16_f32 v90, v24, v25
	v_cvt_pk_bf16_f32 v91, v26, v27
	v_cvt_pk_bf16_f32 v92, v28, v29
	v_cvt_pk_bf16_f32 v93, v30, v31
	ds_read_b64_tr_b16 v[16:17], v200 offset:0
	ds_read_b64_tr_b16 v[18:19], v200 offset:0x800
	ds_read_b64_tr_b16 v[32:33], v200 offset:0x1000
	ds_read_b64_tr_b16 v[34:35], v200 offset:0x1800
	ds_read_b64_tr_b16 v[36:37], v200 offset:0x2000
	ds_read_b64_tr_b16 v[38:39], v200 offset:0x2800
	ds_read_b64_tr_b16 v[40:41], v200 offset:0x3000
	ds_read_b64_tr_b16 v[42:43], v200 offset:0x3800
	s_waitcnt lgkmcnt(0)
	s_nop 0
	v_mfma_f32_32x32x16_bf16 v[16:31], v[64:67], v[16:19], 0
	v_mfma_f32_32x32x16_bf16 v[16:31], v[82:85], v[32:35], v[16:31]
	ds_read_b64_tr_b16 v[32:33], v200 offset:0x200
	ds_read_b64_tr_b16 v[34:35], v200 offset:0xa00
	ds_read_b64_tr_b16 v[48:49], v200 offset:0x1200
	ds_read_b64_tr_b16 v[50:51], v200 offset:0x1a00
	ds_read_b64_tr_b16 v[52:53], v200 offset:0x2200
	ds_read_b64_tr_b16 v[54:55], v200 offset:0x2a00
	ds_read_b64_tr_b16 v[56:57], v200 offset:0x3200
	v_mfma_f32_32x32x16_bf16 v[16:31], v[86:89], v[36:39], v[16:31]
	ds_read_b64_tr_b16 v[58:59], v200 offset:0x3a00
	s_waitcnt lgkmcnt(0)
; template <int D0> __device__ __forceinline__ void pv_one(f32x16& od, unsigned vb, bf16x8 pa0, bf16x8 pa1, bf16x8 pa2, bf16x8 pa3) {
;     const s16x4 l0 = tr_read<v_rd_off(D0, 0, 0)>(vb), h0 = tr_read<v_rd_off(D0, 0, 1)>(vb), l1 = tr_read<v_rd_off(D0, 1, 0)>(vb), h1 = tr_read<v_rd_off(D0, 1, 1)>(vb);
;     const s16x4 l2 = tr_read<v_rd_off(D0, 2, 0)>(vb), h2 = tr_read<v_rd_off(D0, 2, 1)>(vb), l3 = tr_read<v_rd_off(D0, 3, 0)>(vb), h3 = tr_read<v_rd_off(D0, 3, 1)>(vb);
;     asm volatile("s_waitcnt lgkmcnt(0)" ::: "memory"); SBAR();
;     ...
;     od = __builtin_amdgcn_mfma_f32_32x32x16_bf16(pa0, PK(l0, h0), od, 0, 0, 0);
;     od = __builtin_amdgcn_mfma_f32_32x32x16_bf16(pa1, PK(l1, h1), od, 0, 0, 0);
;     od = __builtin_amdgcn_mfma_f32_32x32x16_bf16(pa2, PK(l2, h2), od, 0, 0, 0);
;     od = __builtin_amdgcn_mfma_f32_32x32x16_bf16(pa3, PK(l3, h3), od, 0, 0, 0);
;     ...
; }
; __device__ __forceinline__ void pv_d0(f32x16 (&o)[4], unsigned vb, bf16x8 pa0, bf16x8 pa1, bf16x8 pa2, bf16x8 pa3) {
;     pv_one<0>(o[0], vb, pa0, pa1, pa2, pa3); pv_one<1>(o[1], vb, pa0, pa1, pa2, pa3); pv_one<2>(o[2], vb, pa0, pa1, pa2, pa3); pv_one<3>(o[3], vb, pa0, pa1, pa2, pa3);
; }
; template <int DQK>
; __device__ __forceinline__ void qkt(f32x16& p0, f32x16& p1, const LAS char* Ks, const bf16x8 (&qr)[DQK / 16], const int (&ka)[8], float nMB) {
;     constexpr int RB = DQK * 2, NA = (RB == 256) ? 8 : 4;
; #pragma unroll
;     for (int r = 0; r < 16; ++r) { p0[r] = nMB; p1[r] = nMB; }
; #pragma unroll
;     for (int d0 = 0; d0 < DQK / 16; ++d0) {
;         const LAS char* a = Ks + ka[d0 % NA] + (d0 / NA) * (NA * 32);
;         const bf16x8 b0 = *(const LAS bf16x8*)(a);
;         const bf16x8 b1 = *(const LAS bf16x8*)(a + 32 * RB);
;         p0 = __builtin_amdgcn_mfma_f32_32x32x16_bf16(b0, qr[d0], p0, 0, 0, 0);
;         p1 = __builtin_amdgcn_mfma_f32_32x32x16_bf16(b1, qr[d0], p1, 0, 0, 0); }
; }
; template <int DQK, bool DOUBLE> ...
;     ...
;         for (int j = 0; j < NT; ++j) {
;             SBAR(); qkt<DQK>(p0, p1, K_lds + bc * K_STRIDE, qr, ka, nMB);
;             partialSM(p0, p1); finishSM(p0, p1, l_reg, pa0, pa1, pa2, pa3); SBAR();
;             pv_d0(o, vb0 + bc * V_BYTES, pa0, pa1, pa2, pa3);
;             if (j + 1 < NT) { VMW0(); __syncthreads(); if (j + 3 < NT) DMA(j + 3, bc); }
;             { const int _t = bc; bc = bn; bn = bf; bf = _t; }
;         }
	v_mfma_f32_32x32x16_bf16 v[16:31], v[90:93], v[40:43], v[16:31]
	v_mfma_f32_32x32x16_bf16 v[32:47], v[64:67], v[32:35], 0
	v_mfma_f32_32x32x16_bf16 v[32:47], v[82:85], v[48:51], v[32:47]
	ds_read_b64_tr_b16 v[48:49], v200 offset:0x400
	ds_read_b64_tr_b16 v[50:51], v200 offset:0xc00
	ds_read_b64_tr_b16 v[68:69], v200 offset:0x1400
	ds_read_b64_tr_b16 v[70:71], v200 offset:0x1c00
	ds_read_b64_tr_b16 v[72:73], v200 offset:0x2400
	ds_read_b64_tr_b16 v[74:75], v200 offset:0x2c00
	ds_read_b64_tr_b16 v[76:77], v200 offset:0x3400
	v_mfma_f32_32x32x16_bf16 v[32:47], v[86:89], v[52:55], v[32:47]
	ds_read_b64_tr_b16 v[78:79], v200 offset:0x3c00
	s_waitcnt lgkmcnt(0)
	v_mfma_f32_32x32x16_bf16 v[32:47], v[90:93], v[56:59], v[32:47]
	v_mfma_f32_32x32x16_bf16 v[48:63], v[64:67], v[48:51], 0
	v_mfma_f32_32x32x16_bf16 v[48:63], v[82:85], v[68:71], v[48:63]
	ds_read_b64_tr_b16 v[68:69], v200 offset:0x600
	ds_read_b64_tr_b16 v[70:71], v200 offset:0xe00
	ds_read_b64_tr_b16 v[94:95], v200 offset:0x1600
	ds_read_b64_tr_b16 v[96:97], v200 offset:0x1e00
	ds_read_b64_tr_b16 v[98:99], v200 offset:0x2600
	ds_read_b64_tr_b16 v[100:101], v200 offset:0x2e00
	ds_read_b64_tr_b16 v[102:103], v200 offset:0x3600
	v_mfma_f32_32x32x16_bf16 v[48:63], v[86:89], v[72:75], v[48:63]
	ds_read_b64_tr_b16 v[104:105], v200 offset:0x3e00
	s_waitcnt lgkmcnt(0)
	v_mfma_f32_32x32x16_bf16 v[48:63], v[90:93], v[76:79], v[48:63]
	v_mfma_f32_32x32x16_bf16 v[64:79], v[64:67], v[68:71], 0
	s_ashr_i32 s59, s58, 31
	v_lshl_add_u64 v[106:107], v[128:129], 0, s[58:59]
	v_lshlrev_b64 v[106:107], 11, v[106:107]
	v_lshl_add_u64 v[106:107], s[56:57], 0, v[106:107]
	v_lshl_add_u64 v[166:167], v[106:107], 0, v[80:81]
	v_lshl_add_u64 v[106:107], v[130:131], 0, s[58:59]
	s_mov_b32 m0, s4
	v_mfma_f32_32x32x16_bf16 v[64:79], v[82:85], v[94:97], v[64:79]
	v_lshlrev_b64 v[82:83], 11, v[106:107]
	v_lshl_add_u64 v[82:83], s[56:57], 0, v[82:83]
	v_lshl_add_u64 v[168:169], v[82:83], 0, v[80:81]
	v_lshl_add_u64 v[82:83], v[132:133], 0, s[58:59]
	s_waitcnt vmcnt(0)
	s_waitcnt vmcnt(0)
	s_barrier
	global_load_lds_dwordx4 v[166:167], off
	s_mov_b32 m0, s2
	v_lshlrev_b64 v[82:83], 11, v[82:83]
	global_load_lds_dwordx4 v[168:169], off
	v_lshl_add_u64 v[170:171], v[134:135], 0, v[82:83]
	s_mov_b32 m0, s21
	v_mfma_f32_32x32x16_bf16 v[64:79], v[86:89], v[98:101], v[64:79]
	global_load_lds_dwordx4 v[170:171], off
	v_lshl_add_u64 v[138:139], s[56:57], 0, v[80:81]
	s_add_i32 s2, s71, -1
	s_mov_b32 s21, 0
	s_mov_b32 s56, s44
	s_mov_b32 s35, 0
	v_mfma_f32_32x32x16_bf16 v[64:79], v[90:93], v[102:105], v[64:79]
	s_waitcnt lgkmcnt(0)
	s_mul_i32 s42, s5, 0x6000
	v_add_u32_e32 v206, s42, v145
	v_add_u32_e32 v207, s42, v161
	v_add_u32_e32 v208, s42, v198
	v_add_u32_e32 v209, s42, v199
	ds_read_b128 v[222:225], v206 offset:49152
	ds_read_b128 v[238:241], v207 offset:49152
	ds_read_b128 v[242:245], v208 offset:49152
.LBB0_155:
	s_mov_b32 s33, s20
	s_mov_b32 s20, s35
	s_mul_i32 s35, s5, 0x6000
	s_add_i32 s35, s35, 0
	s_lshl_b32 s41, s5, 14
	v_add_u32_e32 v137, s41, v200
	s_waitcnt lgkmcnt(2)
	v_mfma_f32_32x32x16_bf16 v[96:111], v[222:225], v[112:115], v[0:15]
	ds_read_b128 v[246:249], v209 offset:49152
	s_waitcnt lgkmcnt(2)
	v_mfma_f32_32x32x16_bf16 v[96:111], v[238:241], v[116:119], v[96:111]
	ds_read_b128 v[222:225], v206 offset:53248
	s_waitcnt lgkmcnt(2)
	v_mfma_f32_32x32x16_bf16 v[96:111], v[242:245], v[120:123], v[96:111]
	ds_read_b128 v[238:241], v207 offset:53248
	s_waitcnt lgkmcnt(2)
	v_mfma_f32_32x32x16_bf16 v[96:111], v[246:249], v[124:127], v[96:111]
	ds_read_b128 v[242:245], v208 offset:53248
	s_waitcnt lgkmcnt(2)
	v_mfma_f32_32x32x16_bf16 v[80:95], v[222:225], v[112:115], v[0:15]
	ds_read_b128 v[246:249], v209 offset:53248
	s_waitcnt lgkmcnt(2)
	v_mfma_f32_32x32x16_bf16 v[80:95], v[238:241], v[116:119], v[80:95]
	ds_read_b64_tr_b16 v[222:223], v137 offset:0
	ds_read_b64_tr_b16 v[224:225], v137 offset:2048
	s_nop 3
	v_exp_f32_e32 v96, v96
	v_exp_f32_e32 v97, v97
	v_exp_f32_e32 v98, v98
	v_exp_f32_e32 v99, v99
	v_exp_f32_e32 v104, v104
	v_exp_f32_e32 v105, v105
	s_waitcnt lgkmcnt(3)
	v_mfma_f32_32x32x16_bf16 v[80:95], v[242:245], v[120:123], v[80:95]
	ds_read_b64_tr_b16 v[238:239], v137 offset:512
	ds_read_b64_tr_b16 v[240:241], v137 offset:2560
	v_exp_f32_e32 v100, v100
	v_exp_f32_e32 v101, v101
	v_exp_f32_e32 v102, v102
	v_exp_f32_e32 v103, v103
	v_exp_f32_e32 v106, v106
	v_exp_f32_e32 v107, v107
	s_waitcnt lgkmcnt(4)
	v_mfma_f32_32x32x16_bf16 v[80:95], v[246:249], v[124:127], v[80:95]
	ds_read_b64_tr_b16 v[242:243], v137 offset:1024
	ds_read_b64_tr_b16 v[244:245], v137 offset:3072
	v_cvt_pk_bf16_f32 v206, v96, v97
	v_cvt_pk_bf16_f32 v207, v98, v99
	v_cvt_pk_bf16_f32 v208, v100, v101
	v_cvt_pk_bf16_f32 v209, v102, v103
	v_exp_f32_e32 v108, v108
	v_exp_f32_e32 v109, v109
	v_add_f32_e32 v96, 0, v96
	v_add_f32_e32 v96, v97, v96
	s_waitcnt lgkmcnt(4)
	v_mfma_f32_32x32x16_bf16 v[16:31], v[206:209], v[222:225], v[16:31]
	ds_read_b64_tr_b16 v[246:247], v137 offset:1536
	ds_read_b64_tr_b16 v[248:249], v137 offset:3584
	v_exp_f32_e32 v110, v110
	v_exp_f32_e32 v111, v111
	v_add_f32_e32 v96, v98, v96
	v_add_f32_e32 v96, v99, v96
	s_waitcnt lgkmcnt(4)
; #define SBAR() __builtin_amdgcn_sched_barrier(0)
; #define VMW0() asm volatile("s_waitcnt vmcnt(0)" ::: "memory")
; template <int D0> __device__ __forceinline__ void pv_one(f32x16& od, unsigned vb, bf16x8 pa0, bf16x8 pa1, bf16x8 pa2, bf16x8 pa3) {
;     const s16x4 l0 = tr_read<v_rd_off(D0, 0, 0)>(vb), h0 = tr_read<v_rd_off(D0, 0, 1)>(vb), l1 = tr_read<v_rd_off(D0, 1, 0)>(vb), h1 = tr_read<v_rd_off(D0, 1, 1)>(vb);
;     const s16x4 l2 = tr_read<v_rd_off(D0, 2, 0)>(vb), h2 = tr_read<v_rd_off(D0, 2, 1)>(vb), l3 = tr_read<v_rd_off(D0, 3, 0)>(vb), h3 = tr_read<v_rd_off(D0, 3, 1)>(vb);
;     asm volatile("s_waitcnt lgkmcnt(0)" ::: "memory"); SBAR();
;     ...
;     od = __builtin_amdgcn_mfma_f32_32x32x16_bf16(pa0, PK(l0, h0), od, 0, 0, 0);
;     od = __builtin_amdgcn_mfma_f32_32x32x16_bf16(pa1, PK(l1, h1), od, 0, 0, 0);
;     od = __builtin_amdgcn_mfma_f32_32x32x16_bf16(pa2, PK(l2, h2), od, 0, 0, 0);
;     od = __builtin_amdgcn_mfma_f32_32x32x16_bf16(pa3, PK(l3, h3), od, 0, 0, 0);
;     ...
; }
; __device__ __forceinline__ void pv_d0(f32x16 (&o)[4], unsigned vb, bf16x8 pa0, bf16x8 pa1, bf16x8 pa2, bf16x8 pa3) {
;     pv_one<0>(o[0], vb, pa0, pa1, pa2, pa3); pv_one<1>(o[1], vb, pa0, pa1, pa2, pa3); pv_one<2>(o[2], vb, pa0, pa1, pa2, pa3); pv_one<3>(o[3], vb, pa0, pa1, pa2, pa3);
; }
; template <int DQK, bool DOUBLE> ...
;     ...
;         for (int j = 0; j < NT; ++j) {
;             SBAR(); qkt<DQK>(p0, p1, K_lds + bc * K_STRIDE, qr, ka, nMB);
;             partialSM(p0, p1); finishSM(p0, p1, l_reg, pa0, pa1, pa2, pa3); SBAR();
;             pv_d0(o, vb0 + bc * V_BYTES, pa0, pa1, pa2, pa3);
;             if (j + 1 < NT) { VMW0(); __syncthreads(); if (j + 3 < NT) DMA(j + 3, bc); }
;             { const int _t = bc; bc = bn; bn = bf; bf = _t; }
;         }
	v_mfma_f32_32x32x16_bf16 v[32:47], v[206:209], v[238:241], v[32:47]
	ds_read_b64_tr_b16 v[222:223], v137 offset:4096
	ds_read_b64_tr_b16 v[224:225], v137 offset:6144
	v_cvt_pk_bf16_f32 v210, v104, v105
	v_cvt_pk_bf16_f32 v211, v106, v107
	v_exp_f32_e32 v80, v80
	v_exp_f32_e32 v81, v81
	v_exp_f32_e32 v88, v88
	v_exp_f32_e32 v89, v89
	v_add_f32_e32 v96, v100, v96
	v_add_f32_e32 v96, v101, v96
	s_waitcnt lgkmcnt(4)
	v_mfma_f32_32x32x16_bf16 v[48:63], v[206:209], v[242:245], v[48:63]
	ds_read_b64_tr_b16 v[238:239], v137 offset:4608
	ds_read_b64_tr_b16 v[240:241], v137 offset:6656
	v_cvt_pk_bf16_f32 v212, v108, v109
	v_exp_f32_e32 v82, v82
	v_exp_f32_e32 v83, v83
	v_exp_f32_e32 v90, v90
	v_add_f32_e32 v96, v102, v96
	v_add_f32_e32 v96, v103, v96
	s_waitcnt lgkmcnt(4)
	v_mfma_f32_32x32x16_bf16 v[64:79], v[206:209], v[246:249], v[64:79]
	ds_read_b64_tr_b16 v[242:243], v137 offset:5120
	ds_read_b64_tr_b16 v[244:245], v137 offset:7168
	v_cvt_pk_bf16_f32 v213, v110, v111
	v_exp_f32_e32 v84, v84
	v_exp_f32_e32 v85, v85
	v_exp_f32_e32 v91, v91
	v_add_f32_e32 v96, v104, v96
	v_add_f32_e32 v96, v105, v96
	s_waitcnt lgkmcnt(4)
	v_mfma_f32_32x32x16_bf16 v[16:31], v[210:213], v[222:225], v[16:31]
	ds_read_b64_tr_b16 v[246:247], v137 offset:5632
	ds_read_b64_tr_b16 v[248:249], v137 offset:7680
	v_exp_f32_e32 v86, v86
	v_exp_f32_e32 v87, v87
	v_exp_f32_e32 v92, v92
	v_add_f32_e32 v96, v106, v96
	v_add_f32_e32 v96, v107, v96
	s_waitcnt lgkmcnt(4)
	v_mfma_f32_32x32x16_bf16 v[32:47], v[210:213], v[238:241], v[32:47]
	ds_read_b64_tr_b16 v[222:223], v137 offset:8192
	ds_read_b64_tr_b16 v[224:225], v137 offset:10240
	v_cvt_pk_bf16_f32 v214, v80, v81
	v_cvt_pk_bf16_f32 v215, v82, v83
	v_exp_f32_e32 v93, v93
	v_add_f32_e32 v96, v108, v96
	v_add_f32_e32 v96, v109, v96
	s_waitcnt lgkmcnt(4)
	v_mfma_f32_32x32x16_bf16 v[48:63], v[210:213], v[242:245], v[48:63]
	ds_read_b64_tr_b16 v[238:239], v137 offset:8704
	ds_read_b64_tr_b16 v[240:241], v137 offset:10752
	v_cvt_pk_bf16_f32 v216, v84, v85
	v_exp_f32_e32 v94, v94
	v_add_f32_e32 v96, v110, v96
	v_add_f32_e32 v96, v111, v96
	s_waitcnt lgkmcnt(4)
	v_mfma_f32_32x32x16_bf16 v[64:79], v[210:213], v[246:249], v[64:79]
	ds_read_b64_tr_b16 v[242:243], v137 offset:9216
	ds_read_b64_tr_b16 v[244:245], v137 offset:11264
	v_cvt_pk_bf16_f32 v217, v86, v87
	v_exp_f32_e32 v95, v95
	v_add_f32_e32 v80, v80, v96
	v_add_f32_e32 v80, v81, v80
	s_waitcnt lgkmcnt(4)
	v_mfma_f32_32x32x16_bf16 v[16:31], v[214:217], v[222:225], v[16:31]
	ds_read_b64_tr_b16 v[246:247], v137 offset:9728
	ds_read_b64_tr_b16 v[248:249], v137 offset:11776
	v_cvt_pk_bf16_f32 v218, v88, v89
	v_add_f32_e32 v80, v82, v80
	v_add_f32_e32 v80, v83, v80
	v_add_f32_e32 v80, v84, v80
	s_waitcnt lgkmcnt(4)
	v_mfma_f32_32x32x16_bf16 v[32:47], v[214:217], v[238:241], v[32:47]
	ds_read_b64_tr_b16 v[222:223], v137 offset:12288
	ds_read_b64_tr_b16 v[224:225], v137 offset:14336
	v_cvt_pk_bf16_f32 v219, v90, v91
	v_add_f32_e32 v80, v85, v80
	v_add_f32_e32 v80, v86, v80
	v_add_f32_e32 v80, v87, v80
	s_waitcnt lgkmcnt(4)
	v_mfma_f32_32x32x16_bf16 v[48:63], v[214:217], v[242:245], v[48:63]
	ds_read_b64_tr_b16 v[238:239], v137 offset:12800
	ds_read_b64_tr_b16 v[240:241], v137 offset:14848
	v_cvt_pk_bf16_f32 v220, v92, v93
	s_waitcnt lgkmcnt(4)
	v_mfma_f32_32x32x16_bf16 v[64:79], v[214:217], v[246:249], v[64:79]
	ds_read_b64_tr_b16 v[242:243], v137 offset:13312
	ds_read_b64_tr_b16 v[244:245], v137 offset:15360
	v_cvt_pk_bf16_f32 v221, v94, v95
	v_add_f32_e32 v80, v88, v80
	v_add_f32_e32 v80, v89, v80
	v_add_f32_e32 v80, v90, v80
	s_waitcnt lgkmcnt(4)
	v_mfma_f32_32x32x16_bf16 v[16:31], v[218:221], v[222:225], v[16:31]
	ds_read_b64_tr_b16 v[246:247], v137 offset:13824
	ds_read_b64_tr_b16 v[248:249], v137 offset:15872
	s_mul_i32 s42, s33, 0x6000
	v_add_u32_e32 v206, s42, v145
	v_add_u32_e32 v207, s42, v161
	v_add_u32_e32 v208, s42, v198
	v_add_u32_e32 v209, s42, v199
	v_add_f32_e32 v80, v91, v80
	v_add_f32_e32 v80, v92, v80
	v_add_f32_e32 v80, v93, v80
	v_add_f32_e32 v80, v94, v80
	s_waitcnt lgkmcnt(4)
	v_mfma_f32_32x32x16_bf16 v[32:47], v[218:221], v[238:241], v[32:47]
	ds_read_b128 v[222:225], v206 offset:49152
	v_add_f32_e32 v80, v95, v80
	s_waitcnt lgkmcnt(3)
	v_mfma_f32_32x32x16_bf16 v[48:63], v[218:221], v[242:245], v[48:63]
	ds_read_b128 v[238:241], v207 offset:49152
	s_waitcnt lgkmcnt(2)
	v_mfma_f32_32x32x16_bf16 v[64:79], v[218:221], v[246:249], v[64:79]
	ds_read_b128 v[242:245], v208 offset:49152
	s_add_i32 s42, s21, 2
	s_cmp_ge_i32 s42, s71
	s_cbranch_scc1 .LBB0_158
	s_waitcnt vmcnt(0)
	s_add_i32 s42, s21, 4
	s_cmp_ge_i32 s42, s71
	s_waitcnt vmcnt(0)
	s_barrier
	s_cbranch_scc1 .LBB0_158
	s_ashr_i32 s57, s56, 31
	v_lshl_add_u64 v[184:185], s[56:57], 0, v[128:129]
	s_add_i32 s41, s4, s41
	v_lshlrev_b64 v[184:185], 11, v[184:185]
	v_lshl_add_u64 v[184:185], v[138:139], 0, v[184:185]
	s_mov_b32 m0, s41
	s_add_i32 s35, s35, s3
	global_load_lds_dwordx4 v[184:185], off
	v_lshl_add_u64 v[184:185], s[56:57], 0, v[130:131]
	v_lshlrev_b64 v[184:185], 11, v[184:185]
	v_lshl_add_u64 v[184:185], v[138:139], 0, v[184:185]
	s_add_i32 m0, s41, 0x2000
	s_nop 0
	global_load_lds_dwordx4 v[184:185], off
	v_lshl_add_u64 v[184:185], s[56:57], 0, v[132:133]
	v_lshlrev_b64 v[184:185], 11, v[184:185]
	v_lshl_add_u64 v[184:185], v[134:135], 0, v[184:185]
	s_add_i32 m0, s35, 0xc000
	s_nop 0
	global_load_lds_dwordx4 v[184:185], off

; template <int DQK, bool DOUBLE> ...
;     constexpr int RB = DQK * 2, NCH = DQK / 8, NLD = NCH / 8;
;     const int wid = __builtin_amdgcn_readfirstlane(tid >> 6), lane = tid & 63, r32 = lane & 31, hi = lane >> 5;
;     LAS char* V_lds = lds; LAS char* K_lds = lds + K_OFF;
;     bf16x8 qr[DQK / 16];
;     { const bf16_t* Qw = Q + (size_t)(wid * 32 + r32) * ldq + hi * 8;
; #pragma unroll
;       for (int d0 = 0; d0 < DQK / 16; ++d0) qr[d0] = *(const bf16x8*)(Qw + d0 * 16); }
; #pragma unroll
;     for (int d = 0; d < 4; ++d) o[d] = f32x16{};
;     l_reg = 0.f;
;     int vrow[2], vcol[2], krow[NLD], kcol[NLD];
; #pragma unroll
;     for (int i = 0; i < 2; ++i) { const int q = tid + 512 * i, sub = q >> 5, within = q & 31, kk = (sub >> 2) * 8 + (within >> 2);
;         vrow[i] = kk; vcol[i] = (sub & 3) * 32 + (within & 3) * 8; }
; #pragma unroll
;     for (int i = 0; i < NLD; ++i) { const int q = tid + 512 * i, row = q / NCH, chp = q % NCH; const int x = (RB == 256) ? (row & 15) : ((row >> 1) & 7);
;         krow[i] = row; kcol[i] = (chp ^ x) * 8; }
; __device__ __forceinline__ void row_recip(float l_reg, float (&rli)[16], LAS float* li, int r32, int hi) {
;     { auto rr = __builtin_amdgcn_permlane32_swap(__float_as_uint(l_reg), __float_as_uint(l_reg), false, false);
;       l_reg = __uint_as_float(rr[0]) + __uint_as_float(rr[1]); }
;     if (hi == 0) li[r32] = l_reg;
;     asm volatile("s_waitcnt lgkmcnt(0)" ::: "memory");
; #pragma unroll
;     for (int r = 0; r < 16; ++r) rli[r] = __builtin_amdgcn_rcpf(li[crow(r, hi)]);
;     asm volatile("s_waitcnt lgkmcnt(0)" ::: "memory");
; }
; __device__ __forceinline__ void attn_item(const AttnBufs& T, int type, int b, int h, int qrow0, int NT, LAS char* lds, int tid_) {
;     ...
;         att::row_recip(l_reg, rli, li, r32, hi);
;         f32x4* scr = (f32x4*)(T.SCR + ((size_t)blockIdx.x * 512 + tid) * 64);
; #pragma unroll
;         for (int d0 = 0; d0 < 4; ++d0)
; #pragma unroll
;             for (int q = 0; q < 4; ++q) scr[d0 * 4 + q] = (f32x4){o[d0][q * 4] * rli[q * 4], o[d0][q * 4 + 1] * rli[q * 4 + 1], o[d0][q * 4 + 2] * rli[q * 4 + 2], o[d0][q * 4 + 3] * rli[q * 4 + 3]};
;         att::attn_pass<64, ATT_DBL>(T.QC + (size_t)qrow0 * 1024 + h * 128 + 64, 1024, T.KC + h * 128 + 64, 1024, T.VC + h * 128, 1024, rowc, rowl, NT,
;                            T.lamv[3], o, l_reg, lds, tid);
.LBB0_160:
	s_waitcnt lgkmcnt(0)
	s_nop 11
	v_mov_b32_e32 v0, v136
	s_nop 1
	v_permlane32_swap_b32_e32 v136, v0
	v_cmp_gt_u32_e32 vcc, 32, v182
	s_and_saveexec_b64 s[56:57], vcc
	v_lshl_add_u32 v1, v181, 2, s90
	v_add_f32_e32 v0, v136, v0
	ds_write_b32 v1, v0
	s_or_b64 exec, exec, s[56:57]
	s_waitcnt lgkmcnt(0)
	v_add_u32_e32 v201, s90, v144
	ds_read_b128 v[0:3], v201
	ds_read_b128 v[4:7], v201 offset:32
	v_readlane_b32 s4, v253, 11
	v_readlane_b32 s5, v253, 12
	v_readfirstlane_b32 s3, v164
	s_waitcnt lgkmcnt(0)
	v_rcp_f32_e32 v8, v0
	v_rcp_f32_e32 v9, v1
	v_rcp_f32_e32 v10, v2
	v_rcp_f32_e32 v11, v3
	ds_read_b128 v[0:3], v201 offset:64
	v_rcp_f32_e32 v12, v4
	v_rcp_f32_e32 v13, v5
	v_rcp_f32_e32 v14, v6
	v_rcp_f32_e32 v15, v7
	ds_read_b128 v[4:7], v201 offset:96
	s_waitcnt lgkmcnt(0)
	v_rcp_f32_e32 v80, v0
	v_rcp_f32_e32 v81, v1
	v_rcp_f32_e32 v82, v2
	v_rcp_f32_e32 v83, v3
	v_rcp_f32_e32 v4, v4
	v_rcp_f32_e32 v5, v5
	v_rcp_f32_e32 v6, v6
	v_rcp_f32_e32 v7, v7
	v_lshlrev_b64 v[0:1], 8, v[164:165]
	v_lshl_add_u64 v[136:137], s[4:5], 0, v[0:1]
	v_pk_mul_f32 v[0:1], v[16:17], v[8:9]
	v_pk_mul_f32 v[2:3], v[18:19], v[10:11]
	s_waitcnt lgkmcnt(0)
	global_store_dwordx4 v[136:137], v[0:3], off
	s_ashr_i32 s3, s3, 6
	s_mov_b32 s5, 1
	v_pk_mul_f32 v[0:1], v[20:21], v[12:13]
	v_pk_mul_f32 v[2:3], v[22:23], v[14:15]
	global_store_dwordx4 v[136:137], v[0:3], off offset:16
	s_nop 1
	v_pk_mul_f32 v[0:1], v[24:25], v[80:81]
	v_pk_mul_f32 v[2:3], v[26:27], v[82:83]
	global_store_dwordx4 v[136:137], v[0:3], off offset:32
	s_nop 1
	v_pk_mul_f32 v[0:1], v[28:29], v[4:5]
	v_pk_mul_f32 v[2:3], v[30:31], v[6:7]
	global_store_dwordx4 v[136:137], v[0:3], off offset:48
	s_nop 1
	v_pk_mul_f32 v[0:1], v[32:33], v[8:9]
	v_pk_mul_f32 v[2:3], v[34:35], v[10:11]
	global_store_dwordx4 v[136:137], v[0:3], off offset:64
	s_nop 1
	v_pk_mul_f32 v[0:1], v[36:37], v[12:13]
	v_pk_mul_f32 v[2:3], v[38:39], v[14:15]
	global_store_dwordx4 v[136:137], v[0:3], off offset:80
	s_nop 1
	v_pk_mul_f32 v[0:1], v[40:41], v[80:81]
	v_pk_mul_f32 v[2:3], v[42:43], v[82:83]
	global_store_dwordx4 v[136:137], v[0:3], off offset:96
	s_nop 1
	v_pk_mul_f32 v[0:1], v[44:45], v[4:5]
	v_pk_mul_f32 v[2:3], v[46:47], v[6:7]
	global_store_dwordx4 v[136:137], v[0:3], off offset:112
	s_nop 1
	v_pk_mul_f32 v[0:1], v[48:49], v[8:9]
	v_pk_mul_f32 v[2:3], v[50:51], v[10:11]
	global_store_dwordx4 v[136:137], v[0:3], off offset:128
	s_nop 1
	v_pk_mul_f32 v[0:1], v[52:53], v[12:13]
	v_pk_mul_f32 v[2:3], v[54:55], v[14:15]
	global_store_dwordx4 v[136:137], v[0:3], off offset:144
	s_nop 1
	v_pk_mul_f32 v[0:1], v[56:57], v[80:81]
	v_pk_mul_f32 v[2:3], v[58:59], v[82:83]
	global_store_dwordx4 v[136:137], v[0:3], off offset:160
	s_nop 1
	v_pk_mul_f32 v[0:1], v[60:61], v[4:5]
	v_pk_mul_f32 v[2:3], v[62:63], v[6:7]
	global_store_dwordx4 v[136:137], v[0:3], off offset:176
	s_nop 1
	v_pk_mul_f32 v[0:1], v[64:65], v[8:9]
	v_pk_mul_f32 v[2:3], v[66:67], v[10:11]
	global_store_dwordx4 v[136:137], v[0:3], off offset:192
	s_nop 1
	v_pk_mul_f32 v[0:1], v[68:69], v[12:13]
	v_pk_mul_f32 v[2:3], v[70:71], v[14:15]
	global_store_dwordx4 v[136:137], v[0:3], off offset:208
	s_nop 1
	v_pk_mul_f32 v[0:1], v[72:73], v[80:81]
	v_pk_mul_f32 v[2:3], v[74:75], v[82:83]
	global_store_dwordx4 v[136:137], v[0:3], off offset:224
	s_nop 1
	v_pk_mul_f32 v[0:1], v[76:77], v[4:5]
	v_pk_mul_f32 v[2:3], v[78:79], v[6:7]
	global_store_dwordx4 v[136:137], v[0:3], off offset:240
	global_load_dword v48, v177, s[14:15] offset:12
	s_waitcnt vmcnt(0)
	v_mov_b32_e32 v49, v48
	v_lshl_or_b32 v0, s3, 5, v181
	v_ashrrev_i32_e32 v1, 31, v0
	v_lshlrev_b64 v[0:1], 11, v[0:1]
	s_lshl_b32 s3, s3, 10
	v_lshl_add_u64 v[0:1], s[50:51], 0, v[0:1]
	v_lshlrev_b32_e32 v2, 1, v172
	v_mov_b32_e32 v3, v177
	s_add_i32 s4, s3, 0
	v_lshl_add_u64 v[0:1], v[0:1], 0, v[2:3]
	s_mov_b32 m0, s4
	s_add_i32 s20, s4, 0x2000
	global_load_dwordx4 v[112:115], v[0:1], off offset:128
	global_load_dwordx4 v[116:119], v[0:1], off offset:160
	global_load_dwordx4 v[120:123], v[0:1], off offset:192
	global_load_dwordx4 v[124:127], v[0:1], off offset:224
	s_barrier
	global_load_lds_dwordx4 v[140:141], off
	s_mov_b32 m0, s20
	s_add_i32 s21, s4, 0xc000
	global_load_lds_dwordx4 v[142:143], off
	v_lshl_add_u64 v[0:1], v[146:147], 0, s[0:1]
	s_mov_b32 m0, s21
	v_mov_b32_e32 v50, v48
	global_load_lds_dwordx4 v[0:1], off
	s_add_i32 m0, s4, 0x4000
	v_lshl_add_u64 v[0:1], v[152:153], 0, s[0:1]
	global_load_lds_dwordx4 v[148:149], off
	s_add_i32 m0, s4, 0x6000
	v_mov_b32_e32 v51, v48
	global_load_lds_dwordx4 v[150:151], off
	s_add_i32 m0, s4, 0x12000
	v_mov_b32_e32 v52, v48
	global_load_lds_dwordx4 v[0:1], off
	s_add_i32 m0, s4, 0x8000
	s_waitcnt vmcnt(0)
	s_waitcnt vmcnt(0) lgkmcnt(0)
	s_barrier
; #define LAS __attribute__((address_space(3)))
; #define SBAR() __builtin_amdgcn_sched_barrier(0)
; __device__ __forceinline__ int v_rd_base(int lane) { return ((lane & 3) << 3) | (((lane >> 2) & 3) << 6) | (((lane >> 4) & 1) << 5) | (((lane >> 5) & 1) << 8); }
; #define VMW0() asm volatile("s_waitcnt vmcnt(0)" ::: "memory")
; template <int DQK, bool DOUBLE> ...
;     constexpr int RB = DQK * 2, NCH = DQK / 8, NLD = NCH / 8;
;     const int wid = __builtin_amdgcn_readfirstlane(tid >> 6), lane = tid & 63, r32 = lane & 31, hi = lane >> 5;
;     LAS char* V_lds = lds; LAS char* K_lds = lds + K_OFF;
;     bf16x8 qr[DQK / 16];
;     { const bf16_t* Qw = Q + (size_t)(wid * 32 + r32) * ldq + hi * 8;
; #pragma unroll
;       for (int d0 = 0; d0 < DQK / 16; ++d0) qr[d0] = *(const bf16x8*)(Qw + d0 * 16); }
; #pragma unroll
;     for (int d = 0; d < 4; ++d) o[d] = f32x16{};
;     l_reg = 0.f;
;     int vrow[2], vcol[2], krow[NLD], kcol[NLD];
; #pragma unroll
;     for (int i = 0; i < 2; ++i) { const int q = tid + 512 * i, sub = q >> 5, within = q & 31, kk = (sub >> 2) * 8 + (within >> 2);
;         vrow[i] = kk; vcol[i] = (sub & 3) * 32 + (within & 3) * 8; }
; #pragma unroll
;     for (int i = 0; i < NLD; ++i) { const int q = tid + 512 * i, row = q / NCH, chp = q % NCH; const int x = (RB == 256) ? (row & 15) : ((row >> 1) & 7);
;         krow[i] = row; kcol[i] = (chp ^ x) * 8; }
;     const unsigned vb0 = (unsigned)(uintptr_t)V_lds + v_rd_base(lane);
;     int ka[8];
; #pragma unroll
;     for (int q = 0; q < 8; ++q) ka[q] = kswz<RB>(r32, q * 32 + hi * 16);
;     ...
;     bf16x8 pa0, pa1, pa2, pa3;
;     __syncthreads();
;     DMA(0, 0); DMA(1, 1); VMW0(); __syncthreads();
;     if constexpr (!DOUBLE) {
;         f32x16 p0, p1;
;         DMA(2, 2);
;         int bc = 0, bn = 1, bf = 2;
;         for (int j = 0; j < NT; ++j) {
;             SBAR(); qkt<DQK>(p0, p1, K_lds + bc * K_STRIDE, qr, ka, nMB);
;             partialSM(p0, p1); finishSM(p0, p1, l_reg, pa0, pa1, pa2, pa3); SBAR();
;             pv_d0(o, vb0 + bc * V_BYTES, pa0, pa1, pa2, pa3);
;             if (j + 1 < NT) { VMW0(); __syncthreads(); if (j + 3 < NT) DMA(j + 3, bc); }
;             { const int _t = bc; bc = bn; bn = bf; bf = _t; }
;         }
	global_load_lds_dwordx4 v[154:155], off
	s_add_i32 m0, s4, 0xa000
	v_lshl_add_u64 v[0:1], v[158:159], 0, s[0:1]
	global_load_lds_dwordx4 v[156:157], off
	s_add_i32 m0, s4, 0x18000
	v_mov_b32_e32 v53, v48
	global_load_lds_dwordx4 v[0:1], off
	v_mov_b32_e32 v54, v48
	v_mov_b32_e32 v55, v48
	v_mov_b32_e32 v56, v48
	v_mov_b32_e32 v57, v48
	v_mov_b32_e32 v58, v48
	v_mov_b32_e32 v59, v48
	v_mov_b32_e32 v60, v48
	v_mov_b32_e32 v61, v48
	v_mov_b32_e32 v62, v48
	v_mov_b32_e32 v63, v48
	ds_read_b128 v[0:3], v202 offset:49152
	ds_read_b128 v[32:35], v202 offset:53248
	s_waitcnt lgkmcnt(0)
	v_mfma_f32_32x32x16_bf16 v[16:31], v[0:3], v[112:115], v[48:63]
	v_mfma_f32_32x32x16_bf16 v[0:15], v[32:35], v[112:115], v[48:63]
	ds_read_b128 v[32:35], v203 offset:49152
	ds_read_b128 v[36:39], v203 offset:53248
	s_waitcnt lgkmcnt(0)
	v_mfma_f32_32x32x16_bf16 v[16:31], v[32:35], v[116:119], v[16:31]
	v_mfma_f32_32x32x16_bf16 v[0:15], v[36:39], v[116:119], v[0:15]
	ds_read_b128 v[32:35], v204 offset:49152
	ds_read_b128 v[36:39], v204 offset:53248
	s_waitcnt lgkmcnt(0)
	v_mfma_f32_32x32x16_bf16 v[16:31], v[32:35], v[120:123], v[16:31]
	v_mfma_f32_32x32x16_bf16 v[0:15], v[36:39], v[120:123], v[0:15]
	ds_read_b128 v[32:35], v205 offset:49152
	ds_read_b128 v[36:39], v205 offset:53248
	s_waitcnt lgkmcnt(0)
	v_mfma_f32_32x32x16_bf16 v[16:31], v[32:35], v[124:127], v[16:31]
	v_mfma_f32_32x32x16_bf16 v[0:15], v[36:39], v[124:127], v[0:15]
	s_nop 10
	v_exp_f32_e32 v16, v16
	v_exp_f32_e32 v17, v17
	v_exp_f32_e32 v18, v18
	v_exp_f32_e32 v19, v19
	v_exp_f32_e32 v20, v20
	v_exp_f32_e32 v21, v21
	v_exp_f32_e32 v22, v22
	v_exp_f32_e32 v32, v0
	v_add_f32_e32 v0, 0, v16
	v_add_f32_e32 v0, v17, v0
	v_add_f32_e32 v0, v18, v0
	v_exp_f32_e32 v23, v23
	v_add_f32_e32 v0, v19, v0
	v_exp_f32_e32 v24, v24
	v_add_f32_e32 v0, v20, v0
	v_exp_f32_e32 v25, v25
	v_add_f32_e32 v0, v21, v0
	v_exp_f32_e32 v26, v26
	v_add_f32_e32 v0, v22, v0
	v_exp_f32_e32 v27, v27
	v_add_f32_e32 v0, v23, v0
	v_exp_f32_e32 v28, v28
	v_add_f32_e32 v0, v24, v0
	v_exp_f32_e32 v29, v29
	v_add_f32_e32 v0, v25, v0
	v_exp_f32_e32 v30, v30
	v_add_f32_e32 v0, v26, v0
	v_exp_f32_e32 v31, v31
	v_add_f32_e32 v0, v27, v0
	v_add_f32_e32 v0, v28, v0
	v_exp_f32_e32 v33, v1
	v_add_f32_e32 v0, v29, v0
	v_exp_f32_e32 v34, v2
	v_add_f32_e32 v0, v30, v0
	v_exp_f32_e32 v35, v3
	v_add_f32_e32 v0, v31, v0
	v_exp_f32_e32 v4, v4
	v_add_f32_e32 v0, v32, v0
	v_exp_f32_e32 v5, v5
	v_add_f32_e32 v0, v33, v0
	v_exp_f32_e32 v6, v6
	v_add_f32_e32 v0, v34, v0
	v_exp_f32_e32 v7, v7
	v_add_f32_e32 v0, v35, v0
	v_exp_f32_e32 v8, v8
	v_add_f32_e32 v0, v4, v0
	v_exp_f32_e32 v9, v9
	v_add_f32_e32 v0, v5, v0
	v_exp_f32_e32 v10, v10
	v_add_f32_e32 v0, v6, v0
	v_exp_f32_e32 v11, v11
	v_add_f32_e32 v0, v7, v0
	v_exp_f32_e32 v12, v12
	v_add_f32_e32 v0, v8, v0
	v_exp_f32_e32 v13, v13
	v_add_f32_e32 v0, v9, v0
	v_exp_f32_e32 v14, v14
	v_add_f32_e32 v0, v10, v0
	v_exp_f32_e32 v15, v15
	v_add_f32_e32 v0, v11, v0
	v_add_f32_e32 v0, v12, v0
	v_add_f32_e32 v0, v13, v0
	v_add_f32_e32 v0, v14, v0
	v_add_f32_e32 v0, v15, v0
	v_add_f32_e32 v140, 0, v0
	v_cvt_pk_bf16_f32 v0, v16, v17
	v_cvt_pk_bf16_f32 v1, v18, v19
	v_cvt_pk_bf16_f32 v2, v20, v21
	v_cvt_pk_bf16_f32 v3, v22, v23
	v_cvt_pk_bf16_f32 v80, v24, v25
	v_cvt_pk_bf16_f32 v81, v26, v27
	v_cvt_pk_bf16_f32 v82, v28, v29
	v_cvt_pk_bf16_f32 v83, v30, v31
	v_cvt_pk_bf16_f32 v84, v32, v33
	v_cvt_pk_bf16_f32 v85, v34, v35
	v_cvt_pk_bf16_f32 v86, v4, v5
	v_cvt_pk_bf16_f32 v87, v6, v7
	v_cvt_pk_bf16_f32 v88, v8, v9
	v_cvt_pk_bf16_f32 v89, v10, v11
	v_cvt_pk_bf16_f32 v90, v12, v13
	v_cvt_pk_bf16_f32 v91, v14, v15
	ds_read_b64_tr_b16 v[4:5], v200 offset:0
	ds_read_b64_tr_b16 v[6:7], v200 offset:0x800
	ds_read_b64_tr_b16 v[8:9], v200 offset:0x1000
	ds_read_b64_tr_b16 v[10:11], v200 offset:0x1800
	ds_read_b64_tr_b16 v[12:13], v200 offset:0x2000
	ds_read_b64_tr_b16 v[14:15], v200 offset:0x2800
	ds_read_b64_tr_b16 v[16:17], v200 offset:0x3000
	ds_read_b64_tr_b16 v[18:19], v200 offset:0x3800
	s_waitcnt lgkmcnt(0)
	s_nop 0
	v_mfma_f32_32x32x16_bf16 v[64:79], v[0:3], v[4:7], 0
	ds_read_b64_tr_b16 v[4:5], v200 offset:0x200
	ds_read_b64_tr_b16 v[6:7], v200 offset:0xa00
	v_mfma_f32_32x32x16_bf16 v[64:79], v[80:83], v[8:11], v[64:79]
	ds_read_b64_tr_b16 v[8:9], v200 offset:0x1200
	ds_read_b64_tr_b16 v[10:11], v200 offset:0x1a00
	v_mfma_f32_32x32x16_bf16 v[64:79], v[84:87], v[12:15], v[64:79]
	ds_read_b64_tr_b16 v[12:13], v200 offset:0x2200
	ds_read_b64_tr_b16 v[14:15], v200 offset:0x2a00
	v_mfma_f32_32x32x16_bf16 v[64:79], v[88:91], v[16:19], v[64:79]
	ds_read_b64_tr_b16 v[16:17], v200 offset:0x3200
	ds_read_b64_tr_b16 v[18:19], v200 offset:0x3a00
	s_waitcnt lgkmcnt(0)
	v_mfma_f32_32x32x16_bf16 v[32:47], v[0:3], v[4:7], 0
	ds_read_b64_tr_b16 v[4:5], v200 offset:0x400
	ds_read_b64_tr_b16 v[6:7], v200 offset:0xc00
	v_mfma_f32_32x32x16_bf16 v[32:47], v[80:83], v[8:11], v[32:47]
	ds_read_b64_tr_b16 v[8:9], v200 offset:0x1400
	ds_read_b64_tr_b16 v[10:11], v200 offset:0x1c00
	v_mfma_f32_32x32x16_bf16 v[32:47], v[84:87], v[12:15], v[32:47]
	ds_read_b64_tr_b16 v[12:13], v200 offset:0x2400
	ds_read_b64_tr_b16 v[14:15], v200 offset:0x2c00
	ds_read_b64_tr_b16 v[92:93], v200 offset:0x3400
	ds_read_b64_tr_b16 v[94:95], v200 offset:0x3c00
	s_waitcnt lgkmcnt(0)
	v_mfma_f32_32x32x16_bf16 v[32:47], v[88:91], v[16:19], v[32:47]
	v_mfma_f32_32x32x16_bf16 v[16:31], v[0:3], v[4:7], 0
	ds_read_b64_tr_b16 v[4:5], v200 offset:0x600
	ds_read_b64_tr_b16 v[6:7], v200 offset:0xe00
	v_mfma_f32_32x32x16_bf16 v[16:31], v[80:83], v[8:11], v[16:31]
	v_mfma_f32_32x32x16_bf16 v[16:31], v[84:87], v[12:15], v[16:31]
	v_mfma_f32_32x32x16_bf16 v[16:31], v[88:91], v[92:95], v[16:31]
	ds_read_b64_tr_b16 v[92:93], v200 offset:0x1600
	ds_read_b64_tr_b16 v[94:95], v200 offset:0x1e00
	ds_read_b64_tr_b16 v[96:97], v200 offset:0x2600
	ds_read_b64_tr_b16 v[98:99], v200 offset:0x2e00
	ds_read_b64_tr_b16 v[100:101], v200 offset:0x3600
	ds_read_b64_tr_b16 v[102:103], v200 offset:0x3e00
	s_waitcnt lgkmcnt(0)
	v_mfma_f32_32x32x16_bf16 v[0:15], v[0:3], v[4:7], 0
	s_mov_b32 m0, s4
	s_waitcnt vmcnt(0)
	s_waitcnt vmcnt(0)
	s_barrier
	global_load_lds_dwordx4 v[166:167], off
	s_mov_b32 m0, s20
	v_mfma_f32_32x32x16_bf16 v[0:15], v[80:83], v[92:95], v[0:15]
	global_load_lds_dwordx4 v[168:169], off
	v_lshl_add_u64 v[80:81], v[170:171], 0, s[0:1]
	s_mov_b32 m0, s21
	s_mov_b32 s21, 2
	global_load_lds_dwordx4 v[80:81], off
	v_mfma_f32_32x32x16_bf16 v[0:15], v[84:87], v[96:99], v[0:15]
	s_mov_b32 s20, 0
	s_mov_b32 s50, s44
	s_mov_b32 s35, 0
	v_mfma_f32_32x32x16_bf16 v[0:15], v[88:91], v[100:103], v[0:15]
	s_waitcnt lgkmcnt(0)
	s_mul_i32 s42, s5, 0x6000
	v_add_u32_e32 v146, s42, v145
	v_add_u32_e32 v147, s42, v161
	v_add_u32_e32 v148, s42, v198
	v_add_u32_e32 v149, s42, v199
	ds_read_b128 v[202:205], v146 offset:49152
	ds_read_b128 v[206:209], v147 offset:49152
	ds_read_b128 v[210:213], v148 offset:49152
; template <int D0> __device__ __forceinline__ void pv_one(f32x16& od, unsigned vb, bf16x8 pa0, bf16x8 pa1, bf16x8 pa2, bf16x8 pa3) {
;     const s16x4 l0 = tr_read<v_rd_off(D0, 0, 0)>(vb), h0 = tr_read<v_rd_off(D0, 0, 1)>(vb), l1 = tr_read<v_rd_off(D0, 1, 0)>(vb), h1 = tr_read<v_rd_off(D0, 1, 1)>(vb);
;     const s16x4 l2 = tr_read<v_rd_off(D0, 2, 0)>(vb), h2 = tr_read<v_rd_off(D0, 2, 1)>(vb), l3 = tr_read<v_rd_off(D0, 3, 0)>(vb), h3 = tr_read<v_rd_off(D0, 3, 1)>(vb);
;     asm volatile("s_waitcnt lgkmcnt(0)" ::: "memory"); SBAR();
;     ...
;     od = __builtin_amdgcn_mfma_f32_32x32x16_bf16(pa0, PK(l0, h0), od, 0, 0, 0);
;     od = __builtin_amdgcn_mfma_f32_32x32x16_bf16(pa1, PK(l1, h1), od, 0, 0, 0);
;     od = __builtin_amdgcn_mfma_f32_32x32x16_bf16(pa2, PK(l2, h2), od, 0, 0, 0);
;     od = __builtin_amdgcn_mfma_f32_32x32x16_bf16(pa3, PK(l3, h3), od, 0, 0, 0);
;     ...
; }
; __device__ __forceinline__ void pv_d0(f32x16 (&o)[4], unsigned vb, bf16x8 pa0, bf16x8 pa1, bf16x8 pa2, bf16x8 pa3) {
;     pv_one<0>(o[0], vb, pa0, pa1, pa2, pa3); pv_one<1>(o[1], vb, pa0, pa1, pa2, pa3); pv_one<2>(o[2], vb, pa0, pa1, pa2, pa3); pv_one<3>(o[3], vb, pa0, pa1, pa2, pa3);
; }
; __device__ __forceinline__ void partialSM(f32x16& p0, f32x16& p1) {
; #pragma unroll
;     for (int r = 0; r < 16; ++r) p0[r] = __builtin_amdgcn_exp2f(p0[r]);
; }
; __device__ __forceinline__ void finishSM(f32x16& p0, f32x16& p1, float& l_reg, bf16x8& pa0, bf16x8& pa1, bf16x8& pa2, bf16x8& pa3) {
; #pragma unroll
;     for (int r = 0; r < 16; ++r) p1[r] = __builtin_amdgcn_exp2f(p1[r]);
;     float ps = 0;
; #pragma unroll
;     for (int r = 0; r < 16; ++r) ps += p0[r];
; #pragma unroll
;     for (int r = 0; r < 16; ++r) ps += p1[r];
;     l_reg += ps;
;     ...
;     PK8(p0, 0, pa0); PK8(p0, 8, pa1); PK8(p1, 0, pa2); PK8(p1, 8, pa3);
;     ...
; }
; template <int DQK>
; __device__ __forceinline__ void qkt(f32x16& p0, f32x16& p1, const LAS char* Ks, const bf16x8 (&qr)[DQK / 16], const int (&ka)[8], float nMB) {
;     constexpr int RB = DQK * 2, NA = (RB == 256) ? 8 : 4;
; #pragma unroll
;     for (int r = 0; r < 16; ++r) { p0[r] = nMB; p1[r] = nMB; }
; #pragma unroll
;     for (int d0 = 0; d0 < DQK / 16; ++d0) {
;         const LAS char* a = Ks + ka[d0 % NA] + (d0 / NA) * (NA * 32);
;         const bf16x8 b0 = *(const LAS bf16x8*)(a);
;         const bf16x8 b1 = *(const LAS bf16x8*)(a + 32 * RB);
.LBB0_163:
	s_mov_b32 s33, s21
	s_mov_b32 s21, s35
	s_mul_i32 s35, s5, 0x6000
	s_add_i32 s35, s35, 0
	s_lshl_b32 s41, s5, 14
	v_add_u32_e32 v141, s41, v200
	s_waitcnt lgkmcnt(2)
	v_mfma_f32_32x32x16_bf16 v[96:111], v[202:205], v[112:115], v[48:63]
	ds_read_b128 v[214:217], v149 offset:49152
	s_waitcnt lgkmcnt(2)
	v_mfma_f32_32x32x16_bf16 v[96:111], v[206:209], v[116:119], v[96:111]
	ds_read_b128 v[202:205], v146 offset:53248
	s_waitcnt lgkmcnt(2)
	v_mfma_f32_32x32x16_bf16 v[96:111], v[210:213], v[120:123], v[96:111]
	ds_read_b128 v[206:209], v147 offset:53248
	s_waitcnt lgkmcnt(2)
	v_mfma_f32_32x32x16_bf16 v[96:111], v[214:217], v[124:127], v[96:111]
	ds_read_b128 v[210:213], v148 offset:53248
	s_waitcnt lgkmcnt(2)
	v_mfma_f32_32x32x16_bf16 v[80:95], v[202:205], v[112:115], v[48:63]
	ds_read_b128 v[214:217], v149 offset:53248
	s_waitcnt lgkmcnt(2)
	v_mfma_f32_32x32x16_bf16 v[80:95], v[206:209], v[116:119], v[80:95]
	ds_read_b64_tr_b16 v[202:203], v141 offset:0
	ds_read_b64_tr_b16 v[204:205], v141 offset:2048
	s_nop 3
	v_exp_f32_e32 v96, v96
	v_exp_f32_e32 v97, v97
	v_exp_f32_e32 v98, v98
	v_exp_f32_e32 v99, v99
	v_exp_f32_e32 v104, v104
	v_exp_f32_e32 v105, v105
	s_waitcnt lgkmcnt(3)
	v_mfma_f32_32x32x16_bf16 v[80:95], v[210:213], v[120:123], v[80:95]
	ds_read_b64_tr_b16 v[206:207], v141 offset:512
	ds_read_b64_tr_b16 v[208:209], v141 offset:2560
	v_exp_f32_e32 v100, v100
	v_exp_f32_e32 v101, v101
	v_exp_f32_e32 v102, v102
	v_exp_f32_e32 v103, v103
	v_exp_f32_e32 v106, v106
	v_exp_f32_e32 v107, v107
	s_waitcnt lgkmcnt(4)
	v_mfma_f32_32x32x16_bf16 v[80:95], v[214:217], v[124:127], v[80:95]
	ds_read_b64_tr_b16 v[210:211], v141 offset:1024
	ds_read_b64_tr_b16 v[212:213], v141 offset:3072
	v_cvt_pk_bf16_f32 v146, v96, v97
	v_cvt_pk_bf16_f32 v147, v98, v99
	v_cvt_pk_bf16_f32 v148, v100, v101
	v_cvt_pk_bf16_f32 v149, v102, v103
	v_exp_f32_e32 v108, v108
	v_exp_f32_e32 v109, v109
	v_add_f32_e32 v96, 0, v96
	v_add_f32_e32 v96, v97, v96
	s_waitcnt lgkmcnt(4)
	v_mfma_f32_32x32x16_bf16 v[64:79], v[146:149], v[202:205], v[64:79]
	ds_read_b64_tr_b16 v[214:215], v141 offset:1536
	ds_read_b64_tr_b16 v[216:217], v141 offset:3584
	v_exp_f32_e32 v110, v110
	v_exp_f32_e32 v111, v111
	v_add_f32_e32 v96, v98, v96
	v_add_f32_e32 v96, v99, v96
	s_waitcnt lgkmcnt(4)
	v_mfma_f32_32x32x16_bf16 v[32:47], v[146:149], v[206:209], v[32:47]
	ds_read_b64_tr_b16 v[202:203], v141 offset:4096
	ds_read_b64_tr_b16 v[204:205], v141 offset:6144
	v_cvt_pk_bf16_f32 v150, v104, v105
	v_cvt_pk_bf16_f32 v151, v106, v107
	v_exp_f32_e32 v80, v80
	v_exp_f32_e32 v81, v81
	v_exp_f32_e32 v88, v88
	v_exp_f32_e32 v89, v89
	v_add_f32_e32 v96, v100, v96
	v_add_f32_e32 v96, v101, v96
	s_waitcnt lgkmcnt(4)
	v_mfma_f32_32x32x16_bf16 v[16:31], v[146:149], v[210:213], v[16:31]
	ds_read_b64_tr_b16 v[206:207], v141 offset:4608
	ds_read_b64_tr_b16 v[208:209], v141 offset:6656
	v_cvt_pk_bf16_f32 v152, v108, v109
	v_exp_f32_e32 v82, v82
	v_exp_f32_e32 v83, v83
	v_exp_f32_e32 v90, v90
	v_add_f32_e32 v96, v102, v96
	v_add_f32_e32 v96, v103, v96
	s_waitcnt lgkmcnt(4)
	v_mfma_f32_32x32x16_bf16 v[0:15], v[146:149], v[214:217], v[0:15]
	ds_read_b64_tr_b16 v[210:211], v141 offset:5120
	ds_read_b64_tr_b16 v[212:213], v141 offset:7168
	v_cvt_pk_bf16_f32 v153, v110, v111
	v_exp_f32_e32 v84, v84
	v_exp_f32_e32 v85, v85
	v_exp_f32_e32 v91, v91
	v_add_f32_e32 v96, v104, v96
	v_add_f32_e32 v96, v105, v96
	s_waitcnt lgkmcnt(4)
	v_mfma_f32_32x32x16_bf16 v[64:79], v[150:153], v[202:205], v[64:79]
	ds_read_b64_tr_b16 v[214:215], v141 offset:5632
	ds_read_b64_tr_b16 v[216:217], v141 offset:7680
	v_exp_f32_e32 v86, v86
	v_exp_f32_e32 v87, v87
	v_exp_f32_e32 v92, v92
	v_add_f32_e32 v96, v106, v96
	v_add_f32_e32 v96, v107, v96
	s_waitcnt lgkmcnt(4)
	v_mfma_f32_32x32x16_bf16 v[32:47], v[150:153], v[206:209], v[32:47]
	ds_read_b64_tr_b16 v[202:203], v141 offset:8192
	ds_read_b64_tr_b16 v[204:205], v141 offset:10240
	v_cvt_pk_bf16_f32 v154, v80, v81
	v_cvt_pk_bf16_f32 v155, v82, v83
	v_exp_f32_e32 v93, v93
	v_add_f32_e32 v96, v108, v96
	v_add_f32_e32 v96, v109, v96
	s_waitcnt lgkmcnt(4)
	v_mfma_f32_32x32x16_bf16 v[16:31], v[150:153], v[210:213], v[16:31]
	ds_read_b64_tr_b16 v[206:207], v141 offset:8704
	ds_read_b64_tr_b16 v[208:209], v141 offset:10752
	v_cvt_pk_bf16_f32 v156, v84, v85
	v_exp_f32_e32 v94, v94
	v_add_f32_e32 v96, v110, v96
	v_add_f32_e32 v96, v111, v96
	s_waitcnt lgkmcnt(4)
	v_mfma_f32_32x32x16_bf16 v[0:15], v[150:153], v[214:217], v[0:15]
	ds_read_b64_tr_b16 v[210:211], v141 offset:9216
	ds_read_b64_tr_b16 v[212:213], v141 offset:11264
	v_cvt_pk_bf16_f32 v157, v86, v87
	v_exp_f32_e32 v95, v95
	v_add_f32_e32 v80, v80, v96
	v_add_f32_e32 v80, v81, v80
	s_waitcnt lgkmcnt(4)
	v_mfma_f32_32x32x16_bf16 v[64:79], v[154:157], v[202:205], v[64:79]
	ds_read_b64_tr_b16 v[214:215], v141 offset:9728
	ds_read_b64_tr_b16 v[216:217], v141 offset:11776
	v_cvt_pk_bf16_f32 v166, v88, v89
	v_add_f32_e32 v80, v82, v80
	v_add_f32_e32 v80, v83, v80
	v_add_f32_e32 v80, v84, v80
	s_waitcnt lgkmcnt(4)
	v_mfma_f32_32x32x16_bf16 v[32:47], v[154:157], v[206:209], v[32:47]
	ds_read_b64_tr_b16 v[202:203], v141 offset:12288
	ds_read_b64_tr_b16 v[204:205], v141 offset:14336
	v_cvt_pk_bf16_f32 v167, v90, v91
	v_add_f32_e32 v80, v85, v80
	v_add_f32_e32 v80, v86, v80
	v_add_f32_e32 v80, v87, v80
	s_waitcnt lgkmcnt(4)
	v_mfma_f32_32x32x16_bf16 v[16:31], v[154:157], v[210:213], v[16:31]
	ds_read_b64_tr_b16 v[206:207], v141 offset:12800
	ds_read_b64_tr_b16 v[208:209], v141 offset:14848
	v_cvt_pk_bf16_f32 v168, v92, v93
	s_waitcnt lgkmcnt(4)
	v_mfma_f32_32x32x16_bf16 v[0:15], v[154:157], v[214:217], v[0:15]
	ds_read_b64_tr_b16 v[210:211], v141 offset:13312
	ds_read_b64_tr_b16 v[212:213], v141 offset:15360
	v_cvt_pk_bf16_f32 v169, v94, v95
	v_add_f32_e32 v80, v88, v80
	v_add_f32_e32 v80, v89, v80
	v_add_f32_e32 v80, v90, v80
	s_waitcnt lgkmcnt(4)
	v_mfma_f32_32x32x16_bf16 v[64:79], v[166:169], v[202:205], v[64:79]
	ds_read_b64_tr_b16 v[214:215], v141 offset:13824
	ds_read_b64_tr_b16 v[216:217], v141 offset:15872
	s_mul_i32 s42, s33, 0x6000
	v_add_u32_e32 v146, s42, v145
	v_add_u32_e32 v147, s42, v161
	v_add_u32_e32 v148, s42, v198
	v_add_u32_e32 v149, s42, v199
	v_add_f32_e32 v80, v91, v80
	v_add_f32_e32 v80, v92, v80
	v_add_f32_e32 v80, v93, v80
	v_add_f32_e32 v80, v94, v80
	s_waitcnt lgkmcnt(4)
	v_mfma_f32_32x32x16_bf16 v[32:47], v[166:169], v[206:209], v[32:47]
	ds_read_b128 v[202:205], v146 offset:49152
	v_add_f32_e32 v80, v95, v80
	s_waitcnt lgkmcnt(3)
	v_mfma_f32_32x32x16_bf16 v[16:31], v[166:169], v[210:213], v[16:31]
	ds_read_b128 v[206:209], v147 offset:49152
	s_waitcnt lgkmcnt(2)
	v_mfma_f32_32x32x16_bf16 v[0:15], v[166:169], v[214:217], v[0:15]
	ds_read_b128 v[210:213], v148 offset:49152
	s_add_i32 s42, s20, 2
	s_cmp_ge_i32 s42, s71
	s_cbranch_scc1 .LBB0_166
; #define VMW0() asm volatile("s_waitcnt vmcnt(0)" ::: "memory")
; template <int DQK, bool DOUBLE> ...
;     ...
;             if (j + 1 < NT) { VMW0(); __syncthreads(); if (j + 3 < NT) DMA(j + 3, bc); }
;             { const int _t = bc; bc = bn; bn = bf; bf = _t; }
	s_waitcnt vmcnt(0)
	s_add_i32 s42, s20, 4
	s_cmp_ge_i32 s42, s71
	s_waitcnt vmcnt(0)
	s_barrier
	s_cbranch_scc1 .LBB0_166
	s_ashr_i32 s51, s50, 31
	v_lshl_add_u64 v[142:143], s[50:51], 0, v[128:129]
	s_add_i32 s41, s4, s41
	v_lshlrev_b64 v[142:143], 11, v[142:143]
	v_lshl_add_u64 v[142:143], v[138:139], 0, v[142:143]
	s_mov_b32 m0, s41
	s_add_i32 s35, s35, s3
	global_load_lds_dwordx4 v[142:143], off
	v_lshl_add_u64 v[142:143], s[50:51], 0, v[130:131]
	v_lshlrev_b64 v[142:143], 11, v[142:143]
	v_lshl_add_u64 v[142:143], v[138:139], 0, v[142:143]
	s_add_i32 m0, s41, 0x2000
	s_nop 0
	global_load_lds_dwordx4 v[142:143], off
	v_lshl_add_u64 v[142:143], s[50:51], 0, v[132:133]
	v_lshlrev_b64 v[142:143], 11, v[142:143]
	v_lshl_add_u64 v[142:143], v[134:135], 0, v[142:143]
	v_lshl_add_u64 v[142:143], v[142:143], 0, s[0:1]
	s_add_i32 m0, s35, 0xc000
	s_nop 0
	global_load_lds_dwordx4 v[142:143], off

; #define LAS __attribute__((address_space(3)))
; __device__ __forceinline__ int crow(int r, int hi) { return (r & 3) + 8 * (r >> 2) + 4 * hi; }
; __device__ __forceinline__ void row_recip(float l_reg, float (&rli)[16], LAS float* li, int r32, int hi) {
;     { auto rr = __builtin_amdgcn_permlane32_swap(__float_as_uint(l_reg), __float_as_uint(l_reg), false, false);
;       l_reg = __uint_as_float(rr[0]) + __uint_as_float(rr[1]); }
;     if (hi == 0) li[r32] = l_reg;
;     asm volatile("s_waitcnt lgkmcnt(0)" ::: "memory");
; #pragma unroll
;     for (int r = 0; r < 16; ++r) rli[r] = __builtin_amdgcn_rcpf(li[crow(r, hi)]);
;     asm volatile("s_waitcnt lgkmcnt(0)" ::: "memory");
; }
; __device__ __forceinline__ void attn_item(const AttnBufs& T, int type, int b, int h, int qrow0, int NT, LAS char* lds, int tid_) {
;     ...
;         att::row_recip(l_reg, rli, li, r32, hi);
;         const float lam = T.lamv[0];
; #pragma unroll
;         for (int d0 = 0; d0 < 4; ++d0)
; #pragma unroll
;             for (int q = 0; q < 4; ++q) { const f32x4 a = scr[d0 * 4 + q];
; #pragma unroll
;                 for (int j = 0; j < 4; ++j) o[d0][q * 4 + j] = a[j] - lam * (o[d0][q * 4 + j] * rli[q * 4 + j]); }
.LBB0_168:
	s_waitcnt lgkmcnt(0)
	s_nop 11
	v_mov_b32_e32 v48, v140
	s_nop 1
	v_permlane32_swap_b32_e32 v140, v48
	s_and_saveexec_b64 s[50:51], vcc
	v_lshl_add_u32 v49, v181, 2, s90
	v_add_f32_e32 v48, v140, v48
	ds_write_b32 v49, v48
	s_or_b64 exec, exec, s[50:51]
	s_waitcnt lgkmcnt(0)
	ds_read_b128 v[48:51], v201
	ds_read_b128 v[52:55], v201 offset:32
	s_add_i32 s2, s48, 0x800
	s_movk_i32 s4, 0x1800
	s_mov_b32 s5, 0xf000
	s_waitcnt lgkmcnt(0)
	v_rcp_f32_e32 v87, v48
	v_rcp_f32_e32 v86, v49
	v_rcp_f32_e32 v85, v50
	v_rcp_f32_e32 v84, v51
	ds_read_b128 v[48:51], v201 offset:64
	v_rcp_f32_e32 v83, v52
	v_rcp_f32_e32 v82, v53
	v_rcp_f32_e32 v81, v54
	v_rcp_f32_e32 v80, v55
	s_waitcnt lgkmcnt(0)
	v_rcp_f32_e32 v91, v48
	v_rcp_f32_e32 v90, v49
	v_rcp_f32_e32 v89, v50
	v_rcp_f32_e32 v88, v51
	ds_read_b128 v[48:51], v201 offset:96
	s_waitcnt lgkmcnt(0)
	v_mul_f32_e32 v64, v64, v87
	v_mul_f32_e32 v32, v32, v87
	v_mul_f32_e32 v16, v16, v87
	s_waitcnt lgkmcnt(0)
	v_rcp_f32_e32 v95, v48
	v_rcp_f32_e32 v94, v49
	v_rcp_f32_e32 v93, v50
	v_rcp_f32_e32 v92, v51
	global_load_dword v96, v177, s[14:15]
	global_load_dwordx4 v[60:63], v[136:137], off offset:48
	global_load_dwordx4 v[56:59], v[136:137], off offset:32
	global_load_dwordx4 v[52:55], v[136:137], off offset:16
	global_load_dwordx4 v[48:51], v[136:137], off
	v_mul_f32_e32 v0, v0, v87
	s_mov_b32 s20, 0x15000
	s_mov_b32 s21, 0x1b000
	s_mov_b32 s33, 0x27000
	v_mov_b32_e32 v161, v160
	s_mov_b64 s[48:49], 0
	s_waitcnt vmcnt(0)
	v_fma_f32 v48, -v64, v96, v48
	v_mul_f32_e32 v64, v65, v86
	v_fma_f32 v49, -v64, v96, v49
	v_mul_f32_e32 v64, v66, v85
	v_fma_f32 v50, -v64, v96, v50
	v_mul_f32_e32 v64, v67, v84
	v_fma_f32 v51, -v64, v96, v51
	v_mul_f32_e32 v64, v68, v83
	v_fma_f32 v52, -v64, v96, v52
	v_mul_f32_e32 v64, v69, v82
	v_fma_f32 v53, -v64, v96, v53
	v_mul_f32_e32 v64, v70, v81
	v_fma_f32 v54, -v64, v96, v54
	v_mul_f32_e32 v64, v71, v80
	v_fma_f32 v55, -v64, v96, v55
	v_mul_f32_e32 v64, v72, v91
	v_fma_f32 v56, -v64, v96, v56
	v_mul_f32_e32 v64, v73, v90
	v_fma_f32 v57, -v64, v96, v57
	v_mul_f32_e32 v64, v74, v89
	v_fma_f32 v58, -v64, v96, v58
	v_mul_f32_e32 v64, v75, v88
	v_fma_f32 v59, -v64, v96, v59
	v_mul_f32_e32 v64, v76, v95
	v_fma_f32 v60, -v64, v96, v60
	v_mul_f32_e32 v64, v77, v94
	v_fma_f32 v61, -v64, v96, v61
	v_mul_f32_e32 v64, v78, v93
	v_fma_f32 v62, -v64, v96, v62
	v_mul_f32_e32 v64, v79, v92
	v_fma_f32 v63, -v96, v64, v63
	global_load_dwordx4 v[70:73], v[136:137], off offset:112
	global_load_dwordx4 v[74:77], v[136:137], off offset:96
	global_load_dwordx4 v[98:101], v[136:137], off offset:80
	global_load_dwordx4 v[64:67], v[136:137], off offset:64
	s_waitcnt vmcnt(0)
	v_fma_f32 v64, -v32, v96, v64
	v_mul_f32_e32 v32, v33, v86
	v_fma_f32 v65, -v32, v96, v65
	v_mul_f32_e32 v32, v34, v85
	v_fma_f32 v66, -v32, v96, v66
	v_mul_f32_e32 v32, v35, v84
	v_fma_f32 v67, -v32, v96, v67
	v_mul_f32_e32 v32, v36, v83
	v_fma_f32 v68, -v32, v96, v98
	v_mul_f32_e32 v32, v37, v82
	v_fma_f32 v69, -v32, v96, v99
	v_mul_f32_e32 v32, v38, v81
	v_fma_f32 v38, -v32, v96, v100
	v_mul_f32_e32 v32, v39, v80
	v_fma_f32 v39, -v32, v96, v101
	v_mul_f32_e32 v32, v40, v91
	v_fma_f32 v40, -v32, v96, v74
	v_mul_f32_e32 v32, v41, v90
	v_fma_f32 v41, -v32, v96, v75
	v_mul_f32_e32 v32, v42, v89
	v_fma_f32 v42, -v32, v96, v76
	v_mul_f32_e32 v32, v43, v88
	v_fma_f32 v43, -v32, v96, v77
	v_mul_f32_e32 v32, v44, v95
	v_fma_f32 v44, -v32, v96, v70
	v_mul_f32_e32 v32, v45, v94
	v_fma_f32 v45, -v32, v96, v71
	v_mul_f32_e32 v32, v46, v93
	v_fma_f32 v46, -v32, v96, v72
	v_mul_f32_e32 v32, v47, v92
	v_fma_f32 v47, -v96, v32, v73
	global_load_dwordx4 v[32:35], v[136:137], off offset:176
	global_load_dwordx4 v[98:101], v[136:137], off offset:160
	global_load_dwordx4 v[74:77], v[136:137], off offset:144
	global_load_dwordx4 v[70:73], v[136:137], off offset:128
	s_waitcnt vmcnt(0)
	v_fma_f32 v70, -v16, v96, v70
	v_mul_f32_e32 v16, v17, v86
	v_fma_f32 v71, -v16, v96, v71
	v_mul_f32_e32 v16, v18, v85
	v_fma_f32 v72, -v16, v96, v72
	v_mul_f32_e32 v16, v19, v84
	v_fma_f32 v73, -v16, v96, v73
	v_mul_f32_e32 v16, v20, v83
	v_fma_f32 v74, -v16, v96, v74
	v_mul_f32_e32 v16, v21, v82
	v_fma_f32 v75, -v16, v96, v75
	v_mul_f32_e32 v16, v22, v81
	v_fma_f32 v76, -v16, v96, v76
	v_mul_f32_e32 v16, v23, v80
	v_fma_f32 v77, -v16, v96, v77
	v_mul_f32_e32 v16, v24, v91
	v_fma_f32 v78, -v16, v96, v98
	v_mul_f32_e32 v16, v25, v90
	v_fma_f32 v79, -v16, v96, v99
	v_mul_f32_e32 v16, v26, v89
	v_fma_f32 v97, -v16, v96, v100
	v_mul_f32_e32 v16, v27, v88
	v_fma_f32 v98, -v16, v96, v101
	v_mul_f32_e32 v16, v28, v95
	v_fma_f32 v99, -v16, v96, v32
	v_mul_f32_e32 v16, v29, v94
	v_fma_f32 v100, -v16, v96, v33
	v_mul_f32_e32 v16, v30, v93
	v_fma_f32 v101, -v16, v96, v34
	v_mul_f32_e32 v16, v31, v92
	v_fma_f32 v102, -v96, v16, v35
	global_load_dwordx4 v[16:19], v[136:137], off offset:240
	global_load_dwordx4 v[20:23], v[136:137], off offset:224
	global_load_dwordx4 v[24:27], v[136:137], off offset:208
	global_load_dwordx4 v[28:31], v[136:137], off offset:192
	s_waitcnt vmcnt(0)
; #define LAS __attribute__((address_space(3)))
; __device__ __forceinline__ int crow(int r, int hi) { return (r & 3) + 8 * (r >> 2) + 4 * hi; }
; template <bool SUBLN>
; __device__ __forceinline__ void attn_out(const AttnBufs& T, f32x16 (&o)[4], int type, int h, size_t orow0, LAS char* lds, int wid, int lane, int r32, int hi) {
;     const int rr = lane >> 5, c4 = (lane & 31) * 4;
;     const int col = type * 1024 + h * 128 + c4;
;     const bf16_t* gp = T.GATE + (orow0 + rr) * 3072 + col; bf16_t* op = T.BR + (orow0 + rr) * 3072 + col;
;     u32x2 gg[16];
; #pragma unroll
;     for (int i = 0; i < 16; ++i) gg[i] = *(const u32x2*)(gp + (size_t)i * 2 * 3072);
;     __syncthreads();
;     LAS float* stg = (LAS float*)(lds + wid * 16896);
; #pragma unroll
;     for (int d0 = 0; d0 < 4; ++d0)
; #pragma unroll
;         for (int r = 0; r < 16; ++r) stg[att::crow(r, hi) * 132 + d0 * 32 + r32] = o[d0][r];
;     asm volatile("s_waitcnt lgkmcnt(0)" ::: "memory");
; __device__ __forceinline__ void attn_item(const AttnBufs& T, int type, int b, int h, int qrow0, int NT, LAS char* lds, int tid_) {
;     ...
;             for (int q = 0; q < 4; ++q) { const f32x4 a = scr[d0 * 4 + q];
; #pragma unroll
;                 for (int j = 0; j < 4; ++j) o[d0][q * 4 + j] = a[j] - lam * (o[d0][q * 4 + j] * rli[q * 4 + j]); }
	v_fma_f32 v87, -v0, v96, v28
	v_mul_f32_e32 v0, v1, v86
	v_fma_f32 v86, -v0, v96, v29
	v_mul_f32_e32 v0, v2, v85
	v_fma_f32 v85, -v0, v96, v30
	v_mul_f32_e32 v0, v3, v84
	v_fma_f32 v84, -v0, v96, v31
	v_mul_f32_e32 v0, v4, v83
	v_fma_f32 v83, -v0, v96, v24
	v_mul_f32_e32 v0, v5, v82
	v_fma_f32 v82, -v0, v96, v25
	v_mul_f32_e32 v0, v6, v81
	v_fma_f32 v81, -v0, v96, v26
	v_mul_f32_e32 v0, v7, v80
	v_fma_f32 v80, -v0, v96, v27
	v_mul_f32_e32 v0, v8, v91
	v_fma_f32 v91, -v0, v96, v20
	v_mul_f32_e32 v0, v9, v90
	v_fma_f32 v90, -v0, v96, v21
	v_mul_f32_e32 v0, v10, v89
	v_fma_f32 v89, -v0, v96, v22
	v_mul_f32_e32 v0, v11, v88
	v_fma_f32 v88, -v0, v96, v23
	v_mul_f32_e32 v0, v12, v95
	v_fma_f32 v95, -v0, v96, v16
	v_mul_f32_e32 v0, v13, v94
	v_fma_f32 v94, -v0, v96, v17
	v_mul_f32_e32 v0, v14, v93
	v_fma_f32 v93, -v0, v96, v18
	v_mul_f32_e32 v0, v15, v92
	v_fma_f32 v92, -v96, v0, v19
	v_lshlrev_b32_e32 v0, 2, v182
	v_and_b32_e32 v96, 0x7c, v0
	v_or_b32_e32 v0, s2, v96
	v_readlane_b32 s2, v251, 46
	v_readlane_b32 s3, v251, 47
	v_lshl_add_u64 v[2:3], s[36:37], 0, v[176:177]
	v_ashrrev_i32_e32 v1, 31, v0
	v_mov_b64_e32 v[4:5], s[2:3]
	v_mad_u64_u32 v[4:5], s[2:3], v2, s4, v[4:5]
	v_readlane_b32 s2, v251, 48
	v_mad_i32_i24 v5, v3, s4, v5
	v_lshlrev_b64 v[0:1], 1, v[0:1]
	v_readlane_b32 s3, v251, 49
	v_lshl_add_u64 v[6:7], v[4:5], 0, v[0:1]
	global_load_dwordx2 v[36:37], v[6:7], off
	v_mov_b64_e32 v[4:5], s[2:3]
	v_mad_u64_u32 v[8:9], s[2:3], v2, s4, v[4:5]
	v_add_co_u32_e32 v2, vcc, s40, v6
	v_mad_i32_i24 v9, v3, s4, v9
	s_nop 0
	v_addc_co_u32_e32 v3, vcc, 0, v7, vcc
	global_load_dwordx2 v[34:35], v[2:3], off
	v_add_co_u32_e32 v2, vcc, s82, v6
	s_mov_b32 s4, 0x9000
	s_nop 0
	v_addc_co_u32_e32 v3, vcc, 0, v7, vcc
	global_load_dwordx2 v[32:33], v[2:3], off
	v_add_co_u32_e32 v2, vcc, s4, v6
	s_mov_b32 s3, 0x21000
	s_nop 0
	v_addc_co_u32_e32 v3, vcc, 0, v7, vcc
	global_load_dwordx2 v[30:31], v[2:3], off
	v_add_co_u32_e32 v2, vcc, s77, v6
	s_mov_b32 s2, 0x2d000
	s_nop 0
	v_addc_co_u32_e32 v3, vcc, 0, v7, vcc
	global_load_dwordx2 v[28:29], v[2:3], off
	v_add_co_u32_e32 v2, vcc, s5, v6
	v_lshl_add_u64 v[0:1], v[8:9], 0, v[0:1]
	s_nop 0
	v_addc_co_u32_e32 v3, vcc, 0, v7, vcc
	global_load_dwordx2 v[26:27], v[2:3], off
	v_add_co_u32_e32 v2, vcc, s85, v6
	s_nop 1
	v_addc_co_u32_e32 v3, vcc, 0, v7, vcc
	global_load_dwordx2 v[24:25], v[2:3], off
	v_add_co_u32_e32 v2, vcc, s20, v6
	s_nop 1
	v_addc_co_u32_e32 v3, vcc, 0, v7, vcc
	global_load_dwordx2 v[22:23], v[2:3], off
	v_add_co_u32_e32 v2, vcc, s76, v6
	s_nop 1
	v_addc_co_u32_e32 v3, vcc, 0, v7, vcc
	global_load_dwordx2 v[20:21], v[2:3], off
	v_add_co_u32_e32 v2, vcc, s21, v6
	s_nop 1
	v_addc_co_u32_e32 v3, vcc, 0, v7, vcc
	global_load_dwordx2 v[18:19], v[2:3], off
	v_add_co_u32_e32 v2, vcc, s92, v6
	s_nop 1
	v_addc_co_u32_e32 v3, vcc, 0, v7, vcc
	global_load_dwordx2 v[16:17], v[2:3], off
	v_add_co_u32_e32 v2, vcc, s3, v6
	s_nop 1
	v_addc_co_u32_e32 v3, vcc, 0, v7, vcc
	global_load_dwordx2 v[14:15], v[2:3], off
	v_add_co_u32_e32 v2, vcc, s91, v6
	s_nop 1
	v_addc_co_u32_e32 v3, vcc, 0, v7, vcc
	global_load_dwordx2 v[12:13], v[2:3], off
	v_add_co_u32_e32 v2, vcc, s33, v6
	s_nop 1
	v_addc_co_u32_e32 v3, vcc, 0, v7, vcc
	global_load_dwordx2 v[10:11], v[2:3], off
	v_add_co_u32_e32 v2, vcc, s94, v6
	s_nop 1
	v_addc_co_u32_e32 v3, vcc, 0, v7, vcc
	global_load_dwordx2 v[4:5], v[2:3], off
	v_add_co_u32_e32 v2, vcc, s2, v6
	s_add_i32 s2, s73, 0
	s_nop 0
	v_addc_co_u32_e32 v3, vcc, 0, v7, vcc
	v_lshlrev_b32_e32 v6, 2, v181
	v_mul_u32_u24_e32 v7, 0x840, v176
	v_add3_u32 v6, s2, v6, v7
	global_load_dwordx2 v[2:3], v[2:3], off
	s_barrier
	ds_write2_b32 v6, v48, v64 offset1:32
	ds_write2_b32 v6, v49, v65 offset0:132 offset1:164
	v_add_u32_e32 v7, 0x400, v6
	v_add_u32_e32 v48, 0x1000, v6
	v_add_u32_e32 v49, 0x1400, v6
	ds_write2_b32 v7, v50, v66 offset0:8 offset1:40
	ds_write2_b32 v7, v51, v67 offset0:140 offset1:172
	ds_write2_b32 v48, v52, v68 offset0:32 offset1:64
	ds_write2_b32 v48, v53, v69 offset0:164 offset1:196
	ds_write2_b32 v49, v54, v38 offset0:40 offset1:72
	ds_write2_b32 v49, v55, v39 offset0:172 offset1:204
	v_add_u32_e32 v38, 0x2000, v6
	ds_write2_b32 v38, v56, v40 offset0:64 offset1:96
	ds_write2_b32 v38, v57, v41 offset0:196 offset1:228
	v_add_u32_e32 v39, 0x2400, v6
	v_add_u32_e32 v41, 0x3200, v6
	ds_write2_b32 v39, v58, v42 offset0:72 offset1:104
	ds_write2_b32 v39, v59, v43 offset0:204 offset1:236
	v_add_u32_e32 v40, 0x3000, v6
	ds_write2_b32 v41, v61, v45 offset0:100 offset1:132
	v_add_u32_e32 v41, 0x3400, v6
	v_add_u32_e32 v42, 0x3600, v6
	ds_write2_b32 v40, v60, v44 offset0:96 offset1:128
	ds_write2_b32 v41, v62, v46 offset0:104 offset1:136
	ds_write2_b32 v42, v63, v47 offset0:108 offset1:140
	ds_write2_b32 v6, v70, v87 offset0:64 offset1:96
	ds_write2_b32 v6, v71, v86 offset0:196 offset1:228
	ds_write2_b32 v7, v72, v85 offset0:72 offset1:104
	ds_write2_b32 v7, v73, v84 offset0:204 offset1:236
	ds_write2_b32 v48, v74, v83 offset0:96 offset1:128
	v_add_u32_e32 v7, 0x1200, v6
	ds_write2_b32 v7, v75, v82 offset0:100 offset1:132
	ds_write2_b32 v49, v76, v81 offset0:104 offset1:136
	v_add_u32_e32 v7, 0x1600, v6
	ds_write2_b32 v7, v77, v80 offset0:108 offset1:140
	ds_write2_b32 v38, v78, v91 offset0:128 offset1:160
	ds_write2_b32 v39, v79, v90 offset0:4 offset1:36
	ds_write2_b32 v39, v97, v89 offset0:136 offset1:168
	v_add_u32_e32 v7, 0x2800, v6
	v_add_u32_e32 v6, 0x3800, v6
	ds_write2_b32 v7, v98, v88 offset0:12 offset1:44
	ds_write2_b32 v40, v99, v95 offset0:160 offset1:192
	ds_write2_b32 v41, v100, v94 offset0:36 offset1:68
	ds_write2_b32 v41, v101, v93 offset0:168 offset1:200
	ds_write2_b32 v6, v102, v92 offset0:44 offset1:76
	s_waitcnt lgkmcnt(0)
; #define LAS __attribute__((address_space(3)))
; __device__ __forceinline__ float bf2f(unsigned h) { return __uint_as_float(h << 16); }
; __device__ __forceinline__ unsigned cvt_pk_bf16(float lo, float hi) { unsigned r; asm volatile("v_cvt_pk_bf16_f32 %0, %1, %2" : "=v"(r) : "v"(lo), "v"(hi)); return r; }
; template <bool SUBLN>
; __device__ __forceinline__ void attn_out(const AttnBufs& T, f32x16 (&o)[4], int type, int h, size_t orow0, LAS char* lds, int wid, int lane, int r32, int hi) {
;     ...
;     f32x4 wsub = {1.f, 1.f, 1.f, 1.f};
;     if (SUBLN) { wsub = *(const f32x4*)(T.subln + c4) * (1.f - T.lam_init); }
; #pragma unroll
;     for (int i = 0; i < 16; ++i) {
;         f32x4 v = *(const LAS f32x4*)(stg + (2 * i + rr) * 132 + c4);
;         if (SUBLN) {
;             float s = (v[0] * v[0] + v[1] * v[1]) + (v[2] * v[2] + v[3] * v[3]);
;             s += __shfl_xor(s, 1); s += __shfl_xor(s, 2); s += __shfl_xor(s, 4); s += __shfl_xor(s, 8); s += __shfl_xor(s, 16);
;             v = v * (rsqrtf(s * (1.f / 128.f) + EPS)) * wsub;
;         }
;         u32x2 w; w.x = cvt_pk_bf16(v[0] * bf2f(gg[i].x & 0xffffu), v[1] * bf2f(gg[i].x >> 16)); w.y = cvt_pk_bf16(v[2] * bf2f(gg[i].y & 0xffffu), v[3] * bf2f(gg[i].y >> 16));
;         *(u32x2*)(op + (size_t)i * 2 * 3072) = w;
;     }
	v_lshlrev_b32_e32 v43, 2, v96
	global_load_dwordx4 v[38:41], v43, s[26:27]
	v_xor_b32_e32 v44, 16, v228
	s_waitcnt vmcnt(0)
	v_pk_mul_f32 v[8:9], v[162:163], v[38:39]
	v_and_b32_e32 v39, 64, v228
	v_xor_b32_e32 v38, 1, v228
	v_add_u32_e32 v42, 64, v39
	v_cmp_lt_i32_e32 vcc, v38, v42
	v_xor_b32_e32 v39, 2, v228
	v_pk_mul_f32 v[6:7], v[160:161], v[40:41]
	v_cndmask_b32_e32 v38, v228, v38, vcc
	v_cmp_lt_i32_e32 vcc, v39, v42
	v_xor_b32_e32 v40, 4, v228
	v_xor_b32_e32 v41, 8, v228
	v_cndmask_b32_e32 v39, v228, v39, vcc
	v_cmp_lt_i32_e32 vcc, v40, v42
	v_lshlrev_b32_e32 v38, 2, v38
	v_lshlrev_b32_e32 v39, 2, v39
	v_cndmask_b32_e32 v40, v228, v40, vcc
	v_cmp_lt_i32_e32 vcc, v41, v42
	v_lshlrev_b32_e32 v40, 2, v40
	s_nop 0
	v_cndmask_b32_e32 v41, v228, v41, vcc
	v_cmp_lt_i32_e32 vcc, v44, v42
	v_lshlrev_b32_e32 v41, 2, v41
	s_nop 0
	v_cndmask_b32_e32 v42, v228, v44, vcc
	v_mul_u32_u24_e32 v44, 0x210, v176
	v_add3_u32 v43, s2, v43, v44
	ds_read_b128 v[44:47], v43
	v_lshlrev_b32_e32 v42, 2, v42
	s_mov_b32 s2, 0x800000
	s_waitcnt lgkmcnt(0)
	v_pk_mul_f32 v[48:49], v[46:47], v[46:47]
	v_pk_mul_f32 v[50:51], v[44:45], v[44:45]
	s_nop 0
	v_pk_mov_b32 v[52:53], v[50:51], v[48:49] op_sel:[1,0]
	v_mov_b32_e32 v51, v49
	v_pk_add_f32 v[48:49], v[52:53], v[50:51]
	s_nop 0
	v_add_f32_e32 v48, v48, v49
	ds_bpermute_b32 v49, v38, v48
	s_waitcnt lgkmcnt(0)
	v_add_f32_e32 v48, v48, v49
	ds_bpermute_b32 v49, v39, v48
	s_waitcnt lgkmcnt(0)
	v_add_f32_e32 v48, v48, v49
	ds_bpermute_b32 v49, v40, v48
	s_waitcnt lgkmcnt(0)
	v_add_f32_e32 v48, v48, v49
	ds_bpermute_b32 v49, v41, v48
	s_waitcnt lgkmcnt(0)
	v_add_f32_e32 v48, v48, v49
	ds_bpermute_b32 v49, v42, v48
	s_waitcnt lgkmcnt(0)
	v_add_f32_e32 v48, v48, v49
	v_fmamk_f32 v48, v48, 0x3c000000, v178
	v_cmp_gt_f32_e32 vcc, s2, v48
	v_mul_f32_e32 v49, 0x4b800000, v48
	s_nop 0
	v_cndmask_b32_e32 v48, v48, v49, vcc
	v_rsq_f32_e32 v48, v48
	s_nop 0
	v_mul_f32_e32 v49, 0x45800000, v48
	v_cndmask_b32_e32 v48, v48, v49, vcc
	v_pk_mul_f32 v[44:45], v[44:45], v[48:49] op_sel_hi:[1,0]
	v_pk_mul_f32 v[46:47], v[46:47], v[48:49] op_sel_hi:[1,0]
	v_pk_mul_f32 v[44:45], v[8:9], v[44:45]
	v_lshlrev_b32_e32 v48, 16, v36
	v_and_b32_e32 v36, 0xffff0000, v36
	v_mul_f32_e32 v44, v44, v48
	v_mul_f32_e32 v36, v45, v36
	v_pk_mul_f32 v[46:47], v[6:7], v[46:47]
	v_cvt_pk_bf16_f32 v36, v44, v36
	v_lshlrev_b32_e32 v44, 16, v37
	v_and_b32_e32 v37, 0xffff0000, v37
	v_mul_f32_e32 v44, v46, v44
	v_mul_f32_e32 v37, v47, v37
	v_cvt_pk_bf16_f32 v37, v44, v37
	ds_read_b128 v[44:47], v43 offset:1056
	global_store_dwordx2 v[0:1], v[36:37], off
	s_waitcnt lgkmcnt(0)
	v_pk_mul_f32 v[36:37], v[46:47], v[46:47]
	v_pk_mul_f32 v[48:49], v[44:45], v[44:45]
	s_nop 0
	v_pk_mov_b32 v[50:51], v[48:49], v[36:37] op_sel:[1,0]
	v_mov_b32_e32 v49, v37
	v_pk_add_f32 v[36:37], v[50:51], v[48:49]
	s_nop 0
	v_add_f32_e32 v36, v36, v37
	ds_bpermute_b32 v37, v38, v36
	s_waitcnt lgkmcnt(0)
	v_add_f32_e32 v36, v36, v37
	ds_bpermute_b32 v37, v39, v36
	s_waitcnt lgkmcnt(0)
	v_add_f32_e32 v36, v36, v37
	ds_bpermute_b32 v37, v40, v36
	s_waitcnt lgkmcnt(0)
	v_add_f32_e32 v36, v36, v37
	ds_bpermute_b32 v37, v41, v36
	s_waitcnt lgkmcnt(0)
	v_add_f32_e32 v36, v36, v37
	ds_bpermute_b32 v37, v42, v36
	s_waitcnt lgkmcnt(0)
	v_add_f32_e32 v36, v36, v37
	v_fmamk_f32 v36, v36, 0x3c000000, v178
	v_cmp_gt_f32_e32 vcc, s2, v36
	v_mul_f32_e32 v37, 0x4b800000, v36
	s_nop 0
	v_cndmask_b32_e32 v36, v36, v37, vcc
	v_rsq_f32_e32 v36, v36
	s_nop 0
	v_mul_f32_e32 v37, 0x45800000, v36
	v_cndmask_b32_e32 v36, v36, v37, vcc
	v_pk_mul_f32 v[44:45], v[44:45], v[36:37] op_sel_hi:[1,0]
	v_pk_mul_f32 v[36:37], v[46:47], v[36:37] op_sel_hi:[1,0]
	v_pk_mul_f32 v[44:45], v[8:9], v[44:45]
	v_lshlrev_b32_e32 v46, 16, v34
	v_and_b32_e32 v34, 0xffff0000, v34
	v_mul_f32_e32 v44, v44, v46
	v_mul_f32_e32 v34, v45, v34
	v_pk_mul_f32 v[36:37], v[6:7], v[36:37]
	v_cvt_pk_bf16_f32 v34, v44, v34
	v_lshlrev_b32_e32 v44, 16, v35
	v_and_b32_e32 v35, 0xffff0000, v35
	v_mul_f32_e32 v36, v36, v44
	v_mul_f32_e32 v35, v37, v35
	v_cvt_pk_bf16_f32 v35, v36, v35
	v_add_co_u32_e32 v36, vcc, s40, v0
	s_nop 1
	v_addc_co_u32_e32 v37, vcc, 0, v1, vcc
	global_store_dwordx2 v[36:37], v[34:35], off
	ds_read_b128 v[34:37], v43 offset:2112
	s_waitcnt lgkmcnt(0)
	v_pk_mul_f32 v[44:45], v[36:37], v[36:37]
	v_pk_mul_f32 v[46:47], v[34:35], v[34:35]
	s_nop 0
	v_pk_mov_b32 v[48:49], v[46:47], v[44:45] op_sel:[1,0]
	v_mov_b32_e32 v47, v45
	v_pk_add_f32 v[44:45], v[48:49], v[46:47]
	s_nop 0
	v_add_f32_e32 v44, v44, v45
	ds_bpermute_b32 v45, v38, v44
	s_waitcnt lgkmcnt(0)
	v_add_f32_e32 v44, v44, v45
	ds_bpermute_b32 v45, v39, v44
	s_waitcnt lgkmcnt(0)
	v_add_f32_e32 v44, v44, v45
	ds_bpermute_b32 v45, v40, v44
	s_waitcnt lgkmcnt(0)
	v_add_f32_e32 v44, v44, v45
	ds_bpermute_b32 v45, v41, v44
	s_waitcnt lgkmcnt(0)
	v_add_f32_e32 v44, v44, v45
	ds_bpermute_b32 v45, v42, v44
	s_waitcnt lgkmcnt(0)
	v_add_f32_e32 v44, v44, v45
	v_fmamk_f32 v44, v44, 0x3c000000, v178
	v_cmp_gt_f32_e32 vcc, s2, v44
	v_mul_f32_e32 v45, 0x4b800000, v44
	s_nop 0
	v_cndmask_b32_e32 v44, v44, v45, vcc
	v_rsq_f32_e32 v44, v44
	s_nop 0
	v_mul_f32_e32 v45, 0x45800000, v44
	v_cndmask_b32_e32 v44, v44, v45, vcc
	v_pk_mul_f32 v[34:35], v[34:35], v[44:45] op_sel_hi:[1,0]
	v_pk_mul_f32 v[36:37], v[36:37], v[44:45] op_sel_hi:[1,0]
	v_pk_mul_f32 v[34:35], v[8:9], v[34:35]
	v_lshlrev_b32_e32 v44, 16, v32
	v_and_b32_e32 v32, 0xffff0000, v32
	v_mul_f32_e32 v34, v34, v44
	v_mul_f32_e32 v32, v35, v32
	v_pk_mul_f32 v[36:37], v[6:7], v[36:37]
	v_cvt_pk_bf16_f32 v32, v34, v32
	v_lshlrev_b32_e32 v34, 16, v33
	v_and_b32_e32 v33, 0xffff0000, v33
	v_mul_f32_e32 v34, v36, v34
	v_mul_f32_e32 v33, v37, v33
	v_cvt_pk_bf16_f32 v33, v34, v33
	v_add_co_u32_e32 v34, vcc, s82, v0
	s_nop 1
	v_addc_co_u32_e32 v35, vcc, 0, v1, vcc
	global_store_dwordx2 v[34:35], v[32:33], off
	ds_read_b128 v[32:35], v43 offset:3168
	s_waitcnt lgkmcnt(0)
; #define LAS __attribute__((address_space(3)))
; __device__ __forceinline__ float bf2f(unsigned h) { return __uint_as_float(h << 16); }
; __device__ __forceinline__ unsigned cvt_pk_bf16(float lo, float hi) { unsigned r; asm volatile("v_cvt_pk_bf16_f32 %0, %1, %2" : "=v"(r) : "v"(lo), "v"(hi)); return r; }
; template <bool SUBLN>
; __device__ __forceinline__ void attn_out(const AttnBufs& T, f32x16 (&o)[4], int type, int h, size_t orow0, LAS char* lds, int wid, int lane, int r32, int hi) {
;     ...
;     f32x4 wsub = {1.f, 1.f, 1.f, 1.f};
;     if (SUBLN) { wsub = *(const f32x4*)(T.subln + c4) * (1.f - T.lam_init); }
; #pragma unroll
;     for (int i = 0; i < 16; ++i) {
;         f32x4 v = *(const LAS f32x4*)(stg + (2 * i + rr) * 132 + c4);
;         if (SUBLN) {
;             float s = (v[0] * v[0] + v[1] * v[1]) + (v[2] * v[2] + v[3] * v[3]);
;             s += __shfl_xor(s, 1); s += __shfl_xor(s, 2); s += __shfl_xor(s, 4); s += __shfl_xor(s, 8); s += __shfl_xor(s, 16);
;             v = v * (rsqrtf(s * (1.f / 128.f) + EPS)) * wsub;
;         }
;         u32x2 w; w.x = cvt_pk_bf16(v[0] * bf2f(gg[i].x & 0xffffu), v[1] * bf2f(gg[i].x >> 16)); w.y = cvt_pk_bf16(v[2] * bf2f(gg[i].y & 0xffffu), v[3] * bf2f(gg[i].y >> 16));
;         *(u32x2*)(op + (size_t)i * 2 * 3072) = w;
;     }
	v_pk_mul_f32 v[36:37], v[34:35], v[34:35]
	v_pk_mul_f32 v[44:45], v[32:33], v[32:33]
	s_nop 0
	v_pk_mov_b32 v[46:47], v[44:45], v[36:37] op_sel:[1,0]
	v_mov_b32_e32 v45, v37
	v_pk_add_f32 v[36:37], v[46:47], v[44:45]
	s_nop 0
	v_add_f32_e32 v36, v36, v37
	ds_bpermute_b32 v37, v38, v36
	s_waitcnt lgkmcnt(0)
	v_add_f32_e32 v36, v36, v37
	ds_bpermute_b32 v37, v39, v36
	s_waitcnt lgkmcnt(0)
	v_add_f32_e32 v36, v36, v37
	ds_bpermute_b32 v37, v40, v36
	s_waitcnt lgkmcnt(0)
	v_add_f32_e32 v36, v36, v37
	ds_bpermute_b32 v37, v41, v36
	s_waitcnt lgkmcnt(0)
	v_add_f32_e32 v36, v36, v37
	ds_bpermute_b32 v37, v42, v36
	s_waitcnt lgkmcnt(0)
	v_add_f32_e32 v36, v36, v37
	v_fmamk_f32 v36, v36, 0x3c000000, v178
	v_cmp_gt_f32_e32 vcc, s2, v36
	v_mul_f32_e32 v37, 0x4b800000, v36
	s_nop 0
	v_cndmask_b32_e32 v36, v36, v37, vcc
	v_rsq_f32_e32 v36, v36
	s_nop 0
	v_mul_f32_e32 v37, 0x45800000, v36
	v_cndmask_b32_e32 v36, v36, v37, vcc
	v_pk_mul_f32 v[32:33], v[32:33], v[36:37] op_sel_hi:[1,0]
	v_pk_mul_f32 v[34:35], v[34:35], v[36:37] op_sel_hi:[1,0]
	v_pk_mul_f32 v[32:33], v[8:9], v[32:33]
	v_lshlrev_b32_e32 v36, 16, v30
	v_and_b32_e32 v30, 0xffff0000, v30
	v_mul_f32_e32 v32, v32, v36
	v_mul_f32_e32 v30, v33, v30
	v_pk_mul_f32 v[34:35], v[6:7], v[34:35]
	v_cvt_pk_bf16_f32 v30, v32, v30
	v_lshlrev_b32_e32 v32, 16, v31
	v_and_b32_e32 v31, 0xffff0000, v31
	v_mul_f32_e32 v32, v34, v32
	v_mul_f32_e32 v31, v35, v31
	v_cvt_pk_bf16_f32 v31, v32, v31
	v_add_co_u32_e32 v32, vcc, s4, v0
	s_nop 1
	v_addc_co_u32_e32 v33, vcc, 0, v1, vcc
	global_store_dwordx2 v[32:33], v[30:31], off
	ds_read_b128 v[30:33], v43 offset:4224
	s_waitcnt lgkmcnt(0)
	v_pk_mul_f32 v[34:35], v[32:33], v[32:33]
	v_pk_mul_f32 v[36:37], v[30:31], v[30:31]
	s_nop 0
	v_pk_mov_b32 v[44:45], v[36:37], v[34:35] op_sel:[1,0]
	v_mov_b32_e32 v37, v35
	v_pk_add_f32 v[34:35], v[44:45], v[36:37]
	s_nop 0
	v_add_f32_e32 v34, v34, v35
	ds_bpermute_b32 v35, v38, v34
	s_waitcnt lgkmcnt(0)
	v_add_f32_e32 v34, v34, v35
	ds_bpermute_b32 v35, v39, v34
	s_waitcnt lgkmcnt(0)
	v_add_f32_e32 v34, v34, v35
	ds_bpermute_b32 v35, v40, v34
	s_waitcnt lgkmcnt(0)
	v_add_f32_e32 v34, v34, v35
	ds_bpermute_b32 v35, v41, v34
	s_waitcnt lgkmcnt(0)
	v_add_f32_e32 v34, v34, v35
	ds_bpermute_b32 v35, v42, v34
	s_waitcnt lgkmcnt(0)
	v_add_f32_e32 v34, v34, v35
	v_fmamk_f32 v34, v34, 0x3c000000, v178
	v_cmp_gt_f32_e32 vcc, s2, v34
	v_mul_f32_e32 v35, 0x4b800000, v34
	s_nop 0
	v_cndmask_b32_e32 v34, v34, v35, vcc
	v_rsq_f32_e32 v34, v34
	s_nop 0
	v_mul_f32_e32 v35, 0x45800000, v34
	v_cndmask_b32_e32 v34, v34, v35, vcc
	v_pk_mul_f32 v[30:31], v[30:31], v[34:35] op_sel_hi:[1,0]
	v_pk_mul_f32 v[32:33], v[32:33], v[34:35] op_sel_hi:[1,0]
	v_pk_mul_f32 v[30:31], v[8:9], v[30:31]
	v_lshlrev_b32_e32 v34, 16, v28
	v_and_b32_e32 v28, 0xffff0000, v28
	v_mul_f32_e32 v30, v30, v34
	v_mul_f32_e32 v28, v31, v28
	v_pk_mul_f32 v[32:33], v[6:7], v[32:33]
	v_cvt_pk_bf16_f32 v28, v30, v28
	v_lshlrev_b32_e32 v30, 16, v29
	v_and_b32_e32 v29, 0xffff0000, v29
	v_mul_f32_e32 v30, v32, v30
	v_mul_f32_e32 v29, v33, v29
	v_cvt_pk_bf16_f32 v29, v30, v29
	v_add_co_u32_e32 v30, vcc, s77, v0
	s_nop 1
	v_addc_co_u32_e32 v31, vcc, 0, v1, vcc
	global_store_dwordx2 v[30:31], v[28:29], off
	ds_read_b128 v[28:31], v43 offset:5280
	s_waitcnt lgkmcnt(0)
	v_pk_mul_f32 v[32:33], v[30:31], v[30:31]
	v_pk_mul_f32 v[34:35], v[28:29], v[28:29]
	s_nop 0
	v_pk_mov_b32 v[36:37], v[34:35], v[32:33] op_sel:[1,0]
	v_mov_b32_e32 v35, v33
	v_pk_add_f32 v[32:33], v[36:37], v[34:35]
	s_nop 0
	v_add_f32_e32 v32, v32, v33
	ds_bpermute_b32 v33, v38, v32
	s_waitcnt lgkmcnt(0)
	v_add_f32_e32 v32, v32, v33
	ds_bpermute_b32 v33, v39, v32
	s_waitcnt lgkmcnt(0)
	v_add_f32_e32 v32, v32, v33
	ds_bpermute_b32 v33, v40, v32
	s_waitcnt lgkmcnt(0)
	v_add_f32_e32 v32, v32, v33
	ds_bpermute_b32 v33, v41, v32
	s_waitcnt lgkmcnt(0)
	v_add_f32_e32 v32, v32, v33
	ds_bpermute_b32 v33, v42, v32
	s_waitcnt lgkmcnt(0)
	v_add_f32_e32 v32, v32, v33
	v_fmamk_f32 v32, v32, 0x3c000000, v178
	v_cmp_gt_f32_e32 vcc, s2, v32
	v_mul_f32_e32 v33, 0x4b800000, v32
	s_nop 0
	v_cndmask_b32_e32 v32, v32, v33, vcc
	v_rsq_f32_e32 v32, v32
	s_nop 0
	v_mul_f32_e32 v33, 0x45800000, v32
	v_cndmask_b32_e32 v32, v32, v33, vcc
	v_pk_mul_f32 v[28:29], v[28:29], v[32:33] op_sel_hi:[1,0]
	v_pk_mul_f32 v[30:31], v[30:31], v[32:33] op_sel_hi:[1,0]
	v_pk_mul_f32 v[28:29], v[8:9], v[28:29]
	v_lshlrev_b32_e32 v32, 16, v26
	v_and_b32_e32 v26, 0xffff0000, v26
	v_mul_f32_e32 v28, v28, v32
	v_mul_f32_e32 v26, v29, v26
	v_pk_mul_f32 v[30:31], v[6:7], v[30:31]
	v_cvt_pk_bf16_f32 v26, v28, v26
	v_lshlrev_b32_e32 v28, 16, v27
	v_and_b32_e32 v27, 0xffff0000, v27
	v_mul_f32_e32 v28, v30, v28
	v_mul_f32_e32 v27, v31, v27
	v_cvt_pk_bf16_f32 v27, v28, v27
	v_add_co_u32_e32 v28, vcc, s5, v0
	s_nop 1
	v_addc_co_u32_e32 v29, vcc, 0, v1, vcc
	global_store_dwordx2 v[28:29], v[26:27], off
	ds_read_b128 v[26:29], v43 offset:6336
	s_waitcnt lgkmcnt(0)
	v_pk_mul_f32 v[30:31], v[28:29], v[28:29]
	v_pk_mul_f32 v[32:33], v[26:27], v[26:27]
	s_nop 0
	v_pk_mov_b32 v[34:35], v[32:33], v[30:31] op_sel:[1,0]
	v_mov_b32_e32 v33, v31
	v_pk_add_f32 v[30:31], v[34:35], v[32:33]
	s_nop 0
	v_add_f32_e32 v30, v30, v31
	ds_bpermute_b32 v31, v38, v30
	s_waitcnt lgkmcnt(0)
	v_add_f32_e32 v30, v30, v31
	ds_bpermute_b32 v31, v39, v30
	s_waitcnt lgkmcnt(0)
	v_add_f32_e32 v30, v30, v31
	ds_bpermute_b32 v31, v40, v30
	s_waitcnt lgkmcnt(0)
	v_add_f32_e32 v30, v30, v31
	ds_bpermute_b32 v31, v41, v30
	s_waitcnt lgkmcnt(0)
	v_add_f32_e32 v30, v30, v31
	ds_bpermute_b32 v31, v42, v30
	s_waitcnt lgkmcnt(0)
; #define LAS __attribute__((address_space(3)))
; __device__ __forceinline__ float bf2f(unsigned h) { return __uint_as_float(h << 16); }
; __device__ __forceinline__ unsigned cvt_pk_bf16(float lo, float hi) { unsigned r; asm volatile("v_cvt_pk_bf16_f32 %0, %1, %2" : "=v"(r) : "v"(lo), "v"(hi)); return r; }
; template <bool SUBLN>
; __device__ __forceinline__ void attn_out(const AttnBufs& T, f32x16 (&o)[4], int type, int h, size_t orow0, LAS char* lds, int wid, int lane, int r32, int hi) {
;     ...
;     f32x4 wsub = {1.f, 1.f, 1.f, 1.f};
;     if (SUBLN) { wsub = *(const f32x4*)(T.subln + c4) * (1.f - T.lam_init); }
; #pragma unroll
;     for (int i = 0; i < 16; ++i) {
;         f32x4 v = *(const LAS f32x4*)(stg + (2 * i + rr) * 132 + c4);
;         if (SUBLN) {
;             float s = (v[0] * v[0] + v[1] * v[1]) + (v[2] * v[2] + v[3] * v[3]);
;             s += __shfl_xor(s, 1); s += __shfl_xor(s, 2); s += __shfl_xor(s, 4); s += __shfl_xor(s, 8); s += __shfl_xor(s, 16);
;             v = v * (rsqrtf(s * (1.f / 128.f) + EPS)) * wsub;
;         }
;         u32x2 w; w.x = cvt_pk_bf16(v[0] * bf2f(gg[i].x & 0xffffu), v[1] * bf2f(gg[i].x >> 16)); w.y = cvt_pk_bf16(v[2] * bf2f(gg[i].y & 0xffffu), v[3] * bf2f(gg[i].y >> 16));
;         *(u32x2*)(op + (size_t)i * 2 * 3072) = w;
;     }
	v_add_f32_e32 v30, v30, v31
	v_fmamk_f32 v30, v30, 0x3c000000, v178
	v_cmp_gt_f32_e32 vcc, s2, v30
	v_mul_f32_e32 v31, 0x4b800000, v30
	s_nop 0
	v_cndmask_b32_e32 v30, v30, v31, vcc
	v_rsq_f32_e32 v30, v30
	s_nop 0
	v_mul_f32_e32 v31, 0x45800000, v30
	v_cndmask_b32_e32 v30, v30, v31, vcc
	v_pk_mul_f32 v[26:27], v[26:27], v[30:31] op_sel_hi:[1,0]
	v_pk_mul_f32 v[28:29], v[28:29], v[30:31] op_sel_hi:[1,0]
	v_pk_mul_f32 v[26:27], v[8:9], v[26:27]
	v_lshlrev_b32_e32 v30, 16, v24
	v_and_b32_e32 v24, 0xffff0000, v24
	v_mul_f32_e32 v26, v26, v30
	v_mul_f32_e32 v24, v27, v24
	v_pk_mul_f32 v[28:29], v[6:7], v[28:29]
	v_cvt_pk_bf16_f32 v24, v26, v24
	v_lshlrev_b32_e32 v26, 16, v25
	v_and_b32_e32 v25, 0xffff0000, v25
	v_mul_f32_e32 v26, v28, v26
	v_mul_f32_e32 v25, v29, v25
	v_cvt_pk_bf16_f32 v25, v26, v25
	v_add_co_u32_e32 v26, vcc, s85, v0
	s_nop 1
	v_addc_co_u32_e32 v27, vcc, 0, v1, vcc
	global_store_dwordx2 v[26:27], v[24:25], off
	ds_read_b128 v[24:27], v43 offset:7392
	s_waitcnt lgkmcnt(0)
	v_pk_mul_f32 v[28:29], v[26:27], v[26:27]
	v_pk_mul_f32 v[30:31], v[24:25], v[24:25]
	s_nop 0
	v_pk_mov_b32 v[32:33], v[30:31], v[28:29] op_sel:[1,0]
	v_mov_b32_e32 v31, v29
	v_pk_add_f32 v[28:29], v[32:33], v[30:31]
	s_nop 0
	v_add_f32_e32 v28, v28, v29
	ds_bpermute_b32 v29, v38, v28
	s_waitcnt lgkmcnt(0)
	v_add_f32_e32 v28, v28, v29
	ds_bpermute_b32 v29, v39, v28
	s_waitcnt lgkmcnt(0)
	v_add_f32_e32 v28, v28, v29
	ds_bpermute_b32 v29, v40, v28
	s_waitcnt lgkmcnt(0)
	v_add_f32_e32 v28, v28, v29
	ds_bpermute_b32 v29, v41, v28
	s_waitcnt lgkmcnt(0)
	v_add_f32_e32 v28, v28, v29
	ds_bpermute_b32 v29, v42, v28
	s_waitcnt lgkmcnt(0)
	v_add_f32_e32 v28, v28, v29
	v_fmamk_f32 v28, v28, 0x3c000000, v178
	v_cmp_gt_f32_e32 vcc, s2, v28
	v_mul_f32_e32 v29, 0x4b800000, v28
	s_nop 0
	v_cndmask_b32_e32 v28, v28, v29, vcc
	v_rsq_f32_e32 v28, v28
	s_nop 0
	v_mul_f32_e32 v29, 0x45800000, v28
	v_cndmask_b32_e32 v28, v28, v29, vcc
	v_pk_mul_f32 v[24:25], v[24:25], v[28:29] op_sel_hi:[1,0]
	v_pk_mul_f32 v[26:27], v[26:27], v[28:29] op_sel_hi:[1,0]
	v_pk_mul_f32 v[24:25], v[8:9], v[24:25]
	v_lshlrev_b32_e32 v28, 16, v22
	v_and_b32_e32 v22, 0xffff0000, v22
	v_mul_f32_e32 v24, v24, v28
	v_mul_f32_e32 v22, v25, v22
	v_pk_mul_f32 v[26:27], v[6:7], v[26:27]
	v_cvt_pk_bf16_f32 v22, v24, v22
	v_lshlrev_b32_e32 v24, 16, v23
	v_and_b32_e32 v23, 0xffff0000, v23
	v_mul_f32_e32 v24, v26, v24
	v_mul_f32_e32 v23, v27, v23
	v_cvt_pk_bf16_f32 v23, v24, v23
	v_add_co_u32_e32 v24, vcc, s20, v0
	s_nop 1
	v_addc_co_u32_e32 v25, vcc, 0, v1, vcc
	global_store_dwordx2 v[24:25], v[22:23], off
	ds_read_b128 v[22:25], v43 offset:8448
	s_waitcnt lgkmcnt(0)
	v_pk_mul_f32 v[26:27], v[24:25], v[24:25]
	v_pk_mul_f32 v[28:29], v[22:23], v[22:23]
	s_nop 0
	v_pk_mov_b32 v[30:31], v[28:29], v[26:27] op_sel:[1,0]
	v_mov_b32_e32 v29, v27
	v_pk_add_f32 v[26:27], v[30:31], v[28:29]
	s_nop 0
	v_add_f32_e32 v26, v26, v27
	ds_bpermute_b32 v27, v38, v26
	s_waitcnt lgkmcnt(0)
	v_add_f32_e32 v26, v26, v27
	ds_bpermute_b32 v27, v39, v26
	s_waitcnt lgkmcnt(0)
	v_add_f32_e32 v26, v26, v27
	ds_bpermute_b32 v27, v40, v26
	s_waitcnt lgkmcnt(0)
	v_add_f32_e32 v26, v26, v27
	ds_bpermute_b32 v27, v41, v26
	s_waitcnt lgkmcnt(0)
	v_add_f32_e32 v26, v26, v27
	ds_bpermute_b32 v27, v42, v26
	s_waitcnt lgkmcnt(0)
	v_add_f32_e32 v26, v26, v27
	v_fmamk_f32 v26, v26, 0x3c000000, v178
	v_cmp_gt_f32_e32 vcc, s2, v26
	v_mul_f32_e32 v27, 0x4b800000, v26
	s_nop 0
	v_cndmask_b32_e32 v26, v26, v27, vcc
	v_rsq_f32_e32 v26, v26
	s_nop 0
	v_mul_f32_e32 v27, 0x45800000, v26
	v_cndmask_b32_e32 v26, v26, v27, vcc
	v_pk_mul_f32 v[22:23], v[22:23], v[26:27] op_sel_hi:[1,0]
	v_pk_mul_f32 v[24:25], v[24:25], v[26:27] op_sel_hi:[1,0]
	v_pk_mul_f32 v[22:23], v[8:9], v[22:23]
	v_lshlrev_b32_e32 v26, 16, v20
	v_and_b32_e32 v20, 0xffff0000, v20
	v_mul_f32_e32 v22, v22, v26
	v_mul_f32_e32 v20, v23, v20
	v_pk_mul_f32 v[24:25], v[6:7], v[24:25]
	v_cvt_pk_bf16_f32 v20, v22, v20
	v_lshlrev_b32_e32 v22, 16, v21
	v_and_b32_e32 v21, 0xffff0000, v21
	v_mul_f32_e32 v22, v24, v22
	v_mul_f32_e32 v21, v25, v21
	v_cvt_pk_bf16_f32 v21, v22, v21
	v_add_co_u32_e32 v22, vcc, s76, v0
	s_nop 1
	v_addc_co_u32_e32 v23, vcc, 0, v1, vcc
	global_store_dwordx2 v[22:23], v[20:21], off
	ds_read_b128 v[20:23], v43 offset:9504
	s_waitcnt lgkmcnt(0)
	v_pk_mul_f32 v[24:25], v[22:23], v[22:23]
	v_pk_mul_f32 v[26:27], v[20:21], v[20:21]
	s_nop 0
	v_pk_mov_b32 v[28:29], v[26:27], v[24:25] op_sel:[1,0]
	v_mov_b32_e32 v27, v25
	v_pk_add_f32 v[24:25], v[28:29], v[26:27]
	s_nop 0
	v_add_f32_e32 v24, v24, v25
	ds_bpermute_b32 v25, v38, v24
	s_waitcnt lgkmcnt(0)
	v_add_f32_e32 v24, v24, v25
	ds_bpermute_b32 v25, v39, v24
	s_waitcnt lgkmcnt(0)
	v_add_f32_e32 v24, v24, v25
	ds_bpermute_b32 v25, v40, v24
	s_waitcnt lgkmcnt(0)
	v_add_f32_e32 v24, v24, v25
	ds_bpermute_b32 v25, v41, v24
	s_waitcnt lgkmcnt(0)
	v_add_f32_e32 v24, v24, v25
	ds_bpermute_b32 v25, v42, v24
	s_waitcnt lgkmcnt(0)
	v_add_f32_e32 v24, v24, v25
	v_fmamk_f32 v24, v24, 0x3c000000, v178
	v_cmp_gt_f32_e32 vcc, s2, v24
	v_mul_f32_e32 v25, 0x4b800000, v24
	s_nop 0
	v_cndmask_b32_e32 v24, v24, v25, vcc
	v_rsq_f32_e32 v24, v24
	s_nop 0
	v_mul_f32_e32 v25, 0x45800000, v24
	v_cndmask_b32_e32 v24, v24, v25, vcc
	v_pk_mul_f32 v[20:21], v[20:21], v[24:25] op_sel_hi:[1,0]
	v_pk_mul_f32 v[22:23], v[22:23], v[24:25] op_sel_hi:[1,0]
	v_pk_mul_f32 v[20:21], v[8:9], v[20:21]
	v_lshlrev_b32_e32 v24, 16, v18
	v_and_b32_e32 v18, 0xffff0000, v18
	v_mul_f32_e32 v20, v20, v24
	v_mul_f32_e32 v18, v21, v18
	v_pk_mul_f32 v[22:23], v[6:7], v[22:23]
	v_cvt_pk_bf16_f32 v18, v20, v18
	v_lshlrev_b32_e32 v20, 16, v19
	v_and_b32_e32 v19, 0xffff0000, v19
	v_mul_f32_e32 v20, v22, v20
	v_mul_f32_e32 v19, v23, v19
	v_cvt_pk_bf16_f32 v19, v20, v19
	v_add_co_u32_e32 v20, vcc, s21, v0
	s_nop 1
	v_addc_co_u32_e32 v21, vcc, 0, v1, vcc
	global_store_dwordx2 v[20:21], v[18:19], off
	ds_read_b128 v[18:21], v43 offset:10560
	s_waitcnt lgkmcnt(0)
; #define LAS __attribute__((address_space(3)))
; __device__ __forceinline__ float bf2f(unsigned h) { return __uint_as_float(h << 16); }
; __device__ __forceinline__ unsigned cvt_pk_bf16(float lo, float hi) { unsigned r; asm volatile("v_cvt_pk_bf16_f32 %0, %1, %2" : "=v"(r) : "v"(lo), "v"(hi)); return r; }
; template <bool SUBLN>
; __device__ __forceinline__ void attn_out(const AttnBufs& T, f32x16 (&o)[4], int type, int h, size_t orow0, LAS char* lds, int wid, int lane, int r32, int hi) {
;     ...
;     f32x4 wsub = {1.f, 1.f, 1.f, 1.f};
;     if (SUBLN) { wsub = *(const f32x4*)(T.subln + c4) * (1.f - T.lam_init); }
; #pragma unroll
;     for (int i = 0; i < 16; ++i) {
;         f32x4 v = *(const LAS f32x4*)(stg + (2 * i + rr) * 132 + c4);
;         if (SUBLN) {
;             float s = (v[0] * v[0] + v[1] * v[1]) + (v[2] * v[2] + v[3] * v[3]);
;             s += __shfl_xor(s, 1); s += __shfl_xor(s, 2); s += __shfl_xor(s, 4); s += __shfl_xor(s, 8); s += __shfl_xor(s, 16);
;             v = v * (rsqrtf(s * (1.f / 128.f) + EPS)) * wsub;
;         }
;         u32x2 w; w.x = cvt_pk_bf16(v[0] * bf2f(gg[i].x & 0xffffu), v[1] * bf2f(gg[i].x >> 16)); w.y = cvt_pk_bf16(v[2] * bf2f(gg[i].y & 0xffffu), v[3] * bf2f(gg[i].y >> 16));
;         *(u32x2*)(op + (size_t)i * 2 * 3072) = w;
;     }
	v_pk_mul_f32 v[22:23], v[20:21], v[20:21]
	v_pk_mul_f32 v[24:25], v[18:19], v[18:19]
	s_nop 0
	v_pk_mov_b32 v[26:27], v[24:25], v[22:23] op_sel:[1,0]
	v_mov_b32_e32 v25, v23
	v_pk_add_f32 v[22:23], v[26:27], v[24:25]
	s_nop 0
	v_add_f32_e32 v22, v22, v23
	ds_bpermute_b32 v23, v38, v22
	s_waitcnt lgkmcnt(0)
	v_add_f32_e32 v22, v22, v23
	ds_bpermute_b32 v23, v39, v22
	s_waitcnt lgkmcnt(0)
	v_add_f32_e32 v22, v22, v23
	ds_bpermute_b32 v23, v40, v22
	s_waitcnt lgkmcnt(0)
	v_add_f32_e32 v22, v22, v23
	ds_bpermute_b32 v23, v41, v22
	s_waitcnt lgkmcnt(0)
	v_add_f32_e32 v22, v22, v23
	ds_bpermute_b32 v23, v42, v22
	s_waitcnt lgkmcnt(0)
	v_add_f32_e32 v22, v22, v23
	v_fmamk_f32 v22, v22, 0x3c000000, v178
	v_cmp_gt_f32_e32 vcc, s2, v22
	v_mul_f32_e32 v23, 0x4b800000, v22
	s_nop 0
	v_cndmask_b32_e32 v22, v22, v23, vcc
	v_rsq_f32_e32 v22, v22
	s_nop 0
	v_mul_f32_e32 v23, 0x45800000, v22
	v_cndmask_b32_e32 v22, v22, v23, vcc
	v_pk_mul_f32 v[18:19], v[18:19], v[22:23] op_sel_hi:[1,0]
	v_pk_mul_f32 v[20:21], v[20:21], v[22:23] op_sel_hi:[1,0]
	v_pk_mul_f32 v[18:19], v[8:9], v[18:19]
	v_lshlrev_b32_e32 v22, 16, v16
	v_and_b32_e32 v16, 0xffff0000, v16
	v_mul_f32_e32 v18, v18, v22
	v_mul_f32_e32 v16, v19, v16
	v_pk_mul_f32 v[20:21], v[6:7], v[20:21]
	v_cvt_pk_bf16_f32 v16, v18, v16
	v_lshlrev_b32_e32 v18, 16, v17
	v_and_b32_e32 v17, 0xffff0000, v17
	v_mul_f32_e32 v18, v20, v18
	v_mul_f32_e32 v17, v21, v17
	v_cvt_pk_bf16_f32 v17, v18, v17
	v_add_co_u32_e32 v18, vcc, s92, v0
	s_nop 1
	v_addc_co_u32_e32 v19, vcc, 0, v1, vcc
	global_store_dwordx2 v[18:19], v[16:17], off
	ds_read_b128 v[16:19], v43 offset:11616
	s_waitcnt lgkmcnt(0)
	v_pk_mul_f32 v[20:21], v[18:19], v[18:19]
	v_pk_mul_f32 v[22:23], v[16:17], v[16:17]
	s_nop 0
	v_pk_mov_b32 v[24:25], v[22:23], v[20:21] op_sel:[1,0]
	v_mov_b32_e32 v23, v21
	v_pk_add_f32 v[20:21], v[24:25], v[22:23]
	s_nop 0
	v_add_f32_e32 v20, v20, v21
	ds_bpermute_b32 v21, v38, v20
	s_waitcnt lgkmcnt(0)
	v_add_f32_e32 v20, v20, v21
	ds_bpermute_b32 v21, v39, v20
	s_waitcnt lgkmcnt(0)
	v_add_f32_e32 v20, v20, v21
	ds_bpermute_b32 v21, v40, v20
	s_waitcnt lgkmcnt(0)
	v_add_f32_e32 v20, v20, v21
	ds_bpermute_b32 v21, v41, v20
	s_waitcnt lgkmcnt(0)
	v_add_f32_e32 v20, v20, v21
	ds_bpermute_b32 v21, v42, v20
	s_waitcnt lgkmcnt(0)
	v_add_f32_e32 v20, v20, v21
	v_fmamk_f32 v20, v20, 0x3c000000, v178
	v_cmp_gt_f32_e32 vcc, s2, v20
	v_mul_f32_e32 v21, 0x4b800000, v20
	s_nop 0
	v_cndmask_b32_e32 v20, v20, v21, vcc
	v_rsq_f32_e32 v20, v20
	s_nop 0
	v_mul_f32_e32 v21, 0x45800000, v20
	v_cndmask_b32_e32 v20, v20, v21, vcc
	v_pk_mul_f32 v[16:17], v[16:17], v[20:21] op_sel_hi:[1,0]
	v_pk_mul_f32 v[18:19], v[18:19], v[20:21] op_sel_hi:[1,0]
	v_pk_mul_f32 v[16:17], v[8:9], v[16:17]
	v_lshlrev_b32_e32 v20, 16, v14
	v_and_b32_e32 v14, 0xffff0000, v14
	v_mul_f32_e32 v16, v16, v20
	v_mul_f32_e32 v14, v17, v14
	v_pk_mul_f32 v[18:19], v[6:7], v[18:19]
	v_cvt_pk_bf16_f32 v14, v16, v14
	v_lshlrev_b32_e32 v16, 16, v15
	v_and_b32_e32 v15, 0xffff0000, v15
	v_mul_f32_e32 v16, v18, v16
	v_mul_f32_e32 v15, v19, v15
	v_cvt_pk_bf16_f32 v15, v16, v15
	v_add_co_u32_e32 v16, vcc, s3, v0
	s_nop 1
	v_addc_co_u32_e32 v17, vcc, 0, v1, vcc
	global_store_dwordx2 v[16:17], v[14:15], off
	ds_read_b128 v[14:17], v43 offset:12672
	s_waitcnt lgkmcnt(0)
	v_pk_mul_f32 v[18:19], v[16:17], v[16:17]
	v_pk_mul_f32 v[20:21], v[14:15], v[14:15]
	s_nop 0
	v_pk_mov_b32 v[22:23], v[20:21], v[18:19] op_sel:[1,0]
	v_mov_b32_e32 v21, v19
	v_pk_add_f32 v[18:19], v[22:23], v[20:21]
	s_nop 0
	v_add_f32_e32 v18, v18, v19
	ds_bpermute_b32 v19, v38, v18
	s_waitcnt lgkmcnt(0)
	v_add_f32_e32 v18, v18, v19
	ds_bpermute_b32 v19, v39, v18
	s_waitcnt lgkmcnt(0)
	v_add_f32_e32 v18, v18, v19
	ds_bpermute_b32 v19, v40, v18
	s_waitcnt lgkmcnt(0)
	v_add_f32_e32 v18, v18, v19
	ds_bpermute_b32 v19, v41, v18
	s_waitcnt lgkmcnt(0)
	v_add_f32_e32 v18, v18, v19
	ds_bpermute_b32 v19, v42, v18
	s_waitcnt lgkmcnt(0)
	v_add_f32_e32 v18, v18, v19
	v_fmamk_f32 v18, v18, 0x3c000000, v178
	v_cmp_gt_f32_e32 vcc, s2, v18
	v_mul_f32_e32 v19, 0x4b800000, v18
	s_nop 0
	v_cndmask_b32_e32 v18, v18, v19, vcc
	v_rsq_f32_e32 v18, v18
	s_nop 0
	v_mul_f32_e32 v19, 0x45800000, v18
	v_cndmask_b32_e32 v18, v18, v19, vcc
	v_pk_mul_f32 v[14:15], v[14:15], v[18:19] op_sel_hi:[1,0]
	v_pk_mul_f32 v[16:17], v[16:17], v[18:19] op_sel_hi:[1,0]
	v_pk_mul_f32 v[14:15], v[8:9], v[14:15]
	v_lshlrev_b32_e32 v18, 16, v12
	v_and_b32_e32 v12, 0xffff0000, v12
	v_mul_f32_e32 v14, v14, v18
	v_mul_f32_e32 v12, v15, v12
	v_pk_mul_f32 v[16:17], v[6:7], v[16:17]
	v_cvt_pk_bf16_f32 v12, v14, v12
	v_lshlrev_b32_e32 v14, 16, v13
	v_and_b32_e32 v13, 0xffff0000, v13
	v_mul_f32_e32 v14, v16, v14
	v_mul_f32_e32 v13, v17, v13
	v_cvt_pk_bf16_f32 v13, v14, v13
	v_add_co_u32_e32 v14, vcc, s91, v0
	s_nop 1
	v_addc_co_u32_e32 v15, vcc, 0, v1, vcc
	global_store_dwordx2 v[14:15], v[12:13], off
	ds_read_b128 v[12:15], v43 offset:13728
	s_waitcnt lgkmcnt(0)
	v_pk_mul_f32 v[16:17], v[14:15], v[14:15]
	v_pk_mul_f32 v[18:19], v[12:13], v[12:13]
	s_nop 0
	v_pk_mov_b32 v[20:21], v[18:19], v[16:17] op_sel:[1,0]
	v_mov_b32_e32 v19, v17
	v_pk_add_f32 v[16:17], v[20:21], v[18:19]
	s_nop 0
	v_add_f32_e32 v16, v16, v17
	ds_bpermute_b32 v17, v38, v16
	s_waitcnt lgkmcnt(0)
	v_add_f32_e32 v16, v16, v17
	ds_bpermute_b32 v17, v39, v16
	s_waitcnt lgkmcnt(0)
	v_add_f32_e32 v16, v16, v17
	ds_bpermute_b32 v17, v40, v16
	s_waitcnt lgkmcnt(0)
	v_add_f32_e32 v16, v16, v17
	ds_bpermute_b32 v17, v41, v16
	s_waitcnt lgkmcnt(0)
	v_add_f32_e32 v16, v16, v17
	ds_bpermute_b32 v17, v42, v16
	s_waitcnt lgkmcnt(0)
; #define LAS __attribute__((address_space(3)))
; __device__ __forceinline__ float bf2f(unsigned h) { return __uint_as_float(h << 16); }
; #define VMW0() asm volatile("s_waitcnt vmcnt(0)" ::: "memory")
; template <int DQK, bool DOUBLE> ...
;     ...
;     const int wid = __builtin_amdgcn_readfirstlane(tid >> 6), lane = tid & 63, r32 = lane & 31, hi = lane >> 5;
;     LAS char* V_lds = lds; LAS char* K_lds = lds + K_OFF;
;     bf16x8 qr[DQK / 16];
;     { const bf16_t* Qw = Q + (size_t)(wid * 32 + r32) * ldq + hi * 8;
; #pragma unroll
;       for (int d0 = 0; d0 < DQK / 16; ++d0) qr[d0] = *(const bf16x8*)(Qw + d0 * 16); }
; #pragma unroll
;     for (int d = 0; d < 4; ++d) o[d] = f32x16{};
;     l_reg = 0.f;
;     int vrow[2], vcol[2], krow[NLD], kcol[NLD];
; #pragma unroll
;     for (int i = 0; i < 2; ++i) { const int q = tid + 512 * i, sub = q >> 5, within = q & 31, kk = (sub >> 2) * 8 + (within >> 2);
;         vrow[i] = kk; vcol[i] = (sub & 3) * 32 + (within & 3) * 8; }
; #pragma unroll
;     for (int i = 0; i < NLD; ++i) { const int q = tid + 512 * i, row = q / NCH, chp = q % NCH; const int x = (RB == 256) ? (row & 15) : ((row >> 1) & 7);
;         krow[i] = row; kcol[i] = (chp ^ x) * 8; }
;     const unsigned vb0 = (unsigned)(uintptr_t)V_lds + v_rd_base(lane);
;     int ka[8];
; #pragma unroll
;     for (int q = 0; q < 8; ++q) ka[q] = kswz<RB>(r32, q * 32 + hi * 16);
;     ...
;     bf16x8 pa0, pa1, pa2, pa3;
;     __syncthreads();
;     DMA(0, 0); DMA(1, 1); VMW0(); __syncthreads();
; template <bool SUBLN>
; __device__ __forceinline__ void attn_out(const AttnBufs& T, f32x16 (&o)[4], int type, int h, size_t orow0, LAS char* lds, int wid, int lane, int r32, int hi) {
;     ...
;     for (int i = 0; i < 16; ++i) {
;         f32x4 v = *(const LAS f32x4*)(stg + (2 * i + rr) * 132 + c4);
;         if (SUBLN) {
;             float s = (v[0] * v[0] + v[1] * v[1]) + (v[2] * v[2] + v[3] * v[3]);
;             s += __shfl_xor(s, 1); s += __shfl_xor(s, 2); s += __shfl_xor(s, 4); s += __shfl_xor(s, 8); s += __shfl_xor(s, 16);
;             v = v * (rsqrtf(s * (1.f / 128.f) + EPS)) * wsub;
;         }
;         u32x2 w; w.x = cvt_pk_bf16(v[0] * bf2f(gg[i].x & 0xffffu), v[1] * bf2f(gg[i].x >> 16)); w.y = cvt_pk_bf16(v[2] * bf2f(gg[i].y & 0xffffu), v[3] * bf2f(gg[i].y >> 16));
;         *(u32x2*)(op + (size_t)i * 2 * 3072) = w;
;     }
	v_add_f32_e32 v16, v16, v17
	v_fmamk_f32 v16, v16, 0x3c000000, v178
	v_cmp_gt_f32_e32 vcc, s2, v16
	v_mul_f32_e32 v17, 0x4b800000, v16
	s_nop 0
	v_cndmask_b32_e32 v16, v16, v17, vcc
	v_rsq_f32_e32 v16, v16
	s_nop 0
	v_mul_f32_e32 v17, 0x45800000, v16
	v_cndmask_b32_e32 v16, v16, v17, vcc
	v_pk_mul_f32 v[12:13], v[12:13], v[16:17] op_sel_hi:[1,0]
	v_pk_mul_f32 v[14:15], v[14:15], v[16:17] op_sel_hi:[1,0]
	v_pk_mul_f32 v[12:13], v[8:9], v[12:13]
	v_lshlrev_b32_e32 v16, 16, v10
	v_and_b32_e32 v10, 0xffff0000, v10
	v_mul_f32_e32 v12, v12, v16
	v_mul_f32_e32 v10, v13, v10
	v_pk_mul_f32 v[14:15], v[6:7], v[14:15]
	v_cvt_pk_bf16_f32 v10, v12, v10
	v_lshlrev_b32_e32 v12, 16, v11
	v_and_b32_e32 v11, 0xffff0000, v11
	v_mul_f32_e32 v12, v14, v12
	v_mul_f32_e32 v11, v15, v11
	v_cvt_pk_bf16_f32 v11, v12, v11
	v_add_co_u32_e32 v12, vcc, s33, v0
	s_nop 1
	v_addc_co_u32_e32 v13, vcc, 0, v1, vcc
	global_store_dwordx2 v[12:13], v[10:11], off
	ds_read_b128 v[10:13], v43 offset:14784
	s_waitcnt lgkmcnt(0)
	v_pk_mul_f32 v[14:15], v[12:13], v[12:13]
	v_pk_mul_f32 v[16:17], v[10:11], v[10:11]
	s_nop 0
	v_pk_mov_b32 v[18:19], v[16:17], v[14:15] op_sel:[1,0]
	v_mov_b32_e32 v17, v15
	v_pk_add_f32 v[14:15], v[18:19], v[16:17]
	s_nop 0
	v_add_f32_e32 v14, v14, v15
	ds_bpermute_b32 v15, v38, v14
	s_waitcnt lgkmcnt(0)
	v_add_f32_e32 v14, v14, v15
	ds_bpermute_b32 v15, v39, v14
	s_waitcnt lgkmcnt(0)
	v_add_f32_e32 v14, v14, v15
	ds_bpermute_b32 v15, v40, v14
	s_waitcnt lgkmcnt(0)
	v_add_f32_e32 v14, v14, v15
	ds_bpermute_b32 v15, v41, v14
	s_waitcnt lgkmcnt(0)
	v_add_f32_e32 v14, v14, v15
	ds_bpermute_b32 v15, v42, v14
	s_waitcnt lgkmcnt(0)
	v_add_f32_e32 v14, v14, v15
	v_fmamk_f32 v14, v14, 0x3c000000, v178
	v_cmp_gt_f32_e32 vcc, s2, v14
	v_mul_f32_e32 v15, 0x4b800000, v14
	s_nop 0
	v_cndmask_b32_e32 v14, v14, v15, vcc
	v_rsq_f32_e32 v14, v14
	s_nop 0
	v_mul_f32_e32 v15, 0x45800000, v14
	v_cndmask_b32_e32 v14, v14, v15, vcc
	v_pk_mul_f32 v[10:11], v[10:11], v[14:15] op_sel_hi:[1,0]
	v_pk_mul_f32 v[12:13], v[12:13], v[14:15] op_sel_hi:[1,0]
	v_pk_mul_f32 v[10:11], v[8:9], v[10:11]
	v_lshlrev_b32_e32 v14, 16, v4
	v_and_b32_e32 v4, 0xffff0000, v4
	v_mul_f32_e32 v10, v10, v14
	v_mul_f32_e32 v4, v11, v4
	v_pk_mul_f32 v[12:13], v[6:7], v[12:13]
	v_cvt_pk_bf16_f32 v4, v10, v4
	v_lshlrev_b32_e32 v10, 16, v5
	v_and_b32_e32 v5, 0xffff0000, v5
	v_mul_f32_e32 v10, v12, v10
	v_mul_f32_e32 v5, v13, v5
	v_cvt_pk_bf16_f32 v5, v10, v5
	v_add_co_u32_e32 v10, vcc, s94, v0
	s_nop 1
	v_addc_co_u32_e32 v11, vcc, 0, v1, vcc
	global_store_dwordx2 v[10:11], v[4:5], off
	ds_read_b128 v[10:13], v43 offset:15840
	s_waitcnt lgkmcnt(0)
	v_pk_mul_f32 v[4:5], v[12:13], v[12:13]
	v_pk_mul_f32 v[14:15], v[10:11], v[10:11]
	s_nop 0
	v_pk_mov_b32 v[16:17], v[14:15], v[4:5] op_sel:[1,0]
	v_mov_b32_e32 v15, v5
	v_pk_add_f32 v[4:5], v[16:17], v[14:15]
	s_nop 0
	v_add_f32_e32 v4, v4, v5
	ds_bpermute_b32 v5, v38, v4
	s_waitcnt lgkmcnt(0)
	v_add_f32_e32 v4, v4, v5
	ds_bpermute_b32 v5, v39, v4
	s_waitcnt lgkmcnt(0)
	v_add_f32_e32 v4, v4, v5
	ds_bpermute_b32 v5, v40, v4
	s_waitcnt lgkmcnt(0)
	v_add_f32_e32 v4, v4, v5
	ds_bpermute_b32 v5, v41, v4
	s_waitcnt lgkmcnt(0)
	v_add_f32_e32 v4, v4, v5
	ds_bpermute_b32 v5, v42, v4
	s_waitcnt lgkmcnt(0)
	v_add_f32_e32 v4, v4, v5
	v_fmamk_f32 v4, v4, 0x3c000000, v178
	v_cmp_gt_f32_e32 vcc, s2, v4
	v_mul_f32_e32 v5, 0x4b800000, v4
	s_nop 0
	v_cndmask_b32_e32 v4, v4, v5, vcc
	v_rsq_f32_e32 v4, v4
	s_nop 0
	v_mul_f32_e32 v5, 0x45800000, v4
	v_cndmask_b32_e32 v4, v4, v5, vcc
	v_pk_mul_f32 v[10:11], v[10:11], v[4:5] op_sel_hi:[1,0]
	v_pk_mul_f32 v[4:5], v[12:13], v[4:5] op_sel_hi:[1,0]
	s_nop 0
	v_pk_mul_f32 v[4:5], v[6:7], v[4:5]
	v_pk_mul_f32 v[6:7], v[8:9], v[10:11]
	v_lshlrev_b32_e32 v8, 16, v2
	v_and_b32_e32 v2, 0xffff0000, v2
	v_mul_f32_e32 v6, v6, v8
	v_mul_f32_e32 v2, v7, v2
	v_cvt_pk_bf16_f32 v2, v6, v2
	v_lshlrev_b32_e32 v6, 16, v3
	v_and_b32_e32 v3, 0xffff0000, v3
	v_mul_f32_e32 v3, v5, v3
	v_mul_f32_e32 v4, v4, v6
	v_cvt_pk_bf16_f32 v3, v4, v3
.LBB0_171:
	s_and_b64 vcc, exec, s[48:49]
	s_cbranch_vccz .LBB0_108
	s_lshl_b64 s[2:3], s[30:31], 11
	v_readlane_b32 s4, v251, 26
	v_readlane_b32 s5, v251, 27
	s_add_u32 s4, s4, s2
	s_addc_u32 s5, s5, s3
	s_lshl_b32 s48, s72, 7
	s_ashr_i32 s49, s48, 31
	s_lshl_b64 s[2:3], s[48:49], 1
	s_add_u32 s2, s4, s2
	s_addc_u32 s3, s5, s3
	s_lshl_b32 s4, s72, 5
	s_and_b32 s4, s4, 0xffffff80
	s_ashr_i32 s5, s4, 31
	s_lshl_b64 s[4:5], s[4:5], 1
	v_readlane_b32 s20, v251, 28
	v_readlane_b32 s21, v251, 29
	s_add_u32 s50, s20, s4
	s_addc_u32 s51, s21, s5
	v_readlane_b32 s20, v251, 30
	v_readlane_b32 s21, v251, 31
	s_add_u32 s56, s20, s4
	v_readfirstlane_b32 s4, v164
	s_addc_u32 s57, s21, s5
	s_ashr_i32 s4, s4, 6
	v_lshl_or_b32 v2, s4, 5, v181
	v_bfi_b32 v146, -8, v195, v196
	v_ashrrev_i32_e32 v3, 31, v2
	s_ashr_i32 s47, s46, 31
	v_ashrrev_i32_e32 v147, 31, v146
	v_lshlrev_b64 v[2:3], 11, v[2:3]
	v_lshl_add_u64 v[6:7], v[146:147], 0, s[46:47]
	v_lshl_add_u64 v[2:3], s[2:3], 0, v[2:3]
	v_lshrrev_b32_e32 v1, 28, v165
	s_lshl_b32 s2, s4, 10
	v_lshlrev_b64 v[6:7], 9, v[6:7]
	v_mov_b32_e32 v145, v177
	v_bfi_b32 v148, -8, v197, v196
	v_add_u32_e32 v1, v164, v1
	s_add_i32 s3, s2, 0
	v_lshl_add_u64 v[6:7], s[56:57], 0, v[6:7]
	v_lshlrev_b32_e32 v80, 1, v193
	v_mov_b32_e32 v81, v177
	v_lshl_add_u64 v[2:3], v[2:3], 0, v[144:145]
	v_ashrrev_i32_e32 v150, 4, v1
	v_and_b32_e32 v1, 0x1ffffff0, v1
	v_lshl_add_u64 v[6:7], v[6:7], 0, v[80:81]
	s_mov_b32 m0, s3
	v_ashrrev_i32_e32 v149, 31, v148
	global_load_dword v0, v177, s[14:15] offset:4
	global_load_dwordx4 v[112:115], v[2:3], off
	global_load_dwordx4 v[116:119], v[2:3], off offset:32
	global_load_dwordx4 v[120:123], v[2:3], off offset:64
	global_load_dwordx4 v[124:127], v[2:3], off offset:96
	s_waitcnt lgkmcnt(0)
	global_load_dwordx4 v[128:131], v[2:3], off offset:128
	global_load_dwordx4 v[132:135], v[2:3], off offset:160
	global_load_dwordx4 v[136:139], v[2:3], off offset:192
	global_load_dwordx4 v[140:143], v[2:3], off offset:224
	v_sub_u32_e32 v1, v164, v1
	s_barrier
; #define LAS __attribute__((address_space(3)))
; #define SBAR() __builtin_amdgcn_sched_barrier(0)
; __device__ __forceinline__ int v_rd_base(int lane) { return ((lane & 3) << 3) | (((lane >> 2) & 3) << 6) | (((lane >> 4) & 1) << 5) | (((lane >> 5) & 1) << 8); }
; #define VMW0() asm volatile("s_waitcnt vmcnt(0)" ::: "memory")
; template <int DQK>
; __device__ __forceinline__ void qkt(f32x16& p0, f32x16& p1, const LAS char* Ks, const bf16x8 (&qr)[DQK / 16], const int (&ka)[8], float nMB) {
;     constexpr int RB = DQK * 2, NA = (RB == 256) ? 8 : 4;
; #pragma unroll
;     for (int r = 0; r < 16; ++r) { p0[r] = nMB; p1[r] = nMB; }
; #pragma unroll
;     for (int d0 = 0; d0 < DQK / 16; ++d0) {
;         const LAS char* a = Ks + ka[d0 % NA] + (d0 / NA) * (NA * 32);
;         const bf16x8 b0 = *(const LAS bf16x8*)(a);
;         const bf16x8 b1 = *(const LAS bf16x8*)(a + 32 * RB);
;         p0 = __builtin_amdgcn_mfma_f32_32x32x16_bf16(b0, qr[d0], p0, 0, 0, 0);
;         p1 = __builtin_amdgcn_mfma_f32_32x32x16_bf16(b1, qr[d0], p1, 0, 0, 0); }
; }
; template <int DQK, bool DOUBLE> ...
;     ...
;     int vrow[2], vcol[2], krow[NLD], kcol[NLD];
; #pragma unroll
;     for (int i = 0; i < 2; ++i) { const int q = tid + 512 * i, sub = q >> 5, within = q & 31, kk = (sub >> 2) * 8 + (within >> 2);
;         vrow[i] = kk; vcol[i] = (sub & 3) * 32 + (within & 3) * 8; }
; #pragma unroll
;     for (int i = 0; i < NLD; ++i) { const int q = tid + 512 * i, row = q / NCH, chp = q % NCH; const int x = (RB == 256) ? (row & 15) : ((row >> 1) & 7);
;         krow[i] = row; kcol[i] = (chp ^ x) * 8; }
;     const unsigned vb0 = (unsigned)(uintptr_t)V_lds + v_rd_base(lane);
;     int ka[8];
; #pragma unroll
;     for (int q = 0; q < 8; ++q) ka[q] = kswz<RB>(r32, q * 32 + hi * 16);
;     ...
;     bf16x8 pa0, pa1, pa2, pa3;
;     __syncthreads();
;     DMA(0, 0); DMA(1, 1); VMW0(); __syncthreads();
;     if constexpr (!DOUBLE) {
;         f32x16 p0, p1;
;         DMA(2, 2);
;         int bc = 0, bn = 1, bf = 2;
;         for (int j = 0; j < NT; ++j) {
;             SBAR(); qkt<DQK>(p0, p1, K_lds + bc * K_STRIDE, qr, ka, nMB);
	global_load_lds_dwordx4 v[6:7], off
	v_lshl_add_u64 v[6:7], v[148:149], 0, s[46:47]
	v_bitop3_b32 v1, v150, v1, 15 bitop3:0x6c
	v_lshlrev_b64 v[6:7], 9, v[6:7]
	v_lshlrev_b32_e32 v2, 3, v1
	v_ashrrev_i32_e32 v1, 31, v194
	v_lshl_add_u64 v[6:7], s[56:57], 0, v[6:7]
	s_add_i32 s21, s3, 0x2000
	v_lshrrev_b32_e32 v1, 28, v1
	v_lshl_add_u64 v[6:7], v[6:7], 0, v[80:81]
	s_mov_b32 m0, s21
	v_ashrrev_i32_e32 v151, 31, v150
	v_add_u32_e32 v1, v194, v1
	global_load_lds_dwordx4 v[6:7], off
	v_lshl_add_u64 v[6:7], v[150:151], 0, s[46:47]
	v_ashrrev_i32_e32 v152, 4, v1
	v_and_b32_e32 v1, 0x1ffffff0, v1
	v_lshlrev_b64 v[6:7], 9, v[6:7]
	v_ashrrev_i32_e32 v3, 31, v2
	v_sub_u32_e32 v1, v194, v1
	s_add_i32 s20, s3, 0xc000
	v_lshl_add_u64 v[6:7], s[50:51], 0, v[6:7]
	v_lshlrev_b64 v[82:83], 1, v[2:3]
	v_bitop3_b32 v1, v152, v1, 15 bitop3:0x6c
	v_lshl_add_u64 v[2:3], v[6:7], 0, v[82:83]
	s_mov_b32 m0, s20
	v_ashrrev_i32_e32 v153, 31, v152
	v_lshlrev_b32_e32 v4, 3, v1
	global_load_lds_dwordx4 v[2:3], off
	v_lshl_add_u64 v[2:3], v[152:153], 0, s[46:47]
	v_lshlrev_b64 v[2:3], 9, v[2:3]
	v_ashrrev_i32_e32 v5, 31, v4
	v_lshl_add_u64 v[2:3], s[50:51], 0, v[2:3]
	v_lshlrev_b64 v[84:85], 1, v[4:5]
	s_add_i32 s31, s3, 0xe000
	s_add_i32 s4, s45, 0x4040
	v_lshl_add_u64 v[2:3], v[2:3], 0, v[84:85]
	s_mov_b32 m0, s31
	s_ashr_i32 s5, s4, 31
	global_load_lds_dwordx4 v[2:3], off
	v_lshl_add_u64 v[2:3], v[146:147], 0, s[4:5]
	v_lshlrev_b64 v[2:3], 9, v[2:3]
	v_lshl_add_u64 v[2:3], s[56:57], 0, v[2:3]
	s_add_i32 m0, s3, 0x4000
	v_lshl_add_u64 v[2:3], v[2:3], 0, v[80:81]
	global_load_lds_dwordx4 v[2:3], off
	v_lshl_add_u64 v[2:3], v[148:149], 0, s[4:5]
	v_lshlrev_b64 v[2:3], 9, v[2:3]
	v_lshl_add_u64 v[2:3], s[56:57], 0, v[2:3]
	v_lshl_add_u64 v[2:3], v[2:3], 0, v[80:81]
	s_add_i32 m0, s3, 0x6000
	v_lshlrev_b32_e32 v1, 8, v181
	global_load_lds_dwordx4 v[2:3], off
	v_lshl_add_u64 v[2:3], v[150:151], 0, s[4:5]
	v_lshlrev_b64 v[2:3], 9, v[2:3]
	v_lshl_add_u64 v[2:3], s[50:51], 0, v[2:3]
	s_add_i32 m0, s3, 0x12000
	v_lshl_add_u64 v[2:3], v[2:3], 0, v[82:83]
	global_load_lds_dwordx4 v[2:3], off
	v_lshl_add_u64 v[2:3], v[152:153], 0, s[4:5]
	v_lshlrev_b64 v[2:3], 9, v[2:3]
	v_lshl_add_u64 v[2:3], s[50:51], 0, v[2:3]
	s_add_i32 s4, s45, 0x4080
	v_lshl_add_u64 v[2:3], v[2:3], 0, v[84:85]
	s_add_i32 m0, s3, 0x14000
	s_ashr_i32 s5, s4, 31
	global_load_lds_dwordx4 v[2:3], off
	v_lshl_add_u64 v[2:3], v[146:147], 0, s[4:5]
	v_lshlrev_b64 v[2:3], 9, v[2:3]
	v_lshl_add_u64 v[2:3], s[56:57], 0, v[2:3]
	s_add_i32 m0, s3, 0x8000
	v_lshl_add_u64 v[2:3], v[2:3], 0, v[80:81]
	s_waitcnt vmcnt(0)
	s_waitcnt vmcnt(0) lgkmcnt(0)
	s_barrier
	global_load_lds_dwordx4 v[2:3], off
	v_lshl_add_u64 v[2:3], v[148:149], 0, s[4:5]
	v_lshlrev_b64 v[2:3], 9, v[2:3]
	v_lshl_add_u64 v[2:3], s[56:57], 0, v[2:3]
	v_lshl_add_u64 v[2:3], v[2:3], 0, v[80:81]
	s_add_i32 m0, s3, 0xa000
	s_movk_i32 s33, 0x118
	global_load_lds_dwordx4 v[2:3], off
	v_lshl_add_u64 v[2:3], v[150:151], 0, s[4:5]
	v_lshlrev_b64 v[2:3], 9, v[2:3]
	v_lshl_add_u64 v[2:3], s[50:51], 0, v[2:3]
	s_add_i32 m0, s3, 0x18000
	v_lshl_add_u64 v[2:3], v[2:3], 0, v[82:83]
	global_load_lds_dwordx4 v[2:3], off
	v_lshl_add_u64 v[2:3], v[152:153], 0, s[4:5]
	v_lshlrev_b64 v[2:3], 9, v[2:3]
	v_lshl_add_u64 v[2:3], s[50:51], 0, v[2:3]
	v_lshl_add_u64 v[2:3], v[2:3], 0, v[84:85]
	s_add_i32 m0, s3, 0x1a000
	s_mov_b32 s5, 1
	global_load_lds_dwordx4 v[2:3], off
	v_lshlrev_b32_e32 v2, 4, v181
	v_and_b32_e32 v2, 0xf0, v2
	v_or_b32_e32 v3, 0x80, v144
	v_bitop3_b32 v166, v3, v1, v2 bitop3:0xde
	v_or_b32_e32 v3, 0xa0, v144
	v_bitop3_b32 v167, v3, v1, v2 bitop3:0xde
	v_or_b32_e32 v3, 0xc0, v144
	v_bitop3_b32 v168, v3, v1, v2 bitop3:0xde
	v_or_b32_e32 v3, 0xe0, v144
	v_bitop3_b32 v145, v144, v1, v2 bitop3:0xde
	v_bitop3_b32 v161, v187, v1, v2 bitop3:0xde
	v_bitop3_b32 v164, v191, v1, v2 bitop3:0xde
	v_bitop3_b32 v165, v192, v1, v2 bitop3:0xde
	v_bitop3_b32 v169, v3, v1, v2 bitop3:0xde
	v_and_b32_e32 v1, 32, v175
	v_and_or_b32 v16, v174, s33, v1
	s_mov_b32 s4, 2
	v_mov_b32_e32 v1, v0
	v_mov_b32_e32 v2, v0
	v_mov_b32_e32 v3, v0
	v_mov_b32_e32 v4, v0
	v_mov_b32_e32 v5, v0
	v_mov_b32_e32 v6, v0
	v_mov_b32_e32 v7, v0
	v_mov_b32_e32 v8, v0
	v_mov_b32_e32 v9, v0
	v_mov_b32_e32 v10, v0
	v_mov_b32_e32 v11, v0
	v_mov_b32_e32 v12, v0
	v_mov_b32_e32 v13, v0
	v_mov_b32_e32 v14, v0
	v_mov_b32_e32 v15, v0
	v_add3_u32 v170, v173, 0, v16
	s_add_i32 s46, s45, 0x40c0
	v_add_u32_e32 v20, 0, v145
	ds_read_b128 v[16:19], v20 offset:49152
	ds_read_b128 v[48:51], v20 offset:57344
	v_add_u32_e32 v52, 0, v161
	s_waitcnt lgkmcnt(0)
	v_mfma_f32_32x32x16_bf16 v[32:47], v[16:19], v[112:115], v[0:15]
	v_mfma_f32_32x32x16_bf16 v[16:31], v[48:51], v[112:115], v[0:15]
	ds_read_b128 v[48:51], v52 offset:49152
	ds_read_b128 v[52:55], v52 offset:57344
	s_waitcnt lgkmcnt(0)
	v_mfma_f32_32x32x16_bf16 v[32:47], v[48:51], v[116:119], v[32:47]
	v_mfma_f32_32x32x16_bf16 v[16:31], v[52:55], v[116:119], v[16:31]
	v_add_u32_e32 v52, 0, v164
	ds_read_b128 v[48:51], v52 offset:49152
	ds_read_b128 v[52:55], v52 offset:57344
	s_waitcnt lgkmcnt(0)
	v_mfma_f32_32x32x16_bf16 v[32:47], v[48:51], v[120:123], v[32:47]
	v_mfma_f32_32x32x16_bf16 v[16:31], v[52:55], v[120:123], v[16:31]
	v_add_u32_e32 v52, 0, v165
	ds_read_b128 v[48:51], v52 offset:49152
	ds_read_b128 v[52:55], v52 offset:57344
	s_waitcnt lgkmcnt(0)
	v_mfma_f32_32x32x16_bf16 v[32:47], v[48:51], v[124:127], v[32:47]
	v_mfma_f32_32x32x16_bf16 v[16:31], v[52:55], v[124:127], v[16:31]
	v_add_u32_e32 v52, 0, v166
	ds_read_b128 v[48:51], v52 offset:49152
	ds_read_b128 v[52:55], v52 offset:57344
	s_waitcnt lgkmcnt(0)
; template <int D0> __device__ __forceinline__ void pv_one(f32x16& od, unsigned vb, bf16x8 pa0, bf16x8 pa1, bf16x8 pa2, bf16x8 pa3) {
;     const s16x4 l0 = tr_read<v_rd_off(D0, 0, 0)>(vb), h0 = tr_read<v_rd_off(D0, 0, 1)>(vb), l1 = tr_read<v_rd_off(D0, 1, 0)>(vb), h1 = tr_read<v_rd_off(D0, 1, 1)>(vb);
;     const s16x4 l2 = tr_read<v_rd_off(D0, 2, 0)>(vb), h2 = tr_read<v_rd_off(D0, 2, 1)>(vb), l3 = tr_read<v_rd_off(D0, 3, 0)>(vb), h3 = tr_read<v_rd_off(D0, 3, 1)>(vb);
;     asm volatile("s_waitcnt lgkmcnt(0)" ::: "memory"); SBAR();
;     ...
;     od = __builtin_amdgcn_mfma_f32_32x32x16_bf16(pa0, PK(l0, h0), od, 0, 0, 0);
;     od = __builtin_amdgcn_mfma_f32_32x32x16_bf16(pa1, PK(l1, h1), od, 0, 0, 0);
;     od = __builtin_amdgcn_mfma_f32_32x32x16_bf16(pa2, PK(l2, h2), od, 0, 0, 0);
;     od = __builtin_amdgcn_mfma_f32_32x32x16_bf16(pa3, PK(l3, h3), od, 0, 0, 0);
;     ...
; }
; __device__ __forceinline__ void pv_d0(f32x16 (&o)[4], unsigned vb, bf16x8 pa0, bf16x8 pa1, bf16x8 pa2, bf16x8 pa3) {
;     pv_one<0>(o[0], vb, pa0, pa1, pa2, pa3); pv_one<1>(o[1], vb, pa0, pa1, pa2, pa3); pv_one<2>(o[2], vb, pa0, pa1, pa2, pa3); pv_one<3>(o[3], vb, pa0, pa1, pa2, pa3);
; }
; __device__ __forceinline__ void partialSM(f32x16& p0, f32x16& p1) {
; #pragma unroll
;     for (int r = 0; r < 16; ++r) p0[r] = __builtin_amdgcn_exp2f(p0[r]);
; }
; __device__ __forceinline__ void finishSM(f32x16& p0, f32x16& p1, float& l_reg, bf16x8& pa0, bf16x8& pa1, bf16x8& pa2, bf16x8& pa3) {
; #pragma unroll
;     for (int r = 0; r < 16; ++r) p1[r] = __builtin_amdgcn_exp2f(p1[r]);
;     float ps = 0;
; #pragma unroll
;     for (int r = 0; r < 16; ++r) ps += p0[r];
; #pragma unroll
;     for (int r = 0; r < 16; ++r) ps += p1[r];
;     l_reg += ps;
;     ...
;     PK8(p0, 0, pa0); PK8(p0, 8, pa1); PK8(p1, 0, pa2); PK8(p1, 8, pa3);
;     ...
; }
; template <int DQK>
; __device__ __forceinline__ void qkt(f32x16& p0, f32x16& p1, const LAS char* Ks, const bf16x8 (&qr)[DQK / 16], const int (&ka)[8], float nMB) {
;     constexpr int RB = DQK * 2, NA = (RB == 256) ? 8 : 4;
; #pragma unroll
;     for (int r = 0; r < 16; ++r) { p0[r] = nMB; p1[r] = nMB; }
; #pragma unroll
;     for (int d0 = 0; d0 < DQK / 16; ++d0) {
;         const LAS char* a = Ks + ka[d0 % NA] + (d0 / NA) * (NA * 32);
;         const bf16x8 b0 = *(const LAS bf16x8*)(a);
;         const bf16x8 b1 = *(const LAS bf16x8*)(a + 32 * RB);
	v_mfma_f32_32x32x16_bf16 v[32:47], v[48:51], v[128:131], v[32:47]
	v_mfma_f32_32x32x16_bf16 v[16:31], v[52:55], v[128:131], v[16:31]
	v_add_u32_e32 v52, 0, v167
	ds_read_b128 v[48:51], v52 offset:49152
	ds_read_b128 v[52:55], v52 offset:57344
	s_waitcnt lgkmcnt(0)
	v_mfma_f32_32x32x16_bf16 v[32:47], v[48:51], v[132:135], v[32:47]
	v_mfma_f32_32x32x16_bf16 v[16:31], v[52:55], v[132:135], v[16:31]
	v_add_u32_e32 v52, 0, v168
	ds_read_b128 v[48:51], v52 offset:49152
	ds_read_b128 v[52:55], v52 offset:57344
	s_waitcnt lgkmcnt(0)
	v_mfma_f32_32x32x16_bf16 v[32:47], v[48:51], v[136:139], v[32:47]
	v_mfma_f32_32x32x16_bf16 v[16:31], v[52:55], v[136:139], v[16:31]
	v_add_u32_e32 v52, 0, v169
	ds_read_b128 v[48:51], v52 offset:49152
	ds_read_b128 v[52:55], v52 offset:57344
	s_waitcnt lgkmcnt(0)
	v_mfma_f32_32x32x16_bf16 v[32:47], v[48:51], v[140:143], v[32:47]
	v_mfma_f32_32x32x16_bf16 v[16:31], v[52:55], v[140:143], v[16:31]
	s_nop 10
	v_exp_f32_e32 v32, v32
	v_exp_f32_e32 v33, v33
	v_exp_f32_e32 v34, v34
	v_exp_f32_e32 v35, v35
	v_exp_f32_e32 v36, v36
	v_add_f32_e32 v48, 0, v32
	v_exp_f32_e32 v37, v37
	v_add_f32_e32 v48, v33, v48
	v_exp_f32_e32 v38, v38
	v_add_f32_e32 v48, v34, v48
	v_exp_f32_e32 v39, v39
	v_add_f32_e32 v48, v35, v48
	v_exp_f32_e32 v40, v40
	v_add_f32_e32 v48, v36, v48
	v_exp_f32_e32 v41, v41
	v_add_f32_e32 v48, v37, v48
	v_exp_f32_e32 v42, v42
	v_add_f32_e32 v48, v38, v48
	v_exp_f32_e32 v43, v43
	v_add_f32_e32 v48, v39, v48
	v_exp_f32_e32 v44, v44
	v_add_f32_e32 v48, v40, v48
	v_exp_f32_e32 v45, v45
	v_add_f32_e32 v48, v41, v48
	v_exp_f32_e32 v46, v46
	v_add_f32_e32 v48, v42, v48
	v_exp_f32_e32 v47, v47
	v_add_f32_e32 v48, v43, v48
	v_exp_f32_e32 v16, v16
	v_add_f32_e32 v48, v44, v48
	v_exp_f32_e32 v17, v17
	v_add_f32_e32 v48, v45, v48
	v_exp_f32_e32 v18, v18
	v_add_f32_e32 v48, v46, v48
	v_exp_f32_e32 v19, v19
	v_add_f32_e32 v48, v47, v48
	v_exp_f32_e32 v20, v20
	v_add_f32_e32 v48, v16, v48
	v_exp_f32_e32 v21, v21
	v_add_f32_e32 v48, v17, v48
	v_exp_f32_e32 v22, v22
	v_add_f32_e32 v48, v18, v48
	v_exp_f32_e32 v23, v23
	v_add_f32_e32 v48, v19, v48
	v_exp_f32_e32 v24, v24
	v_add_f32_e32 v48, v20, v48
	v_exp_f32_e32 v25, v25
	v_add_f32_e32 v48, v21, v48
	v_exp_f32_e32 v26, v26
	v_add_f32_e32 v48, v22, v48
	v_exp_f32_e32 v27, v27
	v_add_f32_e32 v48, v23, v48
	v_exp_f32_e32 v28, v28
	v_add_f32_e32 v48, v24, v48
	v_exp_f32_e32 v29, v29
	v_add_f32_e32 v48, v25, v48
	v_exp_f32_e32 v30, v30
	v_add_f32_e32 v48, v26, v48
	v_exp_f32_e32 v31, v31
	v_add_f32_e32 v48, v27, v48
	v_add_f32_e32 v48, v28, v48
	v_add_f32_e32 v48, v29, v48
	v_add_f32_e32 v48, v30, v48
	v_add_f32_e32 v48, v31, v48
	v_add_f32_e32 v171, 0, v48
	v_cvt_pk_bf16_f32 v64, v32, v33
	v_cvt_pk_bf16_f32 v65, v34, v35
	v_cvt_pk_bf16_f32 v66, v36, v37
	v_cvt_pk_bf16_f32 v67, v38, v39
	v_cvt_pk_bf16_f32 v86, v40, v41
	v_cvt_pk_bf16_f32 v87, v42, v43
	v_cvt_pk_bf16_f32 v88, v44, v45
	v_cvt_pk_bf16_f32 v89, v46, v47
	v_cvt_pk_bf16_f32 v90, v16, v17
	v_cvt_pk_bf16_f32 v91, v18, v19
	v_cvt_pk_bf16_f32 v92, v20, v21
	v_cvt_pk_bf16_f32 v93, v22, v23
	v_cvt_pk_bf16_f32 v94, v24, v25
	v_cvt_pk_bf16_f32 v95, v26, v27
	v_cvt_pk_bf16_f32 v96, v28, v29
	v_cvt_pk_bf16_f32 v97, v30, v31
	ds_read_b64_tr_b16 v[16:17], v170 offset:0
	ds_read_b64_tr_b16 v[18:19], v170 offset:0x800
	ds_read_b64_tr_b16 v[32:33], v170 offset:0x1000
	ds_read_b64_tr_b16 v[34:35], v170 offset:0x1800
	ds_read_b64_tr_b16 v[36:37], v170 offset:0x2000
	ds_read_b64_tr_b16 v[38:39], v170 offset:0x2800
	ds_read_b64_tr_b16 v[40:41], v170 offset:0x3000
	ds_read_b64_tr_b16 v[42:43], v170 offset:0x3800
	s_waitcnt lgkmcnt(0)
	s_nop 0
	v_mfma_f32_32x32x16_bf16 v[16:31], v[64:67], v[16:19], 0
	v_mfma_f32_32x32x16_bf16 v[16:31], v[86:89], v[32:35], v[16:31]
	ds_read_b64_tr_b16 v[32:33], v170 offset:0x200
	ds_read_b64_tr_b16 v[34:35], v170 offset:0xa00
	ds_read_b64_tr_b16 v[48:49], v170 offset:0x1200
	ds_read_b64_tr_b16 v[50:51], v170 offset:0x1a00
	ds_read_b64_tr_b16 v[52:53], v170 offset:0x2200
	ds_read_b64_tr_b16 v[54:55], v170 offset:0x2a00
	ds_read_b64_tr_b16 v[56:57], v170 offset:0x3200
	v_mfma_f32_32x32x16_bf16 v[16:31], v[90:93], v[36:39], v[16:31]
	ds_read_b64_tr_b16 v[58:59], v170 offset:0x3a00
	s_waitcnt lgkmcnt(0)
	v_mfma_f32_32x32x16_bf16 v[16:31], v[94:97], v[40:43], v[16:31]
	v_mfma_f32_32x32x16_bf16 v[32:47], v[64:67], v[32:35], 0
	v_mfma_f32_32x32x16_bf16 v[32:47], v[86:89], v[48:51], v[32:47]
	ds_read_b64_tr_b16 v[48:49], v170 offset:0x400
	ds_read_b64_tr_b16 v[50:51], v170 offset:0xc00
	ds_read_b64_tr_b16 v[68:69], v170 offset:0x1400
	ds_read_b64_tr_b16 v[70:71], v170 offset:0x1c00
	ds_read_b64_tr_b16 v[72:73], v170 offset:0x2400
	ds_read_b64_tr_b16 v[74:75], v170 offset:0x2c00
	ds_read_b64_tr_b16 v[76:77], v170 offset:0x3400
	v_mfma_f32_32x32x16_bf16 v[32:47], v[90:93], v[52:55], v[32:47]
	ds_read_b64_tr_b16 v[78:79], v170 offset:0x3c00
	s_waitcnt lgkmcnt(0)
	v_mfma_f32_32x32x16_bf16 v[32:47], v[94:97], v[56:59], v[32:47]
	v_mfma_f32_32x32x16_bf16 v[48:63], v[64:67], v[48:51], 0
	v_mfma_f32_32x32x16_bf16 v[48:63], v[86:89], v[68:71], v[48:63]
	ds_read_b64_tr_b16 v[68:69], v170 offset:0x600
	ds_read_b64_tr_b16 v[70:71], v170 offset:0xe00
	ds_read_b64_tr_b16 v[98:99], v170 offset:0x1600
	ds_read_b64_tr_b16 v[100:101], v170 offset:0x1e00
	ds_read_b64_tr_b16 v[102:103], v170 offset:0x2600
	ds_read_b64_tr_b16 v[104:105], v170 offset:0x2e00
	ds_read_b64_tr_b16 v[106:107], v170 offset:0x3600
	v_mfma_f32_32x32x16_bf16 v[48:63], v[90:93], v[72:75], v[48:63]
	ds_read_b64_tr_b16 v[108:109], v170 offset:0x3e00
	s_waitcnt lgkmcnt(0)
	v_mfma_f32_32x32x16_bf16 v[48:63], v[94:97], v[76:79], v[48:63]
	v_mfma_f32_32x32x16_bf16 v[64:79], v[64:67], v[68:71], 0
	s_ashr_i32 s47, s46, 31
	v_lshl_add_u64 v[110:111], v[146:147], 0, s[46:47]
	v_lshlrev_b64 v[110:111], 9, v[110:111]
	v_lshl_add_u64 v[110:111], s[56:57], 0, v[110:111]
	s_mov_b32 m0, s3
	v_lshl_add_u64 v[110:111], v[110:111], 0, v[80:81]
	s_waitcnt vmcnt(0)
	s_waitcnt vmcnt(0)
	s_barrier
; #define LAS __attribute__((address_space(3)))
; #define SBAR() __builtin_amdgcn_sched_barrier(0)
; #define VMW0() asm volatile("s_waitcnt vmcnt(0)" ::: "memory")
; template <int DQK>
; __device__ __forceinline__ void qkt(f32x16& p0, f32x16& p1, const LAS char* Ks, const bf16x8 (&qr)[DQK / 16], const int (&ka)[8], float nMB) {
;     constexpr int RB = DQK * 2, NA = (RB == 256) ? 8 : 4;
; #pragma unroll
;     for (int r = 0; r < 16; ++r) { p0[r] = nMB; p1[r] = nMB; }
; #pragma unroll
;     for (int d0 = 0; d0 < DQK / 16; ++d0) {
;         const LAS char* a = Ks + ka[d0 % NA] + (d0 / NA) * (NA * 32);
;         const bf16x8 b0 = *(const LAS bf16x8*)(a);
;         const bf16x8 b1 = *(const LAS bf16x8*)(a + 32 * RB);
;         p0 = __builtin_amdgcn_mfma_f32_32x32x16_bf16(b0, qr[d0], p0, 0, 0, 0);
;         p1 = __builtin_amdgcn_mfma_f32_32x32x16_bf16(b1, qr[d0], p1, 0, 0, 0); }
; }
; template <int DQK, bool DOUBLE> ...
;     ...
;         for (int j = 0; j < NT; ++j) {
;             SBAR(); qkt<DQK>(p0, p1, K_lds + bc * K_STRIDE, qr, ka, nMB);
;             partialSM(p0, p1); finishSM(p0, p1, l_reg, pa0, pa1, pa2, pa3); SBAR();
;             pv_d0(o, vb0 + bc * V_BYTES, pa0, pa1, pa2, pa3);
;             if (j + 1 < NT) { VMW0(); __syncthreads(); if (j + 3 < NT) DMA(j + 3, bc); }
;             { const int _t = bc; bc = bn; bn = bf; bf = _t; }
	global_load_lds_dwordx4 v[110:111], off
	v_lshl_add_u64 v[110:111], v[148:149], 0, s[46:47]
	v_mfma_f32_32x32x16_bf16 v[64:79], v[86:89], v[98:101], v[64:79]
	v_lshlrev_b64 v[86:87], 9, v[110:111]
	v_lshl_add_u64 v[86:87], s[56:57], 0, v[86:87]
	v_lshl_add_u64 v[86:87], v[86:87], 0, v[80:81]
	s_mov_b32 m0, s21
	v_lshl_add_u64 v[154:155], s[56:57], 0, v[80:81]
	global_load_lds_dwordx4 v[86:87], off
	v_lshl_add_u64 v[86:87], v[150:151], 0, s[46:47]
	v_lshlrev_b64 v[86:87], 9, v[86:87]
	v_lshl_add_u64 v[86:87], s[50:51], 0, v[86:87]
	v_lshl_add_u64 v[86:87], v[86:87], 0, v[82:83]
	s_mov_b32 m0, s20
	v_mfma_f32_32x32x16_bf16 v[64:79], v[90:93], v[102:105], v[64:79]
	global_load_lds_dwordx4 v[86:87], off
	v_lshl_add_u64 v[86:87], v[152:153], 0, s[46:47]
	v_lshlrev_b64 v[86:87], 9, v[86:87]
	v_lshl_add_u64 v[86:87], s[50:51], 0, v[86:87]
	v_lshl_add_u64 v[86:87], v[86:87], 0, v[84:85]
	s_mov_b32 m0, s31
	v_mfma_f32_32x32x16_bf16 v[64:79], v[94:97], v[106:109], v[64:79]
	global_load_lds_dwordx4 v[86:87], off
	v_lshl_add_u64 v[156:157], s[50:51], 0, v[82:83]
	v_lshl_add_u64 v[158:159], s[50:51], 0, v[84:85]
	s_add_i32 s20, s71, -1
	s_mov_b32 s21, 0
	s_mov_b32 s33, 0
	s_waitcnt lgkmcnt(0)
	s_mul_i32 s41, s5, 0x6000
	v_add_u32_e32 v174, s41, v145
	v_add_u32_e32 v175, s41, v161
	v_add_u32_e32 v192, s41, v164
	v_add_u32_e32 v193, s41, v165
	v_add_u32_e32 v194, s41, v166
	v_add_u32_e32 v195, s41, v167
	v_add_u32_e32 v196, s41, v168
	v_add_u32_e32 v197, s41, v169
	ds_read_b128 v[204:207], v174 offset:49152
	ds_read_b128 v[208:211], v175 offset:49152
	ds_read_b128 v[212:215], v192 offset:49152
.LBB0_173:
	s_mov_b32 s31, s4
	s_mov_b32 s4, s33
	s_mul_i32 s33, s5, 0x6000
	s_add_i32 s33, s33, 0
	s_lshl_b32 s35, s5, 14
	v_add_u32_e32 v184, s35, v170
	s_waitcnt lgkmcnt(2)
	v_mfma_f32_32x32x16_bf16 v[96:111], v[204:207], v[112:115], v[0:15]
	ds_read_b128 v[216:219], v193 offset:49152
	s_waitcnt lgkmcnt(2)
	v_mfma_f32_32x32x16_bf16 v[96:111], v[208:211], v[116:119], v[96:111]
	ds_read_b128 v[204:207], v194 offset:49152
	s_waitcnt lgkmcnt(2)
	v_mfma_f32_32x32x16_bf16 v[96:111], v[212:215], v[120:123], v[96:111]
	ds_read_b128 v[208:211], v195 offset:49152
	s_waitcnt lgkmcnt(2)
	v_mfma_f32_32x32x16_bf16 v[96:111], v[216:219], v[124:127], v[96:111]
	ds_read_b128 v[212:215], v196 offset:49152
	s_waitcnt lgkmcnt(2)
	v_mfma_f32_32x32x16_bf16 v[96:111], v[204:207], v[128:131], v[96:111]
	ds_read_b128 v[216:219], v197 offset:49152
	s_waitcnt lgkmcnt(2)
	v_mfma_f32_32x32x16_bf16 v[96:111], v[208:211], v[132:135], v[96:111]
	ds_read_b128 v[204:207], v174 offset:57344
	s_waitcnt lgkmcnt(2)
	v_mfma_f32_32x32x16_bf16 v[96:111], v[212:215], v[136:139], v[96:111]
	ds_read_b128 v[208:211], v175 offset:57344
	s_waitcnt lgkmcnt(2)
	v_mfma_f32_32x32x16_bf16 v[96:111], v[216:219], v[140:143], v[96:111]
	ds_read_b128 v[212:215], v192 offset:57344
	s_waitcnt lgkmcnt(2)
	v_mfma_f32_32x32x16_bf16 v[80:95], v[204:207], v[112:115], v[0:15]
	ds_read_b128 v[216:219], v193 offset:57344
	s_waitcnt lgkmcnt(2)
	v_mfma_f32_32x32x16_bf16 v[80:95], v[208:211], v[116:119], v[80:95]
	ds_read_b128 v[204:207], v194 offset:57344
	s_nop 4
	v_exp_f32_e32 v96, v96
	v_exp_f32_e32 v97, v97
	v_exp_f32_e32 v104, v104
	v_exp_f32_e32 v105, v105
	s_waitcnt lgkmcnt(2)
	v_mfma_f32_32x32x16_bf16 v[80:95], v[212:215], v[120:123], v[80:95]
	ds_read_b128 v[208:211], v195 offset:57344
	v_exp_f32_e32 v98, v98
	v_exp_f32_e32 v99, v99
	v_exp_f32_e32 v106, v106
	s_waitcnt lgkmcnt(2)
	v_mfma_f32_32x32x16_bf16 v[80:95], v[216:219], v[124:127], v[80:95]
	ds_read_b128 v[212:215], v196 offset:57344
	v_exp_f32_e32 v100, v100
	v_exp_f32_e32 v101, v101
	v_exp_f32_e32 v107, v107
	s_waitcnt lgkmcnt(2)
	v_mfma_f32_32x32x16_bf16 v[80:95], v[204:207], v[128:131], v[80:95]
	ds_read_b128 v[216:219], v197 offset:57344
	v_exp_f32_e32 v102, v102
	v_exp_f32_e32 v103, v103
	v_exp_f32_e32 v108, v108
	s_waitcnt lgkmcnt(2)
	v_mfma_f32_32x32x16_bf16 v[80:95], v[208:211], v[132:135], v[80:95]
	ds_read_b64_tr_b16 v[204:205], v184 offset:0
	ds_read_b64_tr_b16 v[206:207], v184 offset:2048
	v_cvt_pk_bf16_f32 v172, v96, v97
	v_cvt_pk_bf16_f32 v173, v98, v99
	v_exp_f32_e32 v109, v109
	s_waitcnt lgkmcnt(3)
	v_mfma_f32_32x32x16_bf16 v[80:95], v[212:215], v[136:139], v[80:95]
	ds_read_b64_tr_b16 v[208:209], v184 offset:512
	ds_read_b64_tr_b16 v[210:211], v184 offset:2560
	v_cvt_pk_bf16_f32 v174, v100, v101
	v_exp_f32_e32 v110, v110
	s_waitcnt lgkmcnt(4)
	v_mfma_f32_32x32x16_bf16 v[80:95], v[216:219], v[140:143], v[80:95]
	ds_read_b64_tr_b16 v[212:213], v184 offset:1024
	ds_read_b64_tr_b16 v[214:215], v184 offset:3072
	v_cvt_pk_bf16_f32 v175, v102, v103
	v_exp_f32_e32 v111, v111
	v_add_f32_e32 v96, 0, v96
	v_add_f32_e32 v96, v97, v96
	s_waitcnt lgkmcnt(4)
	v_mfma_f32_32x32x16_bf16 v[16:31], v[172:175], v[204:207], v[16:31]
	ds_read_b64_tr_b16 v[216:217], v184 offset:1536
	ds_read_b64_tr_b16 v[218:219], v184 offset:3584
	v_cvt_pk_bf16_f32 v192, v104, v105
	v_add_f32_e32 v96, v98, v96
	v_add_f32_e32 v96, v99, v96
	v_add_f32_e32 v96, v100, v96
	s_waitcnt lgkmcnt(4)
	v_mfma_f32_32x32x16_bf16 v[32:47], v[172:175], v[208:211], v[32:47]
	ds_read_b64_tr_b16 v[204:205], v184 offset:4096
	ds_read_b64_tr_b16 v[206:207], v184 offset:6144
	v_cvt_pk_bf16_f32 v193, v106, v107
	v_exp_f32_e32 v80, v80
	v_exp_f32_e32 v81, v81
	v_exp_f32_e32 v88, v88
	v_exp_f32_e32 v89, v89
	v_add_f32_e32 v96, v101, v96
	v_add_f32_e32 v96, v102, v96
	s_waitcnt lgkmcnt(4)
; #define SBAR() __builtin_amdgcn_sched_barrier(0)
; #define PK8(P, BASE, OUT) do { u32x4 w = {cvt_pk_bf16(P[BASE + 0], P[BASE + 1]), cvt_pk_bf16(P[BASE + 2], P[BASE + 3]), cvt_pk_bf16(P[BASE + 4], P[BASE + 5]), cvt_pk_bf16(P[BASE + 6], P[BASE + 7])}; \
;     OUT = *reinterpret_cast<bf16x8*>(&w); } while (0)
; #define VMW0() asm volatile("s_waitcnt vmcnt(0)" ::: "memory")
; template <int D0> __device__ __forceinline__ void pv_one(f32x16& od, unsigned vb, bf16x8 pa0, bf16x8 pa1, bf16x8 pa2, bf16x8 pa3) {
;     const s16x4 l0 = tr_read<v_rd_off(D0, 0, 0)>(vb), h0 = tr_read<v_rd_off(D0, 0, 1)>(vb), l1 = tr_read<v_rd_off(D0, 1, 0)>(vb), h1 = tr_read<v_rd_off(D0, 1, 1)>(vb);
;     const s16x4 l2 = tr_read<v_rd_off(D0, 2, 0)>(vb), h2 = tr_read<v_rd_off(D0, 2, 1)>(vb), l3 = tr_read<v_rd_off(D0, 3, 0)>(vb), h3 = tr_read<v_rd_off(D0, 3, 1)>(vb);
;     asm volatile("s_waitcnt lgkmcnt(0)" ::: "memory"); SBAR();
;     ...
;     od = __builtin_amdgcn_mfma_f32_32x32x16_bf16(pa0, PK(l0, h0), od, 0, 0, 0);
;     od = __builtin_amdgcn_mfma_f32_32x32x16_bf16(pa1, PK(l1, h1), od, 0, 0, 0);
;     od = __builtin_amdgcn_mfma_f32_32x32x16_bf16(pa2, PK(l2, h2), od, 0, 0, 0);
;     od = __builtin_amdgcn_mfma_f32_32x32x16_bf16(pa3, PK(l3, h3), od, 0, 0, 0);
;     ...
; }
; __device__ __forceinline__ void pv_d0(f32x16 (&o)[4], unsigned vb, bf16x8 pa0, bf16x8 pa1, bf16x8 pa2, bf16x8 pa3) {
;     pv_one<0>(o[0], vb, pa0, pa1, pa2, pa3); pv_one<1>(o[1], vb, pa0, pa1, pa2, pa3); pv_one<2>(o[2], vb, pa0, pa1, pa2, pa3); pv_one<3>(o[3], vb, pa0, pa1, pa2, pa3);
; }
; __device__ __forceinline__ void partialSM(f32x16& p0, f32x16& p1) {
; #pragma unroll
;     for (int r = 0; r < 16; ++r) p0[r] = __builtin_amdgcn_exp2f(p0[r]);
; }
; __device__ __forceinline__ void finishSM(f32x16& p0, f32x16& p1, float& l_reg, bf16x8& pa0, bf16x8& pa1, bf16x8& pa2, bf16x8& pa3) {
; #pragma unroll
;     for (int r = 0; r < 16; ++r) p1[r] = __builtin_amdgcn_exp2f(p1[r]);
;     float ps = 0;
; #pragma unroll
;     for (int r = 0; r < 16; ++r) ps += p0[r];
; #pragma unroll
;     for (int r = 0; r < 16; ++r) ps += p1[r];
;     l_reg += ps;
;     ...
;     PK8(p0, 0, pa0); PK8(p0, 8, pa1); PK8(p1, 0, pa2); PK8(p1, 8, pa3);
;     ...
; }
; template <int DQK, bool DOUBLE> ...
;     ...
;             if (j + 1 < NT) { VMW0(); __syncthreads(); if (j + 3 < NT) DMA(j + 3, bc); }
;             { const int _t = bc; bc = bn; bn = bf; bf = _t; }
	v_mfma_f32_32x32x16_bf16 v[48:63], v[172:175], v[212:215], v[48:63]
	ds_read_b64_tr_b16 v[208:209], v184 offset:4608
	ds_read_b64_tr_b16 v[210:211], v184 offset:6656
	v_cvt_pk_bf16_f32 v194, v108, v109
	v_exp_f32_e32 v82, v82
	v_exp_f32_e32 v83, v83
	v_exp_f32_e32 v90, v90
	v_add_f32_e32 v96, v103, v96
	s_waitcnt lgkmcnt(4)
	v_mfma_f32_32x32x16_bf16 v[64:79], v[172:175], v[216:219], v[64:79]
	ds_read_b64_tr_b16 v[212:213], v184 offset:5120
	ds_read_b64_tr_b16 v[214:215], v184 offset:7168
	v_cvt_pk_bf16_f32 v195, v110, v111
	v_exp_f32_e32 v84, v84
	v_exp_f32_e32 v85, v85
	v_exp_f32_e32 v91, v91
	v_add_f32_e32 v96, v104, v96
	v_add_f32_e32 v96, v105, v96
	s_waitcnt lgkmcnt(4)
	v_mfma_f32_32x32x16_bf16 v[16:31], v[192:195], v[204:207], v[16:31]
	ds_read_b64_tr_b16 v[216:217], v184 offset:5632
	ds_read_b64_tr_b16 v[218:219], v184 offset:7680
	v_exp_f32_e32 v86, v86
	v_exp_f32_e32 v87, v87
	v_exp_f32_e32 v92, v92
	v_add_f32_e32 v96, v106, v96
	v_add_f32_e32 v96, v107, v96
	s_waitcnt lgkmcnt(4)
	v_mfma_f32_32x32x16_bf16 v[32:47], v[192:195], v[208:211], v[32:47]
	ds_read_b64_tr_b16 v[204:205], v184 offset:8192
	ds_read_b64_tr_b16 v[206:207], v184 offset:10240
	v_cvt_pk_bf16_f32 v196, v80, v81
	v_cvt_pk_bf16_f32 v197, v82, v83
	v_exp_f32_e32 v93, v93
	v_add_f32_e32 v96, v108, v96
	v_add_f32_e32 v96, v109, v96
	s_waitcnt lgkmcnt(4)
	v_mfma_f32_32x32x16_bf16 v[48:63], v[192:195], v[212:215], v[48:63]
	ds_read_b64_tr_b16 v[208:209], v184 offset:8704
	ds_read_b64_tr_b16 v[210:211], v184 offset:10752
	v_cvt_pk_bf16_f32 v198, v84, v85
	v_exp_f32_e32 v94, v94
	v_add_f32_e32 v96, v110, v96
	v_add_f32_e32 v96, v111, v96
	s_waitcnt lgkmcnt(4)
	v_mfma_f32_32x32x16_bf16 v[64:79], v[192:195], v[216:219], v[64:79]
	ds_read_b64_tr_b16 v[212:213], v184 offset:9216
	ds_read_b64_tr_b16 v[214:215], v184 offset:11264
	v_cvt_pk_bf16_f32 v199, v86, v87
	v_exp_f32_e32 v95, v95
	v_add_f32_e32 v80, v80, v96
	v_add_f32_e32 v80, v81, v80
	s_waitcnt lgkmcnt(4)
	v_mfma_f32_32x32x16_bf16 v[16:31], v[196:199], v[204:207], v[16:31]
	ds_read_b64_tr_b16 v[216:217], v184 offset:9728
	ds_read_b64_tr_b16 v[218:219], v184 offset:11776
	v_cvt_pk_bf16_f32 v200, v88, v89
	v_add_f32_e32 v80, v82, v80
	v_add_f32_e32 v80, v83, v80
	v_add_f32_e32 v80, v84, v80
	s_waitcnt lgkmcnt(4)
	v_mfma_f32_32x32x16_bf16 v[32:47], v[196:199], v[208:211], v[32:47]
	ds_read_b64_tr_b16 v[204:205], v184 offset:12288
	ds_read_b64_tr_b16 v[206:207], v184 offset:14336
	v_cvt_pk_bf16_f32 v201, v90, v91
	v_add_f32_e32 v80, v85, v80
	v_add_f32_e32 v80, v86, v80
	v_add_f32_e32 v80, v87, v80
	s_waitcnt lgkmcnt(4)
	v_mfma_f32_32x32x16_bf16 v[48:63], v[196:199], v[212:215], v[48:63]
	ds_read_b64_tr_b16 v[208:209], v184 offset:12800
	ds_read_b64_tr_b16 v[210:211], v184 offset:14848
	v_cvt_pk_bf16_f32 v202, v92, v93
	s_waitcnt lgkmcnt(4)
	v_mfma_f32_32x32x16_bf16 v[64:79], v[196:199], v[216:219], v[64:79]
	ds_read_b64_tr_b16 v[212:213], v184 offset:13312
	ds_read_b64_tr_b16 v[214:215], v184 offset:15360
	v_cvt_pk_bf16_f32 v203, v94, v95
	v_add_f32_e32 v80, v88, v80
	v_add_f32_e32 v80, v89, v80
	v_add_f32_e32 v80, v90, v80
	s_waitcnt lgkmcnt(4)
	v_mfma_f32_32x32x16_bf16 v[16:31], v[200:203], v[204:207], v[16:31]
	ds_read_b64_tr_b16 v[216:217], v184 offset:13824
	ds_read_b64_tr_b16 v[218:219], v184 offset:15872
	s_mul_i32 s41, s31, 0x6000
	v_add_u32_e32 v174, s41, v145
	v_add_u32_e32 v175, s41, v161
	v_add_u32_e32 v192, s41, v164
	v_add_u32_e32 v193, s41, v165
	v_add_u32_e32 v194, s41, v166
	v_add_u32_e32 v195, s41, v167
	v_add_u32_e32 v196, s41, v168
	v_add_u32_e32 v197, s41, v169
	v_add_f32_e32 v80, v91, v80
	v_add_f32_e32 v80, v92, v80
	v_add_f32_e32 v80, v93, v80
	v_add_f32_e32 v80, v94, v80
	s_waitcnt lgkmcnt(4)
	v_mfma_f32_32x32x16_bf16 v[32:47], v[200:203], v[208:211], v[32:47]
	ds_read_b128 v[204:207], v174 offset:49152
	v_add_f32_e32 v80, v95, v80
	s_waitcnt lgkmcnt(3)
	v_mfma_f32_32x32x16_bf16 v[48:63], v[200:203], v[212:215], v[48:63]
	ds_read_b128 v[208:211], v175 offset:49152
	s_waitcnt lgkmcnt(2)
	v_mfma_f32_32x32x16_bf16 v[64:79], v[200:203], v[216:219], v[64:79]
	ds_read_b128 v[212:215], v192 offset:49152
	s_add_i32 s41, s21, 2
	s_cmp_ge_i32 s41, s71
	s_cbranch_scc1 .LBB0_176
	s_waitcnt vmcnt(0)
	s_add_i32 s41, s21, 4
	s_cmp_ge_i32 s41, s71
	s_waitcnt vmcnt(0)
	s_barrier
	s_cbranch_scc1 .LBB0_176
	s_ashr_i32 s45, s44, 31
	v_lshl_add_u64 v[172:173], s[44:45], 0, v[146:147]
	s_add_i32 s35, s3, s35
	v_lshlrev_b64 v[172:173], 9, v[172:173]
	v_lshl_add_u64 v[172:173], v[154:155], 0, v[172:173]
	s_mov_b32 m0, s35
	s_add_i32 s33, s33, s2
	global_load_lds_dwordx4 v[172:173], off
	v_lshl_add_u64 v[172:173], s[44:45], 0, v[148:149]
	v_lshlrev_b64 v[172:173], 9, v[172:173]
	v_lshl_add_u64 v[172:173], v[154:155], 0, v[172:173]
	s_add_i32 m0, s35, 0x2000
	s_nop 0
	global_load_lds_dwordx4 v[172:173], off
	v_lshl_add_u64 v[172:173], s[44:45], 0, v[150:151]
	v_lshlrev_b64 v[172:173], 9, v[172:173]
	s_add_i32 m0, s33, 0xc000
	v_lshl_add_u64 v[172:173], v[156:157], 0, v[172:173]
	global_load_lds_dwordx4 v[172:173], off
	v_lshl_add_u64 v[172:173], s[44:45], 0, v[152:153]
	v_lshlrev_b64 v[172:173], 9, v[172:173]
	v_lshl_add_u64 v[172:173], v[158:159], 0, v[172:173]
	s_add_i32 m0, s33, 0xe000
	s_nop 0
	global_load_lds_dwordx4 v[172:173], off

; #define LAS __attribute__((address_space(3)))
; __device__ __forceinline__ void row_recip(float l_reg, float (&rli)[16], LAS float* li, int r32, int hi) {
;     { auto rr = __builtin_amdgcn_permlane32_swap(__float_as_uint(l_reg), __float_as_uint(l_reg), false, false);
;       l_reg = __uint_as_float(rr[0]) + __uint_as_float(rr[1]); }
;     if (hi == 0) li[r32] = l_reg;
.LBB0_178:
	s_waitcnt lgkmcnt(0)
	s_nop 11
	v_mov_b32_e32 v0, v171
	s_nop 1
	v_permlane32_swap_b32_e32 v171, v0
	v_cmp_gt_u32_e32 vcc, 32, v182
	s_and_saveexec_b64 s[44:45], vcc
	s_cbranch_execz .LBB0_107
	v_lshl_add_u32 v1, v181, 2, s90
	v_add_f32_e32 v0, v171, v0
	ds_write_b32 v1, v0
	s_branch .LBB0_107
